# mask fast path made the inline fall-through (slow masked path out of line); otherwise as v6: ZB prefetch + pipelined residual epilogues
# baseline (speedup 1.0000x reference)
.LBB0_1058:
	ds_bpermute_b32 v0, v191, v170
	s_waitcnt vmcnt(0)
	v_mov_b32_e32 v8, v177
	s_add_i32 s18, s18, s74
	v_and_b32_e32 v4, 31, v8
	s_waitcnt lgkmcnt(0)
	v_add_f32_e32 v0, v170, v0
	v_div_scale_f32 v2, s[0:1], v0, v0, 1.0
	v_rcp_f32_e32 v3, v2
	v_div_scale_f32 v5, vcc, 1.0, v0, 1.0
	s_add_i32 s19, s19, 1
	v_fma_f32 v6, -v2, v3, 1.0
	v_fmac_f32_e32 v3, v6, v3
	v_mul_f32_e32 v6, v5, v3
	v_fma_f32 v7, -v2, v6, v5
	v_fmac_f32_e32 v6, v7, v3
	v_fma_f32 v2, -v2, v6, v5
	v_div_fmas_f32 v2, v2, v3, v6
	v_div_fixup_f32 v2, v2, v0, 1.0
	v_cmp_lt_f32_e32 vcc, 0, v0
	v_mul_u32_u24_e32 v6, 0x110, v4
	s_cmpk_gt_i32 s18, 0x7ff
	v_cndmask_b32_e32 v0, 0, v2, vcc
	v_pk_mul_f32 v[2:3], v[64:65], v[0:1] op_sel_hi:[1,0]
	v_pk_mul_f32 v[4:5], v[66:67], v[0:1] op_sel_hi:[1,0]
	v_cvt_pk_bf16_f32 v2, v2, v3
	v_cvt_pk_bf16_f32 v3, v4, v5
	v_ashrrev_i32_e32 v4, 2, v8
	v_and_b32_e32 v4, -8, v4
	v_add3_u32 v9, s95, v6, v4
	v_pk_mul_f32 v[4:5], v[68:69], v[0:1] op_sel_hi:[1,0]
	v_pk_mul_f32 v[6:7], v[70:71], v[0:1] op_sel_hi:[1,0]
	v_cvt_pk_bf16_f32 v4, v4, v5
	v_cvt_pk_bf16_f32 v5, v6, v7
	ds_write2_b64 v9, v[2:3], v[4:5] offset1:2
	v_pk_mul_f32 v[2:3], v[72:73], v[0:1] op_sel_hi:[1,0]
	v_pk_mul_f32 v[4:5], v[74:75], v[0:1] op_sel_hi:[1,0]
	v_cvt_pk_bf16_f32 v2, v2, v3
	v_cvt_pk_bf16_f32 v3, v4, v5
	v_pk_mul_f32 v[4:5], v[76:77], v[0:1] op_sel_hi:[1,0]
	v_pk_mul_f32 v[6:7], v[78:79], v[0:1] op_sel_hi:[1,0]
	v_cvt_pk_bf16_f32 v4, v4, v5
	v_cvt_pk_bf16_f32 v5, v6, v7
	ds_write2_b64 v9, v[2:3], v[4:5] offset0:4 offset1:6
	v_pk_mul_f32 v[2:3], v[48:49], v[0:1] op_sel_hi:[1,0]
	v_pk_mul_f32 v[4:5], v[50:51], v[0:1] op_sel_hi:[1,0]
	v_cvt_pk_bf16_f32 v2, v2, v3
	v_cvt_pk_bf16_f32 v3, v4, v5
	v_pk_mul_f32 v[4:5], v[52:53], v[0:1] op_sel_hi:[1,0]
	v_pk_mul_f32 v[6:7], v[54:55], v[0:1] op_sel_hi:[1,0]
	v_cvt_pk_bf16_f32 v4, v4, v5
	v_cvt_pk_bf16_f32 v5, v6, v7
	ds_write2_b64 v9, v[2:3], v[4:5] offset0:8 offset1:10
	v_pk_mul_f32 v[2:3], v[56:57], v[0:1] op_sel_hi:[1,0]
	v_pk_mul_f32 v[4:5], v[58:59], v[0:1] op_sel_hi:[1,0]
	v_cvt_pk_bf16_f32 v2, v2, v3
	v_cvt_pk_bf16_f32 v3, v4, v5
	v_pk_mul_f32 v[4:5], v[60:61], v[0:1] op_sel_hi:[1,0]
	v_pk_mul_f32 v[6:7], v[62:63], v[0:1] op_sel_hi:[1,0]
	v_cvt_pk_bf16_f32 v4, v4, v5
	v_cvt_pk_bf16_f32 v5, v6, v7
	ds_write2_b64 v9, v[2:3], v[4:5] offset0:12 offset1:14
	v_pk_mul_f32 v[2:3], v[32:33], v[0:1] op_sel_hi:[1,0]
	v_pk_mul_f32 v[4:5], v[34:35], v[0:1] op_sel_hi:[1,0]
	v_cvt_pk_bf16_f32 v2, v2, v3
	v_cvt_pk_bf16_f32 v3, v4, v5
	v_pk_mul_f32 v[4:5], v[36:37], v[0:1] op_sel_hi:[1,0]
	v_pk_mul_f32 v[6:7], v[38:39], v[0:1] op_sel_hi:[1,0]
	v_cvt_pk_bf16_f32 v4, v4, v5
	v_cvt_pk_bf16_f32 v5, v6, v7
	ds_write2_b64 v9, v[2:3], v[4:5] offset0:16 offset1:18
	v_pk_mul_f32 v[2:3], v[40:41], v[0:1] op_sel_hi:[1,0]
	v_pk_mul_f32 v[4:5], v[42:43], v[0:1] op_sel_hi:[1,0]
	v_cvt_pk_bf16_f32 v2, v2, v3
	v_cvt_pk_bf16_f32 v3, v4, v5
	v_pk_mul_f32 v[4:5], v[44:45], v[0:1] op_sel_hi:[1,0]
	v_pk_mul_f32 v[6:7], v[46:47], v[0:1] op_sel_hi:[1,0]
	v_cvt_pk_bf16_f32 v4, v4, v5
	v_cvt_pk_bf16_f32 v5, v6, v7
	ds_write2_b64 v9, v[2:3], v[4:5] offset0:20 offset1:22
	v_pk_mul_f32 v[2:3], v[16:17], v[0:1] op_sel_hi:[1,0]
	v_pk_mul_f32 v[4:5], v[18:19], v[0:1] op_sel_hi:[1,0]
	v_cvt_pk_bf16_f32 v2, v2, v3
	v_cvt_pk_bf16_f32 v3, v4, v5
	v_pk_mul_f32 v[4:5], v[20:21], v[0:1] op_sel_hi:[1,0]
	v_pk_mul_f32 v[6:7], v[22:23], v[0:1] op_sel_hi:[1,0]
	v_cvt_pk_bf16_f32 v4, v4, v5
	v_cvt_pk_bf16_f32 v5, v6, v7
	ds_write2_b64 v9, v[2:3], v[4:5] offset0:24 offset1:26
	v_pk_mul_f32 v[2:3], v[24:25], v[0:1] op_sel_hi:[1,0]
	v_pk_mul_f32 v[4:5], v[26:27], v[0:1] op_sel_hi:[1,0]
	v_cvt_pk_bf16_f32 v2, v2, v3
	v_cvt_pk_bf16_f32 v3, v4, v5
	v_pk_mul_f32 v[4:5], v[28:29], v[0:1] op_sel_hi:[1,0]
	v_pk_mul_f32 v[6:7], v[30:31], v[0:1] op_sel_hi:[1,0]
	v_cvt_pk_bf16_f32 v4, v4, v5
	v_cvt_pk_bf16_f32 v5, v6, v7
	ds_write2_b64 v9, v[2:3], v[4:5] offset0:28 offset1:30
	v_ashrrev_i32_e32 v2, 7, v8
	v_ashrrev_i32_e32 v3, 31, v2
	v_ashrrev_i32_e32 v29, 4, v8
	v_lshl_add_u64 v[2:3], s[80:81], 0, v[2:3]
	v_mov_b64_e32 v[20:21], s[48:49]
	v_lshlrev_b32_e32 v0, 4, v8
	v_and_or_b32 v6, v29, 7, s34
	v_mad_u64_u32 v[4:5], s[0:1], v2, s76, v[20:21]
	v_and_b32_e32 v18, 0xf0, v0
	v_mad_i32_i24 v5, v3, s76, v5
	v_lshlrev_b32_e32 v0, 8, v6
	v_lshl_add_u64 v[4:5], v[4:5], 0, v[0:1]
	v_mov_b32_e32 v19, v1
	v_lshl_add_u64 v[4:5], v[4:5], 0, v[18:19]
	v_add_co_u32_e32 v4, vcc, s86, v4
	s_waitcnt lgkmcnt(0)
	v_mov_b64_e32 v[22:23], s[50:51]
	s_nop 0
	v_addc_co_u32_e32 v5, vcc, 0, v5, vcc
	global_load_dwordx4 v[10:13], v[4:5], off
	global_load_dwordx4 v[40:43], v[4:5], off offset:1024
	v_add_co_u32_e32 v68, vcc, 0x6000, v4
	s_nop 1
	v_addc_co_u32_e32 v69, vcc, 0, v5, vcc
	global_load_dwordx4 v[44:47], v[68:69], off
	global_load_dwordx4 v[48:51], v[68:69], off offset:1024
	v_add_co_u32_e32 v68, vcc, 0xc000, v4
	s_nop 1
	v_addc_co_u32_e32 v69, vcc, 0, v5, vcc
	global_load_dwordx4 v[52:55], v[68:69], off
	global_load_dwordx4 v[56:59], v[68:69], off offset:1024
	v_add_co_u32_e32 v68, vcc, 0x12000, v4
	s_nop 1
	v_addc_co_u32_e32 v69, vcc, 0, v5, vcc
	global_load_dwordx4 v[60:63], v[68:69], off
	global_load_dwordx4 v[64:67], v[68:69], off offset:1024
	v_mad_u64_u32 v[4:5], s[0:1], v2, s77, v[22:23]
	v_mad_i32_i24 v5, v3, s77, v5
	v_lshlrev_b64 v[2:3], 13, v[2:3]
	v_lshl_add_u64 v[2:3], s[44:45], 0, v[2:3]
	v_lshlrev_b32_e32 v24, 2, v6
	v_mov_b32_e32 v25, v1
	v_lshl_add_u64 v[2:3], v[2:3], 0, v[0:1]
	v_lshl_add_u64 v[4:5], v[4:5], 0, v[24:25]
	v_lshl_add_u64 v[26:27], v[2:3], 0, v[18:19]
	global_load_dword v28, v[4:5], off offset:256
	global_load_dwordx4 v[6:9], v[26:27], off
	v_mul_lo_u32 v4, v29, s94
	v_add3_u32 v30, s95, v18, v4
	ds_read_b128 v[14:17], v30
	s_waitcnt vmcnt(2)
	v_lshlrev_b32_e32 v31, 16, v10
	v_and_b32_e32 v10, 0xffff0000, v10
	v_mul_f32_e32 v2, 0xbfb8aa3b, v31
	v_mul_f32_e32 v3, 0xbfb8aa3b, v10
	v_exp_f32_e32 v2, v2
	v_exp_f32_e32 v3, v3
	s_nop 0
	v_pk_add_f32 v[32:33], v[2:3], 1.0 op_sel_hi:[1,0]
	s_nop 0
	v_div_scale_f32 v36, s[0:1], v33, v33, v10
	v_rcp_f32_e32 v37, v36
	ds_read_b128 v[2:5], v30 offset:1088
	s_waitcnt lgkmcnt(1)
	v_lshlrev_b32_e32 v34, 16, v14
	v_and_b32_e32 v35, 0xffff0000, v14
	v_fma_f32 v14, -v36, v37, 1.0
	v_fmac_f32_e32 v37, v14, v37
	v_div_scale_f32 v14, vcc, v10, v33, v10
	v_mul_f32_e32 v38, v14, v37
	v_fma_f32 v39, -v36, v38, v14
	v_fmac_f32_e32 v38, v39, v37
	v_fma_f32 v14, -v36, v38, v14
	v_div_scale_f32 v36, s[0:1], v32, v32, v31
	v_rcp_f32_e32 v39, v36
	v_div_fmas_f32 v14, v14, v37, v38
	v_div_fixup_f32 v33, v14, v33, v10
	v_and_b32_e32 v38, 0xffff0000, v11
	v_fma_f32 v10, -v36, v39, 1.0
	v_fmac_f32_e32 v39, v10, v39
	v_div_scale_f32 v10, vcc, v31, v32, v31
	v_mul_f32_e32 v14, v10, v39
	v_fma_f32 v37, -v36, v14, v10
	v_fmac_f32_e32 v14, v37, v39
	v_fma_f32 v10, -v36, v14, v10
	v_div_fmas_f32 v10, v10, v39, v14
	v_div_fixup_f32 v32, v10, v32, v31
	v_lshlrev_b32_e32 v31, 16, v11
	v_mul_f32_e32 v11, 0xbfb8aa3b, v31
	v_exp_f32_e32 v36, v11
	v_mul_f32_e32 v11, 0xbfb8aa3b, v38
	v_exp_f32_e32 v37, v11
	s_waitcnt vmcnt(1)
	v_pk_mul_f32 v[34:35], v[28:29], v[34:35] op_sel_hi:[0,1]
	s_waitcnt vmcnt(0)
	v_lshlrev_b32_e32 v10, 16, v6
	v_and_b32_e32 v11, 0xffff0000, v6
	v_pk_fma_f32 v[10:11], v[34:35], v[32:33], v[10:11]
	v_lshlrev_b32_e32 v14, 16, v15
	v_cvt_pk_bf16_f32 v6, v10, v11
	v_pk_add_f32 v[10:11], v[36:37], 1.0 op_sel_hi:[1,0]
	v_and_b32_e32 v15, 0xffff0000, v15
	v_div_scale_f32 v32, s[0:1], v11, v11, v38
	v_rcp_f32_e32 v33, v32
	v_pk_mul_f32 v[14:15], v[28:29], v[14:15] op_sel_hi:[0,1]
	v_fma_f32 v34, -v32, v33, 1.0
	v_fmac_f32_e32 v33, v34, v33
	v_div_scale_f32 v34, vcc, v38, v11, v38
	v_mul_f32_e32 v35, v34, v33
	v_fma_f32 v36, -v32, v35, v34
	v_fmac_f32_e32 v35, v36, v33
	v_fma_f32 v32, -v32, v35, v34
	v_div_scale_f32 v34, s[0:1], v10, v10, v31
	v_rcp_f32_e32 v36, v34
	v_div_fmas_f32 v32, v32, v33, v35
	v_div_fixup_f32 v11, v32, v11, v38
	v_fma_f32 v32, -v34, v36, 1.0
	v_fmac_f32_e32 v36, v32, v36
	v_div_scale_f32 v32, vcc, v31, v10, v31
	v_mul_f32_e32 v33, v32, v36
	v_fma_f32 v35, -v34, v33, v32
	v_fmac_f32_e32 v33, v35, v36
	v_fma_f32 v32, -v34, v33, v32
	v_div_fmas_f32 v32, v32, v36, v33
	v_div_fixup_f32 v10, v32, v10, v31
	v_lshlrev_b32_e32 v31, 16, v12
	v_and_b32_e32 v12, 0xffff0000, v12
	v_mul_f32_e32 v33, 0xbfb8aa3b, v31
	v_exp_f32_e32 v34, v33
	v_mul_f32_e32 v33, 0xbfb8aa3b, v12
	v_exp_f32_e32 v35, v33
	v_lshlrev_b32_e32 v32, 16, v7
	v_and_b32_e32 v33, 0xffff0000, v7
	v_pk_fma_f32 v[10:11], v[14:15], v[10:11], v[32:33]
	v_lshlrev_b32_e32 v14, 16, v16
	v_cvt_pk_bf16_f32 v7, v10, v11
	v_pk_add_f32 v[10:11], v[34:35], 1.0 op_sel_hi:[1,0]
	v_and_b32_e32 v15, 0xffff0000, v16
	v_div_scale_f32 v32, s[0:1], v11, v11, v12
	v_rcp_f32_e32 v33, v32
	v_pk_mul_f32 v[14:15], v[28:29], v[14:15] op_sel_hi:[0,1]
	v_fma_f32 v16, -v32, v33, 1.0
	v_fmac_f32_e32 v33, v16, v33
	v_div_scale_f32 v16, vcc, v12, v11, v12
	v_mul_f32_e32 v34, v16, v33
	v_fma_f32 v35, -v32, v34, v16
	v_fmac_f32_e32 v34, v35, v33
	v_fma_f32 v16, -v32, v34, v16
	v_div_scale_f32 v32, s[0:1], v10, v10, v31
	v_rcp_f32_e32 v35, v32
	v_div_fmas_f32 v16, v16, v33, v34
	v_div_fixup_f32 v11, v16, v11, v12
	v_fma_f32 v12, -v32, v35, 1.0
	v_fmac_f32_e32 v35, v12, v35
	v_div_scale_f32 v12, vcc, v31, v10, v31
	v_mul_f32_e32 v16, v12, v35
	v_fma_f32 v33, -v32, v16, v12
	v_fmac_f32_e32 v16, v33, v35
	v_fma_f32 v12, -v32, v16, v12
	v_div_fmas_f32 v12, v12, v35, v16
	v_lshlrev_b32_e32 v16, 16, v13
	v_div_fixup_f32 v10, v12, v10, v31
	v_and_b32_e32 v31, 0xffff0000, v13
	v_mul_f32_e32 v13, 0xbfb8aa3b, v16
	v_exp_f32_e32 v32, v13
	v_mul_f32_e32 v13, 0xbfb8aa3b, v31
	v_exp_f32_e32 v33, v13
	v_lshlrev_b32_e32 v12, 16, v8
	v_and_b32_e32 v13, 0xffff0000, v8
	v_pk_fma_f32 v[10:11], v[14:15], v[10:11], v[12:13]
	v_lshlrev_b32_e32 v12, 16, v17
	v_cvt_pk_bf16_f32 v8, v10, v11
	v_pk_add_f32 v[10:11], v[32:33], 1.0 op_sel_hi:[1,0]
	v_and_b32_e32 v13, 0xffff0000, v17
	v_div_scale_f32 v14, s[0:1], v11, v11, v31
	v_rcp_f32_e32 v15, v14
	v_pk_mul_f32 v[12:13], v[28:29], v[12:13] op_sel_hi:[0,1]
	s_waitcnt lgkmcnt(0)
	v_and_b32_e32 v33, 0xffff0000, v2
	v_fma_f32 v17, -v14, v15, 1.0
	v_fmac_f32_e32 v15, v17, v15
	v_div_scale_f32 v17, vcc, v31, v11, v31
	v_mul_f32_e32 v28, v17, v15
	v_fma_f32 v32, -v14, v28, v17
	v_fmac_f32_e32 v28, v32, v15
	v_fma_f32 v14, -v14, v28, v17
	v_div_scale_f32 v17, s[0:1], v10, v10, v16
	v_rcp_f32_e32 v32, v17
	v_div_fmas_f32 v14, v14, v15, v28
	v_div_fixup_f32 v11, v14, v11, v31
	v_fma_f32 v14, -v17, v32, 1.0
	v_fmac_f32_e32 v32, v14, v32
	v_div_scale_f32 v14, vcc, v16, v10, v16
	v_mul_f32_e32 v15, v14, v32
	v_fma_f32 v28, -v17, v15, v14
	v_fmac_f32_e32 v15, v28, v32
	v_fma_f32 v14, -v17, v15, v14
	v_div_fmas_f32 v14, v14, v32, v15
	v_div_fixup_f32 v10, v14, v10, v16
	v_lshlrev_b32_e32 v14, 16, v9
	v_and_b32_e32 v15, 0xffff0000, v9
	v_pk_fma_f32 v[10:11], v[12:13], v[10:11], v[14:15]
	v_mov_b32_e32 v13, v1
	v_cvt_pk_bf16_f32 v9, v10, v11
	global_store_dwordx4 v[26:27], v[6:9], off
	v_mov_b32_e32 v17, v1
	v_lshlrev_b32_e32 v32, 16, v2
	v_add_u32_e32 v8, 4, v29
	v_ashrrev_i32_e32 v6, 3, v8
	v_ashrrev_i32_e32 v7, 31, v6
	v_lshl_add_u64 v[10:11], s[80:81], 0, v[6:7]
	v_and_or_b32 v16, v8, 7, s34
	v_mad_u64_u32 v[6:7], s[0:1], v10, s76, v[20:21]
	v_mad_i32_i24 v7, v11, s76, v7
	v_lshlrev_b32_e32 v12, 8, v16
	v_lshl_add_u64 v[6:7], v[6:7], 0, v[12:13]
	v_lshl_add_u64 v[6:7], v[6:7], 0, v[18:19]
	v_add_co_u32_e32 v6, vcc, s86, v6
	v_mad_u64_u32 v[14:15], s[0:1], v10, s77, v[22:23]
	s_nop 0
	v_addc_co_u32_e32 v7, vcc, 0, v7, vcc
	global_load_dwordx4 v[6:9], v[6:7], off
	v_mad_i32_i24 v15, v11, s77, v15
	v_lshlrev_b32_e32 v16, 2, v16
	v_lshl_add_u64 v[14:15], v[14:15], 0, v[16:17]
	global_load_dword v14, v[14:15], off offset:256
	v_lshlrev_b64 v[10:11], 13, v[10:11]
	v_lshl_add_u64 v[10:11], s[44:45], 0, v[10:11]
	v_lshl_add_u64 v[10:11], v[10:11], 0, v[12:13]
	v_lshl_add_u64 v[16:17], v[10:11], 0, v[18:19]
	global_load_dwordx4 v[10:13], v[16:17], off
	s_waitcnt vmcnt(2)
	v_lshlrev_b32_e32 v15, 16, v6
	v_and_b32_e32 v6, 0xffff0000, v6
	v_mul_f32_e32 v26, 0xbfb8aa3b, v15
	v_mul_f32_e32 v27, 0xbfb8aa3b, v6
	v_exp_f32_e32 v26, v26
	v_exp_f32_e32 v27, v27
	s_waitcnt vmcnt(1)
	v_pk_mul_f32 v[32:33], v[14:15], v[32:33] op_sel_hi:[0,1]
	v_pk_add_f32 v[26:27], v[26:27], 1.0 op_sel_hi:[1,0]
	s_nop 0
	v_div_scale_f32 v28, s[0:1], v27, v27, v6
	v_rcp_f32_e32 v31, v28
	s_nop 0
	v_fma_f32 v2, -v28, v31, 1.0
	v_fmac_f32_e32 v31, v2, v31
	v_div_scale_f32 v2, vcc, v6, v27, v6
	v_mul_f32_e32 v34, v2, v31
	v_fma_f32 v35, -v28, v34, v2
	v_fmac_f32_e32 v34, v35, v31
	v_fma_f32 v2, -v28, v34, v2
	v_div_scale_f32 v28, s[0:1], v26, v26, v15
	v_rcp_f32_e32 v35, v28
	v_div_fmas_f32 v2, v2, v31, v34
	v_div_fixup_f32 v27, v2, v27, v6
	v_fma_f32 v2, -v28, v35, 1.0
	v_fmac_f32_e32 v35, v2, v35
	v_div_scale_f32 v2, vcc, v15, v26, v15
	v_mul_f32_e32 v6, v2, v35
	v_fma_f32 v31, -v28, v6, v2
	v_fmac_f32_e32 v6, v31, v35
	v_fma_f32 v2, -v28, v6, v2
	v_div_fmas_f32 v2, v2, v35, v6
	v_div_fixup_f32 v26, v2, v26, v15
	v_lshlrev_b32_e32 v15, 16, v7
	v_and_b32_e32 v28, 0xffff0000, v7
	v_mul_f32_e32 v2, 0xbfb8aa3b, v15
	v_exp_f32_e32 v34, v2
	v_mul_f32_e32 v2, 0xbfb8aa3b, v28
	v_exp_f32_e32 v35, v2
	s_waitcnt vmcnt(0)
	v_lshlrev_b32_e32 v6, 16, v10
	v_and_b32_e32 v7, 0xffff0000, v10
	v_pk_fma_f32 v[6:7], v[32:33], v[26:27], v[6:7]
	v_lshlrev_b32_e32 v26, 16, v3
	v_cvt_pk_bf16_f32 v2, v6, v7
	v_pk_add_f32 v[6:7], v[34:35], 1.0 op_sel_hi:[1,0]
	v_and_b32_e32 v27, 0xffff0000, v3
	v_div_scale_f32 v10, s[0:1], v7, v7, v28
	v_rcp_f32_e32 v31, v10
	v_pk_mul_f32 v[26:27], v[14:15], v[26:27] op_sel_hi:[0,1]
	v_fma_f32 v3, -v10, v31, 1.0
	v_fmac_f32_e32 v31, v3, v31
	v_div_scale_f32 v3, vcc, v28, v7, v28
	v_mul_f32_e32 v32, v3, v31
	v_fma_f32 v33, -v10, v32, v3
	v_fmac_f32_e32 v32, v33, v31
	v_fma_f32 v3, -v10, v32, v3
	v_div_scale_f32 v10, s[0:1], v6, v6, v15
	v_rcp_f32_e32 v33, v10
	v_div_fmas_f32 v3, v3, v31, v32
	v_div_fixup_f32 v7, v3, v7, v28
	v_fma_f32 v3, -v10, v33, 1.0
	v_fmac_f32_e32 v33, v3, v33
	v_div_scale_f32 v3, vcc, v15, v6, v15
	v_mul_f32_e32 v28, v3, v33
	v_fma_f32 v31, -v10, v28, v3
	v_fmac_f32_e32 v28, v31, v33
	v_fma_f32 v3, -v10, v28, v3
	v_div_fmas_f32 v3, v3, v33, v28
	v_div_fixup_f32 v6, v3, v6, v15
	v_lshlrev_b32_e32 v15, 16, v8
	v_and_b32_e32 v8, 0xffff0000, v8
	v_mul_f32_e32 v3, 0xbfb8aa3b, v15
	v_exp_f32_e32 v32, v3
	v_mul_f32_e32 v3, 0xbfb8aa3b, v8
	v_exp_f32_e32 v33, v3
	v_lshlrev_b32_e32 v10, 16, v11
	v_and_b32_e32 v11, 0xffff0000, v11
	v_pk_fma_f32 v[6:7], v[26:27], v[6:7], v[10:11]
	v_lshlrev_b32_e32 v10, 16, v4
	v_cvt_pk_bf16_f32 v3, v6, v7
	v_pk_add_f32 v[6:7], v[32:33], 1.0 op_sel_hi:[1,0]
	v_and_b32_e32 v11, 0xffff0000, v4
	v_div_scale_f32 v26, s[0:1], v7, v7, v8
	v_rcp_f32_e32 v27, v26
	v_pk_mul_f32 v[10:11], v[14:15], v[10:11] op_sel_hi:[0,1]
	v_fma_f32 v4, -v26, v27, 1.0
	v_fmac_f32_e32 v27, v4, v27
	v_div_scale_f32 v4, vcc, v8, v7, v8
	v_mul_f32_e32 v28, v4, v27
	v_fma_f32 v31, -v26, v28, v4
	v_fmac_f32_e32 v28, v31, v27
	v_fma_f32 v4, -v26, v28, v4
	v_div_scale_f32 v26, s[0:1], v6, v6, v15
	v_rcp_f32_e32 v31, v26
	v_div_fmas_f32 v4, v4, v27, v28
	v_div_fixup_f32 v7, v4, v7, v8
	v_and_b32_e32 v28, 0xffff0000, v9
	v_fma_f32 v4, -v26, v31, 1.0
	v_fmac_f32_e32 v31, v4, v31
	v_div_scale_f32 v4, vcc, v15, v6, v15
	v_mul_f32_e32 v8, v4, v31
	v_fma_f32 v27, -v26, v8, v4
	v_fmac_f32_e32 v8, v27, v31
	v_fma_f32 v4, -v26, v8, v4
	v_div_fmas_f32 v4, v4, v31, v8
	v_div_fixup_f32 v6, v4, v6, v15
	v_lshlrev_b32_e32 v15, 16, v9
	v_mul_f32_e32 v4, 0xbfb8aa3b, v15
	v_exp_f32_e32 v26, v4
	v_mul_f32_e32 v4, 0xbfb8aa3b, v28
	v_exp_f32_e32 v27, v4
	v_lshlrev_b32_e32 v8, 16, v12
	v_and_b32_e32 v9, 0xffff0000, v12
	v_pk_fma_f32 v[6:7], v[10:11], v[6:7], v[8:9]
	v_lshlrev_b32_e32 v8, 16, v5
	v_cvt_pk_bf16_f32 v4, v6, v7
	v_pk_add_f32 v[6:7], v[26:27], 1.0 op_sel_hi:[1,0]
	v_and_b32_e32 v9, 0xffff0000, v5
	v_div_scale_f32 v10, s[0:1], v7, v7, v28
	v_rcp_f32_e32 v11, v10
	v_pk_mul_f32 v[8:9], v[14:15], v[8:9] op_sel_hi:[0,1]
	v_fma_f32 v5, -v10, v11, 1.0
	v_fmac_f32_e32 v11, v5, v11
	v_div_scale_f32 v5, vcc, v28, v7, v28
	v_mul_f32_e32 v12, v5, v11
	v_fma_f32 v14, -v10, v12, v5
	v_fmac_f32_e32 v12, v14, v11
	v_fma_f32 v5, -v10, v12, v5
	v_div_scale_f32 v10, s[0:1], v6, v6, v15
	v_rcp_f32_e32 v14, v10
	v_div_fmas_f32 v5, v5, v11, v12
	v_div_fixup_f32 v7, v5, v7, v28
	v_fma_f32 v5, -v10, v14, 1.0
	v_fmac_f32_e32 v14, v5, v14
	v_div_scale_f32 v5, vcc, v15, v6, v15
	v_mul_f32_e32 v11, v5, v14
	v_fma_f32 v12, -v10, v11, v5
	v_fmac_f32_e32 v11, v12, v14
	v_fma_f32 v5, -v10, v11, v5
	v_div_fmas_f32 v5, v5, v14, v11
	v_div_fixup_f32 v6, v5, v6, v15
	v_lshlrev_b32_e32 v10, 16, v13
	v_and_b32_e32 v11, 0xffff0000, v13
	v_pk_fma_f32 v[6:7], v[8:9], v[6:7], v[10:11]
	s_nop 0
	v_cvt_pk_bf16_f32 v5, v6, v7
	global_store_dwordx4 v[16:17], v[2:5], off
	ds_read_b128 v[14:17], v30 offset:2176
	s_nop 0
	v_add_u32_e32 v2, 8, v29
	v_ashrrev_i32_e32 v2, 3, v2
	v_ashrrev_i32_e32 v3, 31, v2
	v_lshl_add_u64 v[2:3], s[80:81], 0, v[2:3]
	v_mad_u64_u32 v[4:5], s[0:1], v2, s76, v[20:21]
	v_mad_i32_i24 v5, v3, s76, v5
	v_lshl_add_u64 v[4:5], v[4:5], 0, v[0:1]
	v_lshl_add_u64 v[4:5], v[4:5], 0, v[18:19]
	v_add_co_u32_e32 v4, vcc, s86, v4
	s_nop 1
	v_addc_co_u32_e32 v5, vcc, 0, v5, vcc
	global_load_dwordx4 v[10:13], v[4:5], off
	v_mad_u64_u32 v[4:5], s[0:1], v2, s77, v[22:23]
	v_mad_i32_i24 v5, v3, s77, v5
	v_lshlrev_b64 v[2:3], 13, v[2:3]
	v_lshl_add_u64 v[2:3], s[44:45], 0, v[2:3]
	v_lshl_add_u64 v[2:3], v[2:3], 0, v[0:1]
	v_lshl_add_u64 v[4:5], v[4:5], 0, v[24:25]
	v_lshl_add_u64 v[26:27], v[2:3], 0, v[18:19]
	global_load_dword v28, v[4:5], off offset:256
	global_load_dwordx4 v[6:9], v[26:27], off
	s_waitcnt vmcnt(2)
	v_lshlrev_b32_e32 v31, 16, v10
	v_and_b32_e32 v10, 0xffff0000, v10
	v_mul_f32_e32 v2, 0xbfb8aa3b, v31
	v_mul_f32_e32 v3, 0xbfb8aa3b, v10
	v_exp_f32_e32 v2, v2
	v_exp_f32_e32 v3, v3
	s_nop 0
	v_pk_add_f32 v[32:33], v[2:3], 1.0 op_sel_hi:[1,0]
	s_nop 0
	v_div_scale_f32 v36, s[0:1], v33, v33, v10
	v_rcp_f32_e32 v37, v36
	ds_read_b128 v[2:5], v30 offset:3264
	s_waitcnt lgkmcnt(1)
	v_lshlrev_b32_e32 v34, 16, v14
	v_and_b32_e32 v35, 0xffff0000, v14
	v_fma_f32 v14, -v36, v37, 1.0
	v_fmac_f32_e32 v37, v14, v37
	v_div_scale_f32 v14, vcc, v10, v33, v10
	v_mul_f32_e32 v38, v14, v37
	v_fma_f32 v39, -v36, v38, v14
	v_fmac_f32_e32 v38, v39, v37
	v_fma_f32 v14, -v36, v38, v14
	v_div_scale_f32 v36, s[0:1], v32, v32, v31
	v_rcp_f32_e32 v39, v36
	v_div_fmas_f32 v14, v14, v37, v38
	v_div_fixup_f32 v33, v14, v33, v10
	v_and_b32_e32 v38, 0xffff0000, v11
	v_fma_f32 v10, -v36, v39, 1.0
	v_fmac_f32_e32 v39, v10, v39
	v_div_scale_f32 v10, vcc, v31, v32, v31
	v_mul_f32_e32 v14, v10, v39
	v_fma_f32 v37, -v36, v14, v10
	v_fmac_f32_e32 v14, v37, v39
	v_fma_f32 v10, -v36, v14, v10
	v_div_fmas_f32 v10, v10, v39, v14
	v_div_fixup_f32 v32, v10, v32, v31
	v_lshlrev_b32_e32 v31, 16, v11
	v_mul_f32_e32 v11, 0xbfb8aa3b, v31
	v_exp_f32_e32 v36, v11
	v_mul_f32_e32 v11, 0xbfb8aa3b, v38
	v_exp_f32_e32 v37, v11
	s_waitcnt vmcnt(1)
	v_pk_mul_f32 v[34:35], v[28:29], v[34:35] op_sel_hi:[0,1]
	s_waitcnt vmcnt(0)
	v_lshlrev_b32_e32 v10, 16, v6
	v_and_b32_e32 v11, 0xffff0000, v6
	v_pk_fma_f32 v[10:11], v[34:35], v[32:33], v[10:11]
	v_lshlrev_b32_e32 v14, 16, v15
	v_cvt_pk_bf16_f32 v6, v10, v11
	v_pk_add_f32 v[10:11], v[36:37], 1.0 op_sel_hi:[1,0]
	v_and_b32_e32 v15, 0xffff0000, v15
	v_div_scale_f32 v32, s[0:1], v11, v11, v38
	v_rcp_f32_e32 v33, v32
	v_pk_mul_f32 v[14:15], v[28:29], v[14:15] op_sel_hi:[0,1]
	v_fma_f32 v34, -v32, v33, 1.0
	v_fmac_f32_e32 v33, v34, v33
	v_div_scale_f32 v34, vcc, v38, v11, v38
	v_mul_f32_e32 v35, v34, v33
	v_fma_f32 v36, -v32, v35, v34
	v_fmac_f32_e32 v35, v36, v33
	v_fma_f32 v32, -v32, v35, v34
	v_div_scale_f32 v34, s[0:1], v10, v10, v31
	v_rcp_f32_e32 v36, v34
	v_div_fmas_f32 v32, v32, v33, v35
	v_div_fixup_f32 v11, v32, v11, v38
	v_fma_f32 v32, -v34, v36, 1.0
	v_fmac_f32_e32 v36, v32, v36
	v_div_scale_f32 v32, vcc, v31, v10, v31
	v_mul_f32_e32 v33, v32, v36
	v_fma_f32 v35, -v34, v33, v32
	v_fmac_f32_e32 v33, v35, v36
	v_fma_f32 v32, -v34, v33, v32
	v_div_fmas_f32 v32, v32, v36, v33
	v_div_fixup_f32 v10, v32, v10, v31
	v_lshlrev_b32_e32 v31, 16, v12
	v_and_b32_e32 v12, 0xffff0000, v12
	v_mul_f32_e32 v33, 0xbfb8aa3b, v31
	v_exp_f32_e32 v34, v33
	v_mul_f32_e32 v33, 0xbfb8aa3b, v12
	v_exp_f32_e32 v35, v33
	v_lshlrev_b32_e32 v32, 16, v7
	v_and_b32_e32 v33, 0xffff0000, v7
	v_pk_fma_f32 v[10:11], v[14:15], v[10:11], v[32:33]
	v_lshlrev_b32_e32 v14, 16, v16
	v_cvt_pk_bf16_f32 v7, v10, v11
	v_pk_add_f32 v[10:11], v[34:35], 1.0 op_sel_hi:[1,0]
	v_and_b32_e32 v15, 0xffff0000, v16
	v_div_scale_f32 v32, s[0:1], v11, v11, v12
	v_rcp_f32_e32 v33, v32
	v_pk_mul_f32 v[14:15], v[28:29], v[14:15] op_sel_hi:[0,1]
	v_fma_f32 v16, -v32, v33, 1.0
	v_fmac_f32_e32 v33, v16, v33
	v_div_scale_f32 v16, vcc, v12, v11, v12
	v_mul_f32_e32 v34, v16, v33
	v_fma_f32 v35, -v32, v34, v16
	v_fmac_f32_e32 v34, v35, v33
	v_fma_f32 v16, -v32, v34, v16
	v_div_scale_f32 v32, s[0:1], v10, v10, v31
	v_rcp_f32_e32 v35, v32
	v_div_fmas_f32 v16, v16, v33, v34
	v_div_fixup_f32 v11, v16, v11, v12
	v_fma_f32 v12, -v32, v35, 1.0
	v_fmac_f32_e32 v35, v12, v35
	v_div_scale_f32 v12, vcc, v31, v10, v31
	v_mul_f32_e32 v16, v12, v35
	v_fma_f32 v33, -v32, v16, v12
	v_fmac_f32_e32 v16, v33, v35
	v_fma_f32 v12, -v32, v16, v12
	v_div_fmas_f32 v12, v12, v35, v16
	v_lshlrev_b32_e32 v16, 16, v13
	v_div_fixup_f32 v10, v12, v10, v31
	v_and_b32_e32 v31, 0xffff0000, v13
	v_mul_f32_e32 v13, 0xbfb8aa3b, v16
	v_exp_f32_e32 v32, v13
	v_mul_f32_e32 v13, 0xbfb8aa3b, v31
	v_exp_f32_e32 v33, v13
	v_lshlrev_b32_e32 v12, 16, v8
	v_and_b32_e32 v13, 0xffff0000, v8
	v_pk_fma_f32 v[10:11], v[14:15], v[10:11], v[12:13]
	v_lshlrev_b32_e32 v12, 16, v17
	v_cvt_pk_bf16_f32 v8, v10, v11
	v_pk_add_f32 v[10:11], v[32:33], 1.0 op_sel_hi:[1,0]
	v_and_b32_e32 v13, 0xffff0000, v17
	v_div_scale_f32 v14, s[0:1], v11, v11, v31
	v_rcp_f32_e32 v15, v14
	v_pk_mul_f32 v[12:13], v[28:29], v[12:13] op_sel_hi:[0,1]
	s_waitcnt lgkmcnt(0)
	v_and_b32_e32 v33, 0xffff0000, v2
	v_fma_f32 v17, -v14, v15, 1.0
	v_fmac_f32_e32 v15, v17, v15
	v_div_scale_f32 v17, vcc, v31, v11, v31
	v_mul_f32_e32 v28, v17, v15
	v_fma_f32 v32, -v14, v28, v17
	v_fmac_f32_e32 v28, v32, v15
	v_fma_f32 v14, -v14, v28, v17
	v_div_scale_f32 v17, s[0:1], v10, v10, v16
	v_rcp_f32_e32 v32, v17
	v_div_fmas_f32 v14, v14, v15, v28
	v_div_fixup_f32 v11, v14, v11, v31
	v_fma_f32 v14, -v17, v32, 1.0
	v_fmac_f32_e32 v32, v14, v32
	v_div_scale_f32 v14, vcc, v16, v10, v16
	v_mul_f32_e32 v15, v14, v32
	v_fma_f32 v28, -v17, v15, v14
	v_fmac_f32_e32 v15, v28, v32
	v_fma_f32 v14, -v17, v15, v14
	v_div_fmas_f32 v14, v14, v32, v15
	v_div_fixup_f32 v10, v14, v10, v16
	v_lshlrev_b32_e32 v14, 16, v9
	v_and_b32_e32 v15, 0xffff0000, v9
	v_pk_fma_f32 v[10:11], v[12:13], v[10:11], v[14:15]
	v_mov_b32_e32 v13, v1
	v_cvt_pk_bf16_f32 v9, v10, v11
	global_store_dwordx4 v[26:27], v[6:9], off
	v_mov_b32_e32 v17, v1
	v_lshlrev_b32_e32 v32, 16, v2
	v_add_u32_e32 v8, 12, v29
	v_ashrrev_i32_e32 v6, 3, v8
	v_ashrrev_i32_e32 v7, 31, v6
	v_lshl_add_u64 v[10:11], s[80:81], 0, v[6:7]
	v_and_or_b32 v16, v8, 7, s34
	v_mad_u64_u32 v[6:7], s[0:1], v10, s76, v[20:21]
	v_mad_i32_i24 v7, v11, s76, v7
	v_lshlrev_b32_e32 v12, 8, v16
	v_lshl_add_u64 v[6:7], v[6:7], 0, v[12:13]
	v_lshl_add_u64 v[6:7], v[6:7], 0, v[18:19]
	v_add_co_u32_e32 v6, vcc, s86, v6
	v_mad_u64_u32 v[14:15], s[0:1], v10, s77, v[22:23]
	s_nop 0
	v_addc_co_u32_e32 v7, vcc, 0, v7, vcc
	global_load_dwordx4 v[6:9], v[6:7], off
	v_mad_i32_i24 v15, v11, s77, v15
	v_lshlrev_b32_e32 v16, 2, v16
	v_lshl_add_u64 v[14:15], v[14:15], 0, v[16:17]
	global_load_dword v14, v[14:15], off offset:256
	v_lshlrev_b64 v[10:11], 13, v[10:11]
	v_lshl_add_u64 v[10:11], s[44:45], 0, v[10:11]
	v_lshl_add_u64 v[10:11], v[10:11], 0, v[12:13]
	v_lshl_add_u64 v[16:17], v[10:11], 0, v[18:19]
	global_load_dwordx4 v[10:13], v[16:17], off
	s_waitcnt vmcnt(2)
	v_lshlrev_b32_e32 v15, 16, v6
	v_and_b32_e32 v6, 0xffff0000, v6
	v_mul_f32_e32 v26, 0xbfb8aa3b, v15
	v_mul_f32_e32 v27, 0xbfb8aa3b, v6
	v_exp_f32_e32 v26, v26
	v_exp_f32_e32 v27, v27
	s_waitcnt vmcnt(1)
	v_pk_mul_f32 v[32:33], v[14:15], v[32:33] op_sel_hi:[0,1]
	v_pk_add_f32 v[26:27], v[26:27], 1.0 op_sel_hi:[1,0]
	s_nop 0
	v_div_scale_f32 v28, s[0:1], v27, v27, v6
	v_rcp_f32_e32 v31, v28
	s_nop 0
	v_fma_f32 v2, -v28, v31, 1.0
	v_fmac_f32_e32 v31, v2, v31
	v_div_scale_f32 v2, vcc, v6, v27, v6
	v_mul_f32_e32 v34, v2, v31
	v_fma_f32 v35, -v28, v34, v2
	v_fmac_f32_e32 v34, v35, v31
	v_fma_f32 v2, -v28, v34, v2
	v_div_scale_f32 v28, s[0:1], v26, v26, v15
	v_rcp_f32_e32 v35, v28
	v_div_fmas_f32 v2, v2, v31, v34
	v_div_fixup_f32 v27, v2, v27, v6
	v_fma_f32 v2, -v28, v35, 1.0
	v_fmac_f32_e32 v35, v2, v35
	v_div_scale_f32 v2, vcc, v15, v26, v15
	v_mul_f32_e32 v6, v2, v35
	v_fma_f32 v31, -v28, v6, v2
	v_fmac_f32_e32 v6, v31, v35
	v_fma_f32 v2, -v28, v6, v2
	v_div_fmas_f32 v2, v2, v35, v6
	v_div_fixup_f32 v26, v2, v26, v15
	v_lshlrev_b32_e32 v15, 16, v7
	v_and_b32_e32 v28, 0xffff0000, v7
	v_mul_f32_e32 v2, 0xbfb8aa3b, v15
	v_exp_f32_e32 v34, v2
	v_mul_f32_e32 v2, 0xbfb8aa3b, v28
	v_exp_f32_e32 v35, v2
	s_waitcnt vmcnt(0)
	v_lshlrev_b32_e32 v6, 16, v10
	v_and_b32_e32 v7, 0xffff0000, v10
	v_pk_fma_f32 v[6:7], v[32:33], v[26:27], v[6:7]
	v_lshlrev_b32_e32 v26, 16, v3
	v_cvt_pk_bf16_f32 v2, v6, v7
	v_pk_add_f32 v[6:7], v[34:35], 1.0 op_sel_hi:[1,0]
	v_and_b32_e32 v27, 0xffff0000, v3
	v_div_scale_f32 v10, s[0:1], v7, v7, v28
	v_rcp_f32_e32 v31, v10
	v_pk_mul_f32 v[26:27], v[14:15], v[26:27] op_sel_hi:[0,1]
	v_fma_f32 v3, -v10, v31, 1.0
	v_fmac_f32_e32 v31, v3, v31
	v_div_scale_f32 v3, vcc, v28, v7, v28
	v_mul_f32_e32 v32, v3, v31
	v_fma_f32 v33, -v10, v32, v3
	v_fmac_f32_e32 v32, v33, v31
	v_fma_f32 v3, -v10, v32, v3
	v_div_scale_f32 v10, s[0:1], v6, v6, v15
	v_rcp_f32_e32 v33, v10
	v_div_fmas_f32 v3, v3, v31, v32
	v_div_fixup_f32 v7, v3, v7, v28
	v_fma_f32 v3, -v10, v33, 1.0
	v_fmac_f32_e32 v33, v3, v33
	v_div_scale_f32 v3, vcc, v15, v6, v15
	v_mul_f32_e32 v28, v3, v33
	v_fma_f32 v31, -v10, v28, v3
	v_fmac_f32_e32 v28, v31, v33
	v_fma_f32 v3, -v10, v28, v3
	v_div_fmas_f32 v3, v3, v33, v28
	v_div_fixup_f32 v6, v3, v6, v15
	v_lshlrev_b32_e32 v15, 16, v8
	v_and_b32_e32 v8, 0xffff0000, v8
	v_mul_f32_e32 v3, 0xbfb8aa3b, v15
	v_exp_f32_e32 v32, v3
	v_mul_f32_e32 v3, 0xbfb8aa3b, v8
	v_exp_f32_e32 v33, v3
	v_lshlrev_b32_e32 v10, 16, v11
	v_and_b32_e32 v11, 0xffff0000, v11
	v_pk_fma_f32 v[6:7], v[26:27], v[6:7], v[10:11]
	v_lshlrev_b32_e32 v10, 16, v4
	v_cvt_pk_bf16_f32 v3, v6, v7
	v_pk_add_f32 v[6:7], v[32:33], 1.0 op_sel_hi:[1,0]
	v_and_b32_e32 v11, 0xffff0000, v4
	v_div_scale_f32 v26, s[0:1], v7, v7, v8
	v_rcp_f32_e32 v27, v26
	v_pk_mul_f32 v[10:11], v[14:15], v[10:11] op_sel_hi:[0,1]
	v_fma_f32 v4, -v26, v27, 1.0
	v_fmac_f32_e32 v27, v4, v27
	v_div_scale_f32 v4, vcc, v8, v7, v8
	v_mul_f32_e32 v28, v4, v27
	v_fma_f32 v31, -v26, v28, v4
	v_fmac_f32_e32 v28, v31, v27
	v_fma_f32 v4, -v26, v28, v4
	v_div_scale_f32 v26, s[0:1], v6, v6, v15
	v_rcp_f32_e32 v31, v26
	v_div_fmas_f32 v4, v4, v27, v28
	v_div_fixup_f32 v7, v4, v7, v8
	v_and_b32_e32 v28, 0xffff0000, v9
	v_fma_f32 v4, -v26, v31, 1.0
	v_fmac_f32_e32 v31, v4, v31
	v_div_scale_f32 v4, vcc, v15, v6, v15
	v_mul_f32_e32 v8, v4, v31
	v_fma_f32 v27, -v26, v8, v4
	v_fmac_f32_e32 v8, v27, v31
	v_fma_f32 v4, -v26, v8, v4
	v_div_fmas_f32 v4, v4, v31, v8
	v_div_fixup_f32 v6, v4, v6, v15
	v_lshlrev_b32_e32 v15, 16, v9
	v_mul_f32_e32 v4, 0xbfb8aa3b, v15
	v_exp_f32_e32 v26, v4
	v_mul_f32_e32 v4, 0xbfb8aa3b, v28
	v_exp_f32_e32 v27, v4
	v_lshlrev_b32_e32 v8, 16, v12
	v_and_b32_e32 v9, 0xffff0000, v12
	v_pk_fma_f32 v[6:7], v[10:11], v[6:7], v[8:9]
	v_lshlrev_b32_e32 v8, 16, v5
	v_cvt_pk_bf16_f32 v4, v6, v7
	v_pk_add_f32 v[6:7], v[26:27], 1.0 op_sel_hi:[1,0]
	v_and_b32_e32 v9, 0xffff0000, v5
	v_div_scale_f32 v10, s[0:1], v7, v7, v28
	v_rcp_f32_e32 v11, v10
	v_pk_mul_f32 v[8:9], v[14:15], v[8:9] op_sel_hi:[0,1]
	v_fma_f32 v5, -v10, v11, 1.0
	v_fmac_f32_e32 v11, v5, v11
	v_div_scale_f32 v5, vcc, v28, v7, v28
	v_mul_f32_e32 v12, v5, v11
	v_fma_f32 v14, -v10, v12, v5
	v_fmac_f32_e32 v12, v14, v11
	v_fma_f32 v5, -v10, v12, v5
	v_div_scale_f32 v10, s[0:1], v6, v6, v15
	v_rcp_f32_e32 v14, v10
	v_div_fmas_f32 v5, v5, v11, v12
	v_div_fixup_f32 v7, v5, v7, v28
	v_fma_f32 v5, -v10, v14, 1.0
	v_fmac_f32_e32 v14, v5, v14
	v_div_scale_f32 v5, vcc, v15, v6, v15
	v_mul_f32_e32 v11, v5, v14
	v_fma_f32 v12, -v10, v11, v5
	v_fmac_f32_e32 v11, v12, v14
	v_fma_f32 v5, -v10, v11, v5
	v_div_fmas_f32 v5, v5, v14, v11
	v_div_fixup_f32 v6, v5, v6, v15
	v_lshlrev_b32_e32 v10, 16, v13
	v_and_b32_e32 v11, 0xffff0000, v13
	v_pk_fma_f32 v[6:7], v[8:9], v[6:7], v[10:11]
	s_nop 0
	v_cvt_pk_bf16_f32 v5, v6, v7
	global_store_dwordx4 v[16:17], v[2:5], off
	ds_read_b128 v[14:17], v30 offset:4352
	s_nop 0
	v_add_u32_e32 v2, 16, v29
	v_ashrrev_i32_e32 v2, 3, v2
	v_ashrrev_i32_e32 v3, 31, v2
	v_lshl_add_u64 v[2:3], s[80:81], 0, v[2:3]
	v_mad_u64_u32 v[4:5], s[0:1], v2, s76, v[20:21]
	v_mad_i32_i24 v5, v3, s76, v5
	v_lshl_add_u64 v[4:5], v[4:5], 0, v[0:1]
	v_lshl_add_u64 v[4:5], v[4:5], 0, v[18:19]
	v_add_co_u32_e32 v4, vcc, s86, v4
	s_nop 1
	v_addc_co_u32_e32 v5, vcc, 0, v5, vcc
	global_load_dwordx4 v[10:13], v[4:5], off
	v_mad_u64_u32 v[4:5], s[0:1], v2, s77, v[22:23]
	v_mad_i32_i24 v5, v3, s77, v5
	v_lshlrev_b64 v[2:3], 13, v[2:3]
	v_lshl_add_u64 v[2:3], s[44:45], 0, v[2:3]
	v_lshl_add_u64 v[2:3], v[2:3], 0, v[0:1]
	v_lshl_add_u64 v[4:5], v[4:5], 0, v[24:25]
	v_lshl_add_u64 v[26:27], v[2:3], 0, v[18:19]
	global_load_dword v28, v[4:5], off offset:256
	global_load_dwordx4 v[6:9], v[26:27], off
	s_waitcnt vmcnt(2)
	v_lshlrev_b32_e32 v31, 16, v10
	v_and_b32_e32 v10, 0xffff0000, v10
	v_mul_f32_e32 v2, 0xbfb8aa3b, v31
	v_mul_f32_e32 v3, 0xbfb8aa3b, v10
	v_exp_f32_e32 v2, v2
	v_exp_f32_e32 v3, v3
	s_nop 0
	v_pk_add_f32 v[32:33], v[2:3], 1.0 op_sel_hi:[1,0]
	s_nop 0
	v_div_scale_f32 v36, s[0:1], v33, v33, v10
	v_rcp_f32_e32 v37, v36
	ds_read_b128 v[2:5], v30 offset:5440
	s_waitcnt lgkmcnt(1)
	v_lshlrev_b32_e32 v34, 16, v14
	v_and_b32_e32 v35, 0xffff0000, v14
	v_fma_f32 v14, -v36, v37, 1.0
	v_fmac_f32_e32 v37, v14, v37
	v_div_scale_f32 v14, vcc, v10, v33, v10
	v_mul_f32_e32 v38, v14, v37
	v_fma_f32 v39, -v36, v38, v14
	v_fmac_f32_e32 v38, v39, v37
	v_fma_f32 v14, -v36, v38, v14
	v_div_scale_f32 v36, s[0:1], v32, v32, v31
	v_rcp_f32_e32 v39, v36
	v_div_fmas_f32 v14, v14, v37, v38
	v_div_fixup_f32 v33, v14, v33, v10
	v_and_b32_e32 v38, 0xffff0000, v11
	v_fma_f32 v10, -v36, v39, 1.0
	v_fmac_f32_e32 v39, v10, v39
	v_div_scale_f32 v10, vcc, v31, v32, v31
	v_mul_f32_e32 v14, v10, v39
	v_fma_f32 v37, -v36, v14, v10
	v_fmac_f32_e32 v14, v37, v39
	v_fma_f32 v10, -v36, v14, v10
	v_div_fmas_f32 v10, v10, v39, v14
	v_div_fixup_f32 v32, v10, v32, v31
	v_lshlrev_b32_e32 v31, 16, v11
	v_mul_f32_e32 v11, 0xbfb8aa3b, v31
	v_exp_f32_e32 v36, v11
	v_mul_f32_e32 v11, 0xbfb8aa3b, v38
	v_exp_f32_e32 v37, v11
	s_waitcnt vmcnt(1)
	v_pk_mul_f32 v[34:35], v[28:29], v[34:35] op_sel_hi:[0,1]
	s_waitcnt vmcnt(0)
	v_lshlrev_b32_e32 v10, 16, v6
	v_and_b32_e32 v11, 0xffff0000, v6
	v_pk_fma_f32 v[10:11], v[34:35], v[32:33], v[10:11]
	v_lshlrev_b32_e32 v14, 16, v15
	v_cvt_pk_bf16_f32 v6, v10, v11
	v_pk_add_f32 v[10:11], v[36:37], 1.0 op_sel_hi:[1,0]
	v_and_b32_e32 v15, 0xffff0000, v15
	v_div_scale_f32 v32, s[0:1], v11, v11, v38
	v_rcp_f32_e32 v33, v32
	v_pk_mul_f32 v[14:15], v[28:29], v[14:15] op_sel_hi:[0,1]
	v_fma_f32 v34, -v32, v33, 1.0
	v_fmac_f32_e32 v33, v34, v33
	v_div_scale_f32 v34, vcc, v38, v11, v38
	v_mul_f32_e32 v35, v34, v33
	v_fma_f32 v36, -v32, v35, v34
	v_fmac_f32_e32 v35, v36, v33
	v_fma_f32 v32, -v32, v35, v34
	v_div_scale_f32 v34, s[0:1], v10, v10, v31
	v_rcp_f32_e32 v36, v34
	v_div_fmas_f32 v32, v32, v33, v35
	v_div_fixup_f32 v11, v32, v11, v38
	v_fma_f32 v32, -v34, v36, 1.0
	v_fmac_f32_e32 v36, v32, v36
	v_div_scale_f32 v32, vcc, v31, v10, v31
	v_mul_f32_e32 v33, v32, v36
	v_fma_f32 v35, -v34, v33, v32
	v_fmac_f32_e32 v33, v35, v36
	v_fma_f32 v32, -v34, v33, v32
	v_div_fmas_f32 v32, v32, v36, v33
	v_div_fixup_f32 v10, v32, v10, v31
	v_lshlrev_b32_e32 v31, 16, v12
	v_and_b32_e32 v12, 0xffff0000, v12
	v_mul_f32_e32 v33, 0xbfb8aa3b, v31
	v_exp_f32_e32 v34, v33
	v_mul_f32_e32 v33, 0xbfb8aa3b, v12
	v_exp_f32_e32 v35, v33
	v_lshlrev_b32_e32 v32, 16, v7
	v_and_b32_e32 v33, 0xffff0000, v7
	v_pk_fma_f32 v[10:11], v[14:15], v[10:11], v[32:33]
	v_lshlrev_b32_e32 v14, 16, v16
	v_cvt_pk_bf16_f32 v7, v10, v11
	v_pk_add_f32 v[10:11], v[34:35], 1.0 op_sel_hi:[1,0]
	v_and_b32_e32 v15, 0xffff0000, v16
	v_div_scale_f32 v32, s[0:1], v11, v11, v12
	v_rcp_f32_e32 v33, v32
	v_pk_mul_f32 v[14:15], v[28:29], v[14:15] op_sel_hi:[0,1]
	v_fma_f32 v16, -v32, v33, 1.0
	v_fmac_f32_e32 v33, v16, v33
	v_div_scale_f32 v16, vcc, v12, v11, v12
	v_mul_f32_e32 v34, v16, v33
	v_fma_f32 v35, -v32, v34, v16
	v_fmac_f32_e32 v34, v35, v33
	v_fma_f32 v16, -v32, v34, v16
	v_div_scale_f32 v32, s[0:1], v10, v10, v31
	v_rcp_f32_e32 v35, v32
	v_div_fmas_f32 v16, v16, v33, v34
	v_div_fixup_f32 v11, v16, v11, v12
	v_fma_f32 v12, -v32, v35, 1.0
	v_fmac_f32_e32 v35, v12, v35
	v_div_scale_f32 v12, vcc, v31, v10, v31
	v_mul_f32_e32 v16, v12, v35
	v_fma_f32 v33, -v32, v16, v12
	v_fmac_f32_e32 v16, v33, v35
	v_fma_f32 v12, -v32, v16, v12
	v_div_fmas_f32 v12, v12, v35, v16
	v_lshlrev_b32_e32 v16, 16, v13
	v_div_fixup_f32 v10, v12, v10, v31
	v_and_b32_e32 v31, 0xffff0000, v13
	v_mul_f32_e32 v13, 0xbfb8aa3b, v16
	v_exp_f32_e32 v32, v13
	v_mul_f32_e32 v13, 0xbfb8aa3b, v31
	v_exp_f32_e32 v33, v13
	v_lshlrev_b32_e32 v12, 16, v8
	v_and_b32_e32 v13, 0xffff0000, v8
	v_pk_fma_f32 v[10:11], v[14:15], v[10:11], v[12:13]
	v_lshlrev_b32_e32 v12, 16, v17
	v_cvt_pk_bf16_f32 v8, v10, v11
	v_pk_add_f32 v[10:11], v[32:33], 1.0 op_sel_hi:[1,0]
	v_and_b32_e32 v13, 0xffff0000, v17
	v_div_scale_f32 v14, s[0:1], v11, v11, v31
	v_rcp_f32_e32 v15, v14
	v_pk_mul_f32 v[12:13], v[28:29], v[12:13] op_sel_hi:[0,1]
	s_waitcnt lgkmcnt(0)
	v_and_b32_e32 v33, 0xffff0000, v2
	v_fma_f32 v17, -v14, v15, 1.0
	v_fmac_f32_e32 v15, v17, v15
	v_div_scale_f32 v17, vcc, v31, v11, v31
	v_mul_f32_e32 v28, v17, v15
	v_fma_f32 v32, -v14, v28, v17
	v_fmac_f32_e32 v28, v32, v15
	v_fma_f32 v14, -v14, v28, v17
	v_div_scale_f32 v17, s[0:1], v10, v10, v16
	v_rcp_f32_e32 v32, v17
	v_div_fmas_f32 v14, v14, v15, v28
	v_div_fixup_f32 v11, v14, v11, v31
	v_fma_f32 v14, -v17, v32, 1.0
	v_fmac_f32_e32 v32, v14, v32
	v_div_scale_f32 v14, vcc, v16, v10, v16
	v_mul_f32_e32 v15, v14, v32
	v_fma_f32 v28, -v17, v15, v14
	v_fmac_f32_e32 v15, v28, v32
	v_fma_f32 v14, -v17, v15, v14
	v_div_fmas_f32 v14, v14, v32, v15
	v_div_fixup_f32 v10, v14, v10, v16
	v_lshlrev_b32_e32 v14, 16, v9
	v_and_b32_e32 v15, 0xffff0000, v9
	v_pk_fma_f32 v[10:11], v[12:13], v[10:11], v[14:15]
	v_mov_b32_e32 v13, v1
	v_cvt_pk_bf16_f32 v9, v10, v11
	global_store_dwordx4 v[26:27], v[6:9], off
	v_mov_b32_e32 v17, v1
	v_lshlrev_b32_e32 v32, 16, v2
	v_add_u32_e32 v8, 20, v29
	v_ashrrev_i32_e32 v6, 3, v8
	v_ashrrev_i32_e32 v7, 31, v6
	v_lshl_add_u64 v[10:11], s[80:81], 0, v[6:7]
	v_and_or_b32 v16, v8, 7, s34
	v_mad_u64_u32 v[6:7], s[0:1], v10, s76, v[20:21]
	v_mad_i32_i24 v7, v11, s76, v7
	v_lshlrev_b32_e32 v12, 8, v16
	v_lshl_add_u64 v[6:7], v[6:7], 0, v[12:13]
	v_lshl_add_u64 v[6:7], v[6:7], 0, v[18:19]
	v_add_co_u32_e32 v6, vcc, s86, v6
	v_mad_u64_u32 v[14:15], s[0:1], v10, s77, v[22:23]
	s_nop 0
	v_addc_co_u32_e32 v7, vcc, 0, v7, vcc
	global_load_dwordx4 v[6:9], v[6:7], off
	v_mad_i32_i24 v15, v11, s77, v15
	v_lshlrev_b32_e32 v16, 2, v16
	v_lshl_add_u64 v[14:15], v[14:15], 0, v[16:17]
	global_load_dword v14, v[14:15], off offset:256
	v_lshlrev_b64 v[10:11], 13, v[10:11]
	v_lshl_add_u64 v[10:11], s[44:45], 0, v[10:11]
	v_lshl_add_u64 v[10:11], v[10:11], 0, v[12:13]
	v_lshl_add_u64 v[16:17], v[10:11], 0, v[18:19]
	global_load_dwordx4 v[10:13], v[16:17], off
	s_waitcnt vmcnt(2)
	v_lshlrev_b32_e32 v15, 16, v6
	v_and_b32_e32 v6, 0xffff0000, v6
	v_mul_f32_e32 v26, 0xbfb8aa3b, v15
	v_mul_f32_e32 v27, 0xbfb8aa3b, v6
	v_exp_f32_e32 v26, v26
	v_exp_f32_e32 v27, v27
	s_waitcnt vmcnt(1)
	v_pk_mul_f32 v[32:33], v[14:15], v[32:33] op_sel_hi:[0,1]
	v_pk_add_f32 v[26:27], v[26:27], 1.0 op_sel_hi:[1,0]
	s_nop 0
	v_div_scale_f32 v28, s[0:1], v27, v27, v6
	v_rcp_f32_e32 v31, v28
	s_nop 0
	v_fma_f32 v2, -v28, v31, 1.0
	v_fmac_f32_e32 v31, v2, v31
	v_div_scale_f32 v2, vcc, v6, v27, v6
	v_mul_f32_e32 v34, v2, v31
	v_fma_f32 v35, -v28, v34, v2
	v_fmac_f32_e32 v34, v35, v31
	v_fma_f32 v2, -v28, v34, v2
	v_div_scale_f32 v28, s[0:1], v26, v26, v15
	v_rcp_f32_e32 v35, v28
	v_div_fmas_f32 v2, v2, v31, v34
	v_div_fixup_f32 v27, v2, v27, v6
	v_fma_f32 v2, -v28, v35, 1.0
	v_fmac_f32_e32 v35, v2, v35
	v_div_scale_f32 v2, vcc, v15, v26, v15
	v_mul_f32_e32 v6, v2, v35
	v_fma_f32 v31, -v28, v6, v2
	v_fmac_f32_e32 v6, v31, v35
	v_fma_f32 v2, -v28, v6, v2
	v_div_fmas_f32 v2, v2, v35, v6
	v_div_fixup_f32 v26, v2, v26, v15
	v_lshlrev_b32_e32 v15, 16, v7
	v_and_b32_e32 v28, 0xffff0000, v7
	v_mul_f32_e32 v2, 0xbfb8aa3b, v15
	v_exp_f32_e32 v34, v2
	v_mul_f32_e32 v2, 0xbfb8aa3b, v28
	v_exp_f32_e32 v35, v2
	s_waitcnt vmcnt(0)
	v_lshlrev_b32_e32 v6, 16, v10
	v_and_b32_e32 v7, 0xffff0000, v10
	v_pk_fma_f32 v[6:7], v[32:33], v[26:27], v[6:7]
	v_lshlrev_b32_e32 v26, 16, v3
	v_cvt_pk_bf16_f32 v2, v6, v7
	v_pk_add_f32 v[6:7], v[34:35], 1.0 op_sel_hi:[1,0]
	v_and_b32_e32 v27, 0xffff0000, v3
	v_div_scale_f32 v10, s[0:1], v7, v7, v28
	v_rcp_f32_e32 v31, v10
	v_pk_mul_f32 v[26:27], v[14:15], v[26:27] op_sel_hi:[0,1]
	v_fma_f32 v3, -v10, v31, 1.0
	v_fmac_f32_e32 v31, v3, v31
	v_div_scale_f32 v3, vcc, v28, v7, v28
	v_mul_f32_e32 v32, v3, v31
	v_fma_f32 v33, -v10, v32, v3
	v_fmac_f32_e32 v32, v33, v31
	v_fma_f32 v3, -v10, v32, v3
	v_div_scale_f32 v10, s[0:1], v6, v6, v15
	v_rcp_f32_e32 v33, v10
	v_div_fmas_f32 v3, v3, v31, v32
	v_div_fixup_f32 v7, v3, v7, v28
	v_fma_f32 v3, -v10, v33, 1.0
	v_fmac_f32_e32 v33, v3, v33
	v_div_scale_f32 v3, vcc, v15, v6, v15
	v_mul_f32_e32 v28, v3, v33
	v_fma_f32 v31, -v10, v28, v3
	v_fmac_f32_e32 v28, v31, v33
	v_fma_f32 v3, -v10, v28, v3
	v_div_fmas_f32 v3, v3, v33, v28
	v_div_fixup_f32 v6, v3, v6, v15
	v_lshlrev_b32_e32 v15, 16, v8
	v_and_b32_e32 v8, 0xffff0000, v8
	v_mul_f32_e32 v3, 0xbfb8aa3b, v15
	v_exp_f32_e32 v32, v3
	v_mul_f32_e32 v3, 0xbfb8aa3b, v8
	v_exp_f32_e32 v33, v3
	v_lshlrev_b32_e32 v10, 16, v11
	v_and_b32_e32 v11, 0xffff0000, v11
	v_pk_fma_f32 v[6:7], v[26:27], v[6:7], v[10:11]
	v_lshlrev_b32_e32 v10, 16, v4
	v_cvt_pk_bf16_f32 v3, v6, v7
	v_pk_add_f32 v[6:7], v[32:33], 1.0 op_sel_hi:[1,0]
	v_and_b32_e32 v11, 0xffff0000, v4
	v_div_scale_f32 v26, s[0:1], v7, v7, v8
	v_rcp_f32_e32 v27, v26
	v_pk_mul_f32 v[10:11], v[14:15], v[10:11] op_sel_hi:[0,1]
	v_fma_f32 v4, -v26, v27, 1.0
	v_fmac_f32_e32 v27, v4, v27
	v_div_scale_f32 v4, vcc, v8, v7, v8
	v_mul_f32_e32 v28, v4, v27
	v_fma_f32 v31, -v26, v28, v4
	v_fmac_f32_e32 v28, v31, v27
	v_fma_f32 v4, -v26, v28, v4
	v_div_scale_f32 v26, s[0:1], v6, v6, v15
	v_rcp_f32_e32 v31, v26
	v_div_fmas_f32 v4, v4, v27, v28
	v_div_fixup_f32 v7, v4, v7, v8
	v_and_b32_e32 v28, 0xffff0000, v9
	v_fma_f32 v4, -v26, v31, 1.0
	v_fmac_f32_e32 v31, v4, v31
	v_div_scale_f32 v4, vcc, v15, v6, v15
	v_mul_f32_e32 v8, v4, v31
	v_fma_f32 v27, -v26, v8, v4
	v_fmac_f32_e32 v8, v27, v31
	v_fma_f32 v4, -v26, v8, v4
	v_div_fmas_f32 v4, v4, v31, v8
	v_div_fixup_f32 v6, v4, v6, v15
	v_lshlrev_b32_e32 v15, 16, v9
	v_mul_f32_e32 v4, 0xbfb8aa3b, v15
	v_exp_f32_e32 v26, v4
	v_mul_f32_e32 v4, 0xbfb8aa3b, v28
	v_exp_f32_e32 v27, v4
	v_lshlrev_b32_e32 v8, 16, v12
	v_and_b32_e32 v9, 0xffff0000, v12
	v_pk_fma_f32 v[6:7], v[10:11], v[6:7], v[8:9]
	v_lshlrev_b32_e32 v8, 16, v5
	v_cvt_pk_bf16_f32 v4, v6, v7
	v_pk_add_f32 v[6:7], v[26:27], 1.0 op_sel_hi:[1,0]
	v_and_b32_e32 v9, 0xffff0000, v5
	v_div_scale_f32 v10, s[0:1], v7, v7, v28
	v_rcp_f32_e32 v11, v10
	v_pk_mul_f32 v[8:9], v[14:15], v[8:9] op_sel_hi:[0,1]
	v_fma_f32 v5, -v10, v11, 1.0
	v_fmac_f32_e32 v11, v5, v11
	v_div_scale_f32 v5, vcc, v28, v7, v28
	v_mul_f32_e32 v12, v5, v11
	v_fma_f32 v14, -v10, v12, v5
	v_fmac_f32_e32 v12, v14, v11
	v_fma_f32 v5, -v10, v12, v5
	v_div_scale_f32 v10, s[0:1], v6, v6, v15
	v_rcp_f32_e32 v14, v10
	v_div_fmas_f32 v5, v5, v11, v12
	v_div_fixup_f32 v7, v5, v7, v28
	v_fma_f32 v5, -v10, v14, 1.0
	v_fmac_f32_e32 v14, v5, v14
	v_div_scale_f32 v5, vcc, v15, v6, v15
	v_mul_f32_e32 v11, v5, v14
	v_fma_f32 v12, -v10, v11, v5
	v_fmac_f32_e32 v11, v12, v14
	v_fma_f32 v5, -v10, v11, v5
	v_div_fmas_f32 v5, v5, v14, v11
	v_div_fixup_f32 v6, v5, v6, v15
	v_lshlrev_b32_e32 v10, 16, v13
	v_and_b32_e32 v11, 0xffff0000, v13
	v_pk_fma_f32 v[6:7], v[8:9], v[6:7], v[10:11]
	s_nop 0
	v_cvt_pk_bf16_f32 v5, v6, v7
	global_store_dwordx4 v[16:17], v[2:5], off
	ds_read_b128 v[14:17], v30 offset:6528
	s_nop 0
	v_add_u32_e32 v2, 24, v29
	v_ashrrev_i32_e32 v2, 3, v2
	v_ashrrev_i32_e32 v3, 31, v2
	v_lshl_add_u64 v[2:3], s[80:81], 0, v[2:3]
	v_mad_u64_u32 v[4:5], s[0:1], v2, s76, v[20:21]
	v_mad_i32_i24 v5, v3, s76, v5
	v_lshl_add_u64 v[4:5], v[4:5], 0, v[0:1]
	v_lshl_add_u64 v[4:5], v[4:5], 0, v[18:19]
	v_add_co_u32_e32 v4, vcc, s86, v4
	s_nop 1
	v_addc_co_u32_e32 v5, vcc, 0, v5, vcc
	global_load_dwordx4 v[10:13], v[4:5], off
	v_mad_u64_u32 v[4:5], s[0:1], v2, s77, v[22:23]
	v_mad_i32_i24 v5, v3, s77, v5
	v_lshl_add_u64 v[4:5], v[4:5], 0, v[24:25]
	global_load_dword v26, v[4:5], off offset:256
	v_lshlrev_b64 v[2:3], 13, v[2:3]
	v_lshl_add_u64 v[2:3], s[44:45], 0, v[2:3]
	v_lshl_add_u64 v[2:3], v[2:3], 0, v[0:1]
	v_lshl_add_u64 v[24:25], v[2:3], 0, v[18:19]
	global_load_dwordx4 v[6:9], v[24:25], off
	s_waitcnt vmcnt(2)
	v_lshlrev_b32_e32 v0, 16, v10
	v_and_b32_e32 v10, 0xffff0000, v10
	v_mul_f32_e32 v2, 0xbfb8aa3b, v0
	v_mul_f32_e32 v3, 0xbfb8aa3b, v10
	v_exp_f32_e32 v2, v2
	v_exp_f32_e32 v3, v3
	s_nop 0
	v_pk_add_f32 v[32:33], v[2:3], 1.0 op_sel_hi:[1,0]
	s_nop 0
	v_div_scale_f32 v27, s[0:1], v33, v33, v10
	v_rcp_f32_e32 v28, v27
	ds_read_b128 v[2:5], v30 offset:7616
	s_waitcnt lgkmcnt(1)
	v_lshlrev_b32_e32 v30, 16, v14
	v_and_b32_e32 v31, 0xffff0000, v14
	v_fma_f32 v14, -v27, v28, 1.0
	v_fmac_f32_e32 v28, v14, v28
	v_div_scale_f32 v14, vcc, v10, v33, v10
	v_mul_f32_e32 v34, v14, v28
	v_fma_f32 v35, -v27, v34, v14
	v_fmac_f32_e32 v34, v35, v28
	s_waitcnt vmcnt(1)
	v_pk_mul_f32 v[30:31], v[26:27], v[30:31] op_sel_hi:[0,1]
	v_fma_f32 v14, -v27, v34, v14
	v_div_scale_f32 v27, s[0:1], v32, v32, v0
	v_rcp_f32_e32 v35, v27
	v_div_fmas_f32 v14, v14, v28, v34
	v_div_fixup_f32 v33, v14, v33, v10
	v_fma_f32 v10, -v27, v35, 1.0
	v_fmac_f32_e32 v35, v10, v35
	v_div_scale_f32 v10, vcc, v0, v32, v0
	v_mul_f32_e32 v14, v10, v35
	v_fma_f32 v28, -v27, v14, v10
	v_fmac_f32_e32 v14, v28, v35
	v_fma_f32 v10, -v27, v14, v10
	v_div_fmas_f32 v10, v10, v35, v14
	v_div_fixup_f32 v32, v10, v32, v0
	v_lshlrev_b32_e32 v0, 16, v11
	v_and_b32_e32 v27, 0xffff0000, v11
	v_mul_f32_e32 v11, 0xbfb8aa3b, v0
	v_exp_f32_e32 v34, v11
	v_mul_f32_e32 v11, 0xbfb8aa3b, v27
	v_exp_f32_e32 v35, v11
	s_waitcnt vmcnt(0)
	v_lshlrev_b32_e32 v10, 16, v6
	v_and_b32_e32 v11, 0xffff0000, v6
	v_pk_fma_f32 v[10:11], v[30:31], v[32:33], v[10:11]
	v_lshlrev_b32_e32 v14, 16, v15
	v_cvt_pk_bf16_f32 v6, v10, v11
	v_pk_add_f32 v[10:11], v[34:35], 1.0 op_sel_hi:[1,0]
	v_and_b32_e32 v15, 0xffff0000, v15
	v_div_scale_f32 v28, s[0:1], v11, v11, v27
	v_rcp_f32_e32 v30, v28
	v_pk_mul_f32 v[14:15], v[26:27], v[14:15] op_sel_hi:[0,1]
	v_fma_f32 v31, -v28, v30, 1.0
	v_fmac_f32_e32 v30, v31, v30
	v_div_scale_f32 v31, vcc, v27, v11, v27
	v_mul_f32_e32 v32, v31, v30
	v_fma_f32 v33, -v28, v32, v31
	v_fmac_f32_e32 v32, v33, v30
	v_fma_f32 v28, -v28, v32, v31
	v_div_scale_f32 v31, s[0:1], v10, v10, v0
	v_rcp_f32_e32 v33, v31
	v_div_fmas_f32 v28, v28, v30, v32
	v_div_fixup_f32 v11, v28, v11, v27
	v_fma_f32 v27, -v31, v33, 1.0
	v_fmac_f32_e32 v33, v27, v33
	v_div_scale_f32 v27, vcc, v0, v10, v0
	v_mul_f32_e32 v28, v27, v33
	v_fma_f32 v30, -v31, v28, v27
	v_fmac_f32_e32 v28, v30, v33
	v_fma_f32 v27, -v31, v28, v27
	v_div_fmas_f32 v27, v27, v33, v28
	v_div_fixup_f32 v10, v27, v10, v0
	v_lshlrev_b32_e32 v0, 16, v12
	v_and_b32_e32 v12, 0xffff0000, v12
	v_mul_f32_e32 v27, 0xbfb8aa3b, v0
	v_exp_f32_e32 v32, v27
	v_mul_f32_e32 v27, 0xbfb8aa3b, v12
	v_exp_f32_e32 v33, v27
	v_lshlrev_b32_e32 v30, 16, v7
	v_and_b32_e32 v31, 0xffff0000, v7
	v_pk_fma_f32 v[10:11], v[14:15], v[10:11], v[30:31]
	v_lshlrev_b32_e32 v14, 16, v16
	v_cvt_pk_bf16_f32 v7, v10, v11
	v_pk_add_f32 v[10:11], v[32:33], 1.0 op_sel_hi:[1,0]
	v_and_b32_e32 v15, 0xffff0000, v16
	v_div_scale_f32 v27, s[0:1], v11, v11, v12
	v_rcp_f32_e32 v28, v27
	v_pk_mul_f32 v[14:15], v[26:27], v[14:15] op_sel_hi:[0,1]
	v_fma_f32 v16, -v27, v28, 1.0
	v_fmac_f32_e32 v28, v16, v28
	v_div_scale_f32 v16, vcc, v12, v11, v12
	v_mul_f32_e32 v30, v16, v28
	v_fma_f32 v31, -v27, v30, v16
	v_fmac_f32_e32 v30, v31, v28
	v_fma_f32 v16, -v27, v30, v16
	v_div_scale_f32 v27, s[0:1], v10, v10, v0
	v_rcp_f32_e32 v31, v27
	v_div_fmas_f32 v16, v16, v28, v30
	v_div_fixup_f32 v11, v16, v11, v12
	v_fma_f32 v12, -v27, v31, 1.0
	v_fmac_f32_e32 v31, v12, v31
	v_div_scale_f32 v12, vcc, v0, v10, v0
	v_mul_f32_e32 v16, v12, v31
	v_fma_f32 v28, -v27, v16, v12
	v_fmac_f32_e32 v16, v28, v31
	v_fma_f32 v12, -v27, v16, v12
	v_div_fmas_f32 v12, v12, v31, v16
	v_div_fixup_f32 v10, v12, v10, v0
	v_lshlrev_b32_e32 v0, 16, v13
	v_and_b32_e32 v16, 0xffff0000, v13
	v_mul_f32_e32 v13, 0xbfb8aa3b, v0
	v_exp_f32_e32 v30, v13
	v_mul_f32_e32 v13, 0xbfb8aa3b, v16
	v_exp_f32_e32 v31, v13
	v_lshlrev_b32_e32 v12, 16, v8
	v_and_b32_e32 v13, 0xffff0000, v8
	v_pk_fma_f32 v[10:11], v[14:15], v[10:11], v[12:13]
	v_lshlrev_b32_e32 v12, 16, v17
	v_cvt_pk_bf16_f32 v8, v10, v11
	v_pk_add_f32 v[10:11], v[30:31], 1.0 op_sel_hi:[1,0]
	v_and_b32_e32 v13, 0xffff0000, v17
	v_div_scale_f32 v14, s[0:1], v11, v11, v16
	v_rcp_f32_e32 v15, v14
	v_pk_mul_f32 v[12:13], v[26:27], v[12:13] op_sel_hi:[0,1]
	v_fma_f32 v17, -v14, v15, 1.0
	v_fmac_f32_e32 v15, v17, v15
	v_div_scale_f32 v17, vcc, v16, v11, v16
	v_mul_f32_e32 v26, v17, v15
	v_fma_f32 v27, -v14, v26, v17
	v_fmac_f32_e32 v26, v27, v15
	v_fma_f32 v14, -v14, v26, v17
	v_div_scale_f32 v17, s[0:1], v10, v10, v0
	v_rcp_f32_e32 v27, v17
	v_div_fmas_f32 v14, v14, v15, v26
	v_div_fixup_f32 v11, v14, v11, v16
	v_fma_f32 v14, -v17, v27, 1.0
	v_fmac_f32_e32 v27, v14, v27
	v_div_scale_f32 v14, vcc, v0, v10, v0
	v_mul_f32_e32 v15, v14, v27
	v_fma_f32 v16, -v17, v15, v14
	v_fmac_f32_e32 v15, v16, v27
	v_fma_f32 v14, -v17, v15, v14
	v_div_fmas_f32 v14, v14, v27, v15
	v_div_fixup_f32 v10, v14, v10, v0
	v_lshlrev_b32_e32 v14, 16, v9
	v_and_b32_e32 v15, 0xffff0000, v9
	v_pk_fma_f32 v[10:11], v[12:13], v[10:11], v[14:15]
	v_add_u32_e32 v0, 28, v29
	v_cvt_pk_bf16_f32 v9, v10, v11
	global_store_dwordx4 v[24:25], v[6:9], off
	v_and_or_b32 v14, v0, 7, s34
	v_mov_b32_e32 v15, v1
	v_ashrrev_i32_e32 v6, 3, v0
	v_ashrrev_i32_e32 v7, 31, v6
	v_lshl_add_u64 v[10:11], s[80:81], 0, v[6:7]
	v_mad_u64_u32 v[6:7], s[0:1], v10, s76, v[20:21]
	v_mad_i32_i24 v7, v11, s76, v7
	v_lshlrev_b32_e32 v0, 8, v14
	v_lshl_add_u64 v[6:7], v[6:7], 0, v[0:1]
	v_lshl_add_u64 v[6:7], v[6:7], 0, v[18:19]
	v_add_co_u32_e32 v6, vcc, s86, v6
	v_mad_u64_u32 v[12:13], s[0:1], v10, s77, v[22:23]
	s_nop 0
	v_addc_co_u32_e32 v7, vcc, 0, v7, vcc
	global_load_dwordx4 v[6:9], v[6:7], off
	v_mad_i32_i24 v13, v11, s77, v13
	v_lshlrev_b32_e32 v14, 2, v14
	v_lshl_add_u64 v[12:13], v[12:13], 0, v[14:15]
	global_load_dword v14, v[12:13], off offset:256
	v_lshlrev_b64 v[10:11], 13, v[10:11]
	v_lshl_add_u64 v[10:11], s[44:45], 0, v[10:11]
	v_lshl_add_u64 v[10:11], v[10:11], 0, v[0:1]
	v_lshl_add_u64 v[16:17], v[10:11], 0, v[18:19]
	global_load_dwordx4 v[10:13], v[16:17], off
	s_waitcnt lgkmcnt(0)
	v_lshlrev_b32_e32 v20, 16, v2
	v_and_b32_e32 v21, 0xffff0000, v2
	s_waitcnt vmcnt(2)
	v_lshlrev_b32_e32 v0, 16, v6
	v_and_b32_e32 v6, 0xffff0000, v6
	v_mul_f32_e32 v15, 0xbfb8aa3b, v0
	v_exp_f32_e32 v18, v15
	v_mul_f32_e32 v15, 0xbfb8aa3b, v6
	v_exp_f32_e32 v19, v15
	s_nop 0
	v_pk_add_f32 v[18:19], v[18:19], 1.0 op_sel_hi:[1,0]
	s_nop 0
	v_div_scale_f32 v15, s[0:1], v19, v19, v6
	v_rcp_f32_e32 v22, v15
	s_waitcnt vmcnt(1)
	v_pk_mul_f32 v[20:21], v[14:15], v[20:21] op_sel_hi:[0,1]
	v_fma_f32 v2, -v15, v22, 1.0
	v_fmac_f32_e32 v22, v2, v22
	v_div_scale_f32 v2, vcc, v6, v19, v6
	v_mul_f32_e32 v23, v2, v22
	v_fma_f32 v24, -v15, v23, v2
	v_fmac_f32_e32 v23, v24, v22
	v_fma_f32 v2, -v15, v23, v2
	v_div_scale_f32 v15, s[0:1], v18, v18, v0
	v_rcp_f32_e32 v24, v15
	v_div_fmas_f32 v2, v2, v22, v23
	v_div_fixup_f32 v19, v2, v19, v6
	v_fma_f32 v2, -v15, v24, 1.0
	v_fmac_f32_e32 v24, v2, v24
	v_div_scale_f32 v2, vcc, v0, v18, v0
	v_mul_f32_e32 v6, v2, v24
	v_fma_f32 v22, -v15, v6, v2
	v_fmac_f32_e32 v6, v22, v24
	v_fma_f32 v2, -v15, v6, v2
	v_div_fmas_f32 v2, v2, v24, v6
	v_div_fixup_f32 v18, v2, v18, v0
	v_lshlrev_b32_e32 v0, 16, v7
	v_and_b32_e32 v15, 0xffff0000, v7
	v_mul_f32_e32 v2, 0xbfb8aa3b, v0
	v_exp_f32_e32 v22, v2
	v_mul_f32_e32 v2, 0xbfb8aa3b, v15
	v_exp_f32_e32 v23, v2
	s_waitcnt vmcnt(0)
	v_lshlrev_b32_e32 v6, 16, v10
	v_and_b32_e32 v7, 0xffff0000, v10
	v_pk_fma_f32 v[6:7], v[20:21], v[18:19], v[6:7]
	v_lshlrev_b32_e32 v18, 16, v3
	v_cvt_pk_bf16_f32 v2, v6, v7
	v_pk_add_f32 v[6:7], v[22:23], 1.0 op_sel_hi:[1,0]
	v_and_b32_e32 v19, 0xffff0000, v3
	v_div_scale_f32 v10, s[0:1], v7, v7, v15
	v_rcp_f32_e32 v20, v10
	v_pk_mul_f32 v[18:19], v[14:15], v[18:19] op_sel_hi:[0,1]
	v_fma_f32 v3, -v10, v20, 1.0
	v_fmac_f32_e32 v20, v3, v20
	v_div_scale_f32 v3, vcc, v15, v7, v15
	v_mul_f32_e32 v21, v3, v20
	v_fma_f32 v22, -v10, v21, v3
	v_fmac_f32_e32 v21, v22, v20
	v_fma_f32 v3, -v10, v21, v3
	v_div_scale_f32 v10, s[0:1], v6, v6, v0
	v_rcp_f32_e32 v22, v10
	v_div_fmas_f32 v3, v3, v20, v21
	v_div_fixup_f32 v7, v3, v7, v15
	v_fma_f32 v3, -v10, v22, 1.0
	v_fmac_f32_e32 v22, v3, v22
	v_div_scale_f32 v3, vcc, v0, v6, v0
	v_mul_f32_e32 v15, v3, v22
	v_fma_f32 v20, -v10, v15, v3
	v_fmac_f32_e32 v15, v20, v22
	v_fma_f32 v3, -v10, v15, v3
	v_div_fmas_f32 v3, v3, v22, v15
	v_div_fixup_f32 v6, v3, v6, v0
	v_lshlrev_b32_e32 v0, 16, v8
	v_and_b32_e32 v8, 0xffff0000, v8
	v_mul_f32_e32 v3, 0xbfb8aa3b, v0
	v_exp_f32_e32 v20, v3
	v_mul_f32_e32 v3, 0xbfb8aa3b, v8
	v_exp_f32_e32 v21, v3
	v_lshlrev_b32_e32 v10, 16, v11
	v_and_b32_e32 v11, 0xffff0000, v11
	v_pk_fma_f32 v[6:7], v[18:19], v[6:7], v[10:11]
	v_lshlrev_b32_e32 v10, 16, v4
	v_cvt_pk_bf16_f32 v3, v6, v7
	v_pk_add_f32 v[6:7], v[20:21], 1.0 op_sel_hi:[1,0]
	v_and_b32_e32 v11, 0xffff0000, v4
	v_div_scale_f32 v15, s[0:1], v7, v7, v8
	v_rcp_f32_e32 v18, v15
	v_pk_mul_f32 v[10:11], v[14:15], v[10:11] op_sel_hi:[0,1]
	v_fma_f32 v4, -v15, v18, 1.0
	v_fmac_f32_e32 v18, v4, v18
	v_div_scale_f32 v4, vcc, v8, v7, v8
	v_mul_f32_e32 v19, v4, v18
	v_fma_f32 v20, -v15, v19, v4
	v_fmac_f32_e32 v19, v20, v18
	v_fma_f32 v4, -v15, v19, v4
	v_div_scale_f32 v15, s[0:1], v6, v6, v0
	v_rcp_f32_e32 v20, v15
	v_div_fmas_f32 v4, v4, v18, v19
	v_div_fixup_f32 v7, v4, v7, v8
	v_fma_f32 v4, -v15, v20, 1.0
	v_fmac_f32_e32 v20, v4, v20
	v_div_scale_f32 v4, vcc, v0, v6, v0
	v_mul_f32_e32 v8, v4, v20
	v_fma_f32 v18, -v15, v8, v4
	v_fmac_f32_e32 v8, v18, v20
	v_fma_f32 v4, -v15, v8, v4
	v_div_fmas_f32 v4, v4, v20, v8
	v_div_fixup_f32 v6, v4, v6, v0
	v_lshlrev_b32_e32 v0, 16, v9
	v_and_b32_e32 v15, 0xffff0000, v9
	v_mul_f32_e32 v4, 0xbfb8aa3b, v0
	v_exp_f32_e32 v18, v4
	v_mul_f32_e32 v4, 0xbfb8aa3b, v15
	v_exp_f32_e32 v19, v4
	v_lshlrev_b32_e32 v8, 16, v12
	v_and_b32_e32 v9, 0xffff0000, v12
	v_pk_fma_f32 v[6:7], v[10:11], v[6:7], v[8:9]
	v_lshlrev_b32_e32 v8, 16, v5
	v_cvt_pk_bf16_f32 v4, v6, v7
	v_pk_add_f32 v[6:7], v[18:19], 1.0 op_sel_hi:[1,0]
	v_and_b32_e32 v9, 0xffff0000, v5
	v_div_scale_f32 v10, s[0:1], v7, v7, v15
	v_rcp_f32_e32 v11, v10
	v_pk_mul_f32 v[8:9], v[14:15], v[8:9] op_sel_hi:[0,1]
	v_fma_f32 v5, -v10, v11, 1.0
	v_fmac_f32_e32 v11, v5, v11
	v_div_scale_f32 v5, vcc, v15, v7, v15
	v_mul_f32_e32 v12, v5, v11
	v_fma_f32 v14, -v10, v12, v5
	v_fmac_f32_e32 v12, v14, v11
	v_fma_f32 v5, -v10, v12, v5
	v_div_scale_f32 v10, s[0:1], v6, v6, v0
	v_rcp_f32_e32 v14, v10
	v_div_fmas_f32 v5, v5, v11, v12
	v_div_fixup_f32 v7, v5, v7, v15
	v_fma_f32 v5, -v10, v14, 1.0
	v_fmac_f32_e32 v14, v5, v14
	v_div_scale_f32 v5, vcc, v0, v6, v0
	v_mul_f32_e32 v11, v5, v14
	v_fma_f32 v12, -v10, v11, v5
	v_fmac_f32_e32 v11, v12, v14
	v_fma_f32 v5, -v10, v11, v5
	v_div_fmas_f32 v5, v5, v14, v11
	v_div_fixup_f32 v6, v5, v6, v0
	v_lshlrev_b32_e32 v10, 16, v13
	v_and_b32_e32 v11, 0xffff0000, v13
	v_pk_fma_f32 v[6:7], v[8:9], v[6:7], v[10:11]
	s_nop 0
	v_cvt_pk_bf16_f32 v5, v6, v7
	global_store_dwordx4 v[16:17], v[2:5], off
	s_barrier
	s_cbranch_scc1 .LBB0_1246

.LBB0_1164:
	v_mov_b32_e32 v0, v177
	v_cvt_pk_bf16_f32 v50, v50, v51
	v_and_b32_e32 v66, 31, v0
	v_cvt_pk_bf16_f32 v51, v52, v53
	v_ashrrev_i32_e32 v52, 2, v0
	v_mul_u32_u24_e32 v66, 0x110, v66
	v_and_b32_e32 v52, -8, v52
	v_add3_u32 v66, s95, v66, v52
	v_cvt_pk_bf16_f32 v2, v2, v3
	v_cvt_pk_bf16_f32 v3, v4, v5
	v_cvt_pk_bf16_f32 v4, v6, v7
	v_cvt_pk_bf16_f32 v5, v8, v9
	s_add_i32 s12, s67, s93
	ds_write2_b64 v66, v[2:3], v[4:5] offset0:24 offset1:26
	v_cvt_pk_bf16_f32 v2, v10, v11
	v_cvt_pk_bf16_f32 v3, v12, v13
	v_cvt_pk_bf16_f32 v4, v14, v15
	v_cvt_pk_bf16_f32 v5, v16, v17
	ds_write2_b64 v66, v[2:3], v[4:5] offset0:28 offset1:30
	s_lshl_b64 s[0:1], s[62:63], 12
	s_ashr_i32 s13, s12, 31
	v_lshlrev_b32_e32 v2, 4, v0
	s_add_u32 s80, s0, s12
	v_and_b32_e32 v14, 0xf0, v2
	v_ashrrev_i32_e32 v2, 7, v0
	s_addc_u32 s81, s1, s13
	v_ashrrev_i32_e32 v3, 31, v2
	v_cvt_pk_bf16_f32 v18, v18, v19
	v_cvt_pk_bf16_f32 v19, v20, v21
	v_cvt_pk_bf16_f32 v21, v24, v25
	v_ashrrev_i32_e32 v25, 4, v0
	v_lshl_add_u64 v[2:3], s[80:81], 0, v[2:3]
	v_mov_b64_e32 v[16:17], s[48:49]
	v_cvt_pk_bf16_f32 v52, v54, v55
	v_cvt_pk_bf16_f32 v53, v56, v57
	v_cvt_pk_bf16_f32 v34, v34, v35
	v_cvt_pk_bf16_f32 v35, v36, v37
	v_cvt_pk_bf16_f32 v36, v38, v39
	v_cvt_pk_bf16_f32 v37, v40, v41
	v_cvt_pk_bf16_f32 v20, v22, v23
	v_and_or_b32 v10, v25, 7, s34
	v_mad_u64_u32 v[4:5], s[0:1], v2, s76, v[16:17]
	ds_write2_b64 v66, v[50:51], v[52:53] offset1:2
	v_cvt_pk_bf16_f32 v50, v58, v59
	v_cvt_pk_bf16_f32 v51, v60, v61
	v_cvt_pk_bf16_f32 v52, v62, v63
	v_cvt_pk_bf16_f32 v53, v64, v65
	ds_write2_b64 v66, v[34:35], v[36:37] offset0:8 offset1:10
	v_cvt_pk_bf16_f32 v34, v42, v43
	v_cvt_pk_bf16_f32 v35, v44, v45
	v_cvt_pk_bf16_f32 v36, v46, v47
	v_cvt_pk_bf16_f32 v37, v48, v49
	ds_write2_b64 v66, v[18:19], v[20:21] offset0:16 offset1:18
	v_cvt_pk_bf16_f32 v18, v26, v27
	v_cvt_pk_bf16_f32 v19, v28, v29
	v_cvt_pk_bf16_f32 v20, v30, v31
	v_cvt_pk_bf16_f32 v21, v32, v33
	v_mad_i32_i24 v5, v3, s76, v5
	v_lshlrev_b32_e32 v0, 8, v10
	ds_write2_b64 v66, v[50:51], v[52:53] offset0:4 offset1:6
	ds_write2_b64 v66, v[34:35], v[36:37] offset0:12 offset1:14
	ds_write2_b64 v66, v[18:19], v[20:21] offset0:20 offset1:22
	v_lshl_add_u64 v[4:5], v[4:5], 0, v[0:1]
	v_mov_b32_e32 v15, v1
	s_waitcnt lgkmcnt(0)
	v_lshl_add_u64 v[4:5], v[4:5], 0, v[14:15]
	global_load_dwordx4 v[6:9], v[4:5], off
	global_load_dwordx4 v[40:43], v[4:5], off offset:1024
	v_add_co_u32_e32 v68, vcc, 0x6000, v4
	s_nop 1
	v_addc_co_u32_e32 v69, vcc, 0, v5, vcc
	global_load_dwordx4 v[44:47], v[68:69], off
	global_load_dwordx4 v[48:51], v[68:69], off offset:1024
	v_add_co_u32_e32 v68, vcc, 0xc000, v4
	s_nop 1
	v_addc_co_u32_e32 v69, vcc, 0, v5, vcc
	global_load_dwordx4 v[52:55], v[68:69], off
	global_load_dwordx4 v[56:59], v[68:69], off offset:1024
	v_add_co_u32_e32 v68, vcc, 0x12000, v4
	s_nop 1
	v_addc_co_u32_e32 v69, vcc, 0, v5, vcc
	global_load_dwordx4 v[60:63], v[68:69], off
	global_load_dwordx4 v[64:67], v[68:69], off offset:1024
	v_mov_b64_e32 v[18:19], s[50:51]
	v_mad_u64_u32 v[4:5], s[0:1], v2, s77, v[18:19]
	v_mad_i32_i24 v5, v3, s77, v5
	v_lshlrev_b32_e32 v20, 2, v10
	v_mov_b32_e32 v21, v1
	v_lshl_add_u64 v[4:5], v[4:5], 0, v[20:21]
	global_load_dword v24, v[4:5], off
	v_mul_lo_u32 v4, v25, s94
	v_lshlrev_b64 v[2:3], 13, v[2:3]
	v_add3_u32 v26, s95, v14, v4
	v_lshl_add_u64 v[2:3], s[44:45], 0, v[2:3]
	v_lshl_add_u64 v[22:23], v[2:3], 0, v[0:1]
	ds_read_b128 v[10:13], v26
	ds_read_b128 v[2:5], v26 offset:1088
	s_waitcnt lgkmcnt(1)
	v_lshlrev_b32_e32 v30, 16, v10
	v_and_b32_e32 v31, 0xffff0000, v10
	s_waitcnt vmcnt(1)
	v_lshlrev_b32_e32 v27, 16, v6
	v_and_b32_e32 v6, 0xffff0000, v6
	v_mul_f32_e32 v28, 0xbfb8aa3b, v27
	v_mul_f32_e32 v29, 0xbfb8aa3b, v6
	v_exp_f32_e32 v28, v28
	v_exp_f32_e32 v29, v29
	s_waitcnt vmcnt(0)
	v_pk_mul_f32 v[30:31], v[24:25], v[30:31] op_sel_hi:[0,1]
	v_pk_add_f32 v[28:29], v[28:29], 1.0 op_sel_hi:[1,0]
	s_nop 0
	v_div_scale_f32 v10, s[0:1], v29, v29, v6
	v_rcp_f32_e32 v32, v10
	v_div_scale_f32 v33, vcc, v6, v29, v6
	v_div_scale_f32 v34, s[0:1], v28, v28, v27
	v_fma_f32 v35, -v10, v32, 1.0
	v_fmac_f32_e32 v32, v35, v32
	v_mul_f32_e32 v35, v33, v32
	v_fma_f32 v36, -v10, v35, v33
	v_fmac_f32_e32 v35, v36, v32
	v_fma_f32 v10, -v10, v35, v33
	v_rcp_f32_e32 v33, v34
	v_div_fmas_f32 v10, v10, v32, v35
	v_div_fixup_f32 v29, v10, v29, v6
	v_and_b32_e32 v35, 0xffff0000, v7
	v_fma_f32 v6, -v34, v33, 1.0
	v_fmac_f32_e32 v33, v6, v33
	v_div_scale_f32 v6, vcc, v27, v28, v27
	v_mul_f32_e32 v10, v6, v33
	v_fma_f32 v32, -v34, v10, v6
	v_fmac_f32_e32 v10, v32, v33
	v_fma_f32 v6, -v34, v10, v6
	v_lshlrev_b32_e32 v34, 16, v7
	v_mul_f32_e32 v7, 0xbfb8aa3b, v34
	v_exp_f32_e32 v32, v7
	v_mul_f32_e32 v7, 0xbfb8aa3b, v35
	v_div_fmas_f32 v6, v6, v33, v10
	v_exp_f32_e32 v33, v7
	v_div_fixup_f32 v28, v6, v28, v27
	v_pk_fma_f32 v[6:7], v[30:31], v[28:29], 0 op_sel_hi:[1,1,0]
	v_lshlrev_b32_e32 v10, 16, v11
	v_pk_add_f32 v[28:29], v[32:33], 1.0 op_sel_hi:[1,0]
	v_cvt_pk_bf16_f32 v6, v6, v7
	v_div_scale_f32 v7, s[0:1], v29, v29, v35
	v_rcp_f32_e32 v27, v7
	v_and_b32_e32 v11, 0xffff0000, v11
	v_pk_mul_f32 v[10:11], v[24:25], v[10:11] op_sel_hi:[0,1]
	v_fma_f32 v30, -v7, v27, 1.0
	v_fmac_f32_e32 v27, v30, v27
	v_div_scale_f32 v30, vcc, v35, v29, v35
	v_mul_f32_e32 v31, v30, v27
	v_fma_f32 v32, -v7, v31, v30
	v_fmac_f32_e32 v31, v32, v27
	v_fma_f32 v7, -v7, v31, v30
	v_div_scale_f32 v30, s[0:1], v28, v28, v34
	v_rcp_f32_e32 v32, v30
	v_div_fmas_f32 v7, v7, v27, v31
	v_div_fixup_f32 v29, v7, v29, v35
	v_fma_f32 v7, -v30, v32, 1.0
	v_fmac_f32_e32 v32, v7, v32
	v_div_scale_f32 v7, vcc, v34, v28, v34
	v_mul_f32_e32 v27, v7, v32
	v_fma_f32 v31, -v30, v27, v7
	v_fmac_f32_e32 v27, v31, v32
	v_fma_f32 v7, -v30, v27, v7
	v_div_fmas_f32 v7, v7, v32, v27
	v_lshlrev_b32_e32 v27, 16, v8
	v_and_b32_e32 v8, 0xffff0000, v8
	v_mul_f32_e32 v30, 0xbfb8aa3b, v27
	v_mul_f32_e32 v31, 0xbfb8aa3b, v8
	v_exp_f32_e32 v30, v30
	v_exp_f32_e32 v31, v31
	v_div_fixup_f32 v28, v7, v28, v34
	v_pk_fma_f32 v[10:11], v[10:11], v[28:29], 0 op_sel_hi:[1,1,0]
	v_lshlrev_b32_e32 v28, 16, v12
	v_cvt_pk_bf16_f32 v7, v10, v11
	v_pk_add_f32 v[10:11], v[30:31], 1.0 op_sel_hi:[1,0]
	v_and_b32_e32 v29, 0xffff0000, v12
	v_div_scale_f32 v30, s[0:1], v11, v11, v8
	v_rcp_f32_e32 v31, v30
	v_pk_mul_f32 v[28:29], v[24:25], v[28:29] op_sel_hi:[0,1]
	v_fma_f32 v12, -v30, v31, 1.0
	v_fmac_f32_e32 v31, v12, v31
	v_div_scale_f32 v12, vcc, v8, v11, v8
	v_mul_f32_e32 v32, v12, v31
	v_fma_f32 v33, -v30, v32, v12
	v_fmac_f32_e32 v32, v33, v31
	v_fma_f32 v12, -v30, v32, v12
	v_div_scale_f32 v30, s[0:1], v10, v10, v27
	v_rcp_f32_e32 v33, v30
	v_div_fmas_f32 v12, v12, v31, v32
	v_div_fixup_f32 v11, v12, v11, v8
	v_lshlrev_b32_e32 v32, 16, v9
	v_fma_f32 v8, -v30, v33, 1.0
	v_fmac_f32_e32 v33, v8, v33
	v_div_scale_f32 v8, vcc, v27, v10, v27
	v_mul_f32_e32 v12, v8, v33
	v_fma_f32 v31, -v30, v12, v8
	v_fmac_f32_e32 v12, v31, v33
	v_fma_f32 v8, -v30, v12, v8
	v_div_fmas_f32 v8, v8, v33, v12
	v_and_b32_e32 v33, 0xffff0000, v9
	v_mul_f32_e32 v9, 0xbfb8aa3b, v32
	v_exp_f32_e32 v30, v9
	v_mul_f32_e32 v9, 0xbfb8aa3b, v33
	v_exp_f32_e32 v31, v9
	v_div_fixup_f32 v10, v8, v10, v27
	v_pk_fma_f32 v[8:9], v[28:29], v[10:11], 0 op_sel_hi:[1,1,0]
	v_lshlrev_b32_e32 v12, 16, v13
	v_pk_add_f32 v[10:11], v[30:31], 1.0 op_sel_hi:[1,0]
	v_cvt_pk_bf16_f32 v8, v8, v9
	v_div_scale_f32 v9, s[0:1], v11, v11, v33
	v_rcp_f32_e32 v27, v9
	v_and_b32_e32 v13, 0xffff0000, v13
	v_pk_mul_f32 v[12:13], v[24:25], v[12:13] op_sel_hi:[0,1]
	v_fma_f32 v24, -v9, v27, 1.0
	v_fmac_f32_e32 v27, v24, v27
	v_div_scale_f32 v24, vcc, v33, v11, v33
	v_mul_f32_e32 v28, v24, v27
	v_fma_f32 v29, -v9, v28, v24
	v_fmac_f32_e32 v28, v29, v27
	v_fma_f32 v9, -v9, v28, v24
	v_div_scale_f32 v24, s[0:1], v10, v10, v32
	v_rcp_f32_e32 v29, v24
	v_div_fmas_f32 v9, v9, v27, v28
	v_div_fixup_f32 v11, v9, v11, v33
	v_fma_f32 v9, -v24, v29, 1.0
	v_fmac_f32_e32 v29, v9, v29
	v_div_scale_f32 v9, vcc, v32, v10, v32
	v_mul_f32_e32 v27, v9, v29
	v_fma_f32 v28, -v24, v27, v9
	v_fmac_f32_e32 v27, v28, v29
	v_fma_f32 v9, -v24, v27, v9
	v_div_fmas_f32 v9, v9, v29, v27
	v_div_fixup_f32 v10, v9, v10, v32
	v_pk_fma_f32 v[10:11], v[12:13], v[10:11], 0 op_sel_hi:[1,1,0]
	v_mov_b32_e32 v13, v1
	v_cvt_pk_bf16_f32 v9, v10, v11
	v_lshl_add_u64 v[10:11], v[22:23], 0, v[14:15]
	global_store_dwordx4 v[10:11], v[6:9], off
	v_mov_b32_e32 v29, v1
	s_nop 0
	v_add_u32_e32 v8, 4, v25
	v_ashrrev_i32_e32 v6, 3, v8
	v_ashrrev_i32_e32 v7, 31, v6
	v_lshl_add_u64 v[10:11], s[80:81], 0, v[6:7]
	v_and_or_b32 v24, v8, 7, s34
	v_mad_u64_u32 v[6:7], s[0:1], v10, s76, v[16:17]
	v_mad_i32_i24 v7, v11, s76, v7
	v_lshlrev_b32_e32 v12, 8, v24
	v_lshl_add_u64 v[6:7], v[6:7], 0, v[12:13]
	v_lshl_add_u64 v[6:7], v[6:7], 0, v[14:15]
	global_load_dwordx4 v[6:9], v[6:7], off
	v_mad_u64_u32 v[22:23], s[0:1], v10, s77, v[18:19]
	v_mad_i32_i24 v23, v11, s77, v23
	v_lshlrev_b32_e32 v28, 2, v24
	v_lshl_add_u64 v[22:23], v[22:23], 0, v[28:29]
	global_load_dword v22, v[22:23], off
	v_lshlrev_b64 v[10:11], 13, v[10:11]
	v_lshl_add_u64 v[10:11], s[44:45], 0, v[10:11]
	v_lshl_add_u64 v[10:11], v[10:11], 0, v[12:13]
	s_waitcnt vmcnt(1)
	v_lshlrev_b32_e32 v23, 16, v6
	v_and_b32_e32 v6, 0xffff0000, v6
	v_mul_f32_e32 v24, 0xbfb8aa3b, v23
	v_exp_f32_e32 v28, v24
	v_mul_f32_e32 v24, 0xbfb8aa3b, v6
	v_exp_f32_e32 v29, v24
	s_nop 0
	v_pk_add_f32 v[12:13], v[28:29], 1.0 op_sel_hi:[1,0]
	s_nop 0
	v_div_scale_f32 v24, s[0:1], v13, v13, v6
	v_rcp_f32_e32 v27, v24
	s_waitcnt lgkmcnt(0)
	v_lshlrev_b32_e32 v28, 16, v2
	v_and_b32_e32 v29, 0xffff0000, v2
	s_waitcnt vmcnt(0)
	v_pk_mul_f32 v[28:29], v[22:23], v[28:29] op_sel_hi:[0,1]
	v_fma_f32 v2, -v24, v27, 1.0
	v_fmac_f32_e32 v27, v2, v27
	v_div_scale_f32 v2, vcc, v6, v13, v6
	v_mul_f32_e32 v30, v2, v27
	v_fma_f32 v31, -v24, v30, v2
	v_fmac_f32_e32 v30, v31, v27
	v_fma_f32 v2, -v24, v30, v2
	v_div_scale_f32 v24, s[0:1], v12, v12, v23
	v_rcp_f32_e32 v31, v24
	v_div_fmas_f32 v2, v2, v27, v30
	v_div_fixup_f32 v13, v2, v13, v6
	v_fma_f32 v2, -v24, v31, 1.0
	v_fmac_f32_e32 v31, v2, v31
	v_div_scale_f32 v2, vcc, v23, v12, v23
	v_mul_f32_e32 v6, v2, v31
	v_fma_f32 v27, -v24, v6, v2
	v_fmac_f32_e32 v6, v27, v31
	v_fma_f32 v2, -v24, v6, v2
	v_lshlrev_b32_e32 v24, 16, v7
	v_and_b32_e32 v27, 0xffff0000, v7
	v_div_fmas_f32 v2, v2, v31, v6
	v_mul_f32_e32 v6, 0xbfb8aa3b, v24
	v_mul_f32_e32 v7, 0xbfb8aa3b, v27
	v_exp_f32_e32 v6, v6
	v_exp_f32_e32 v7, v7
	v_div_fixup_f32 v12, v2, v12, v23
	v_pk_fma_f32 v[12:13], v[28:29], v[12:13], 0 op_sel_hi:[1,1,0]
	v_pk_add_f32 v[6:7], v[6:7], 1.0 op_sel_hi:[1,0]
	s_nop 0
	v_div_scale_f32 v23, s[0:1], v7, v7, v27
	v_rcp_f32_e32 v28, v23
	v_cvt_pk_bf16_f32 v2, v12, v13
	v_lshlrev_b32_e32 v12, 16, v3
	v_and_b32_e32 v13, 0xffff0000, v3
	v_fma_f32 v3, -v23, v28, 1.0
	v_fmac_f32_e32 v28, v3, v28
	v_div_scale_f32 v3, vcc, v27, v7, v27
	v_mul_f32_e32 v29, v3, v28
	v_fma_f32 v30, -v23, v29, v3
	v_fmac_f32_e32 v29, v30, v28
	v_pk_mul_f32 v[12:13], v[22:23], v[12:13] op_sel_hi:[0,1]
	v_fma_f32 v3, -v23, v29, v3
	v_div_scale_f32 v23, s[0:1], v6, v6, v24
	v_rcp_f32_e32 v30, v23
	v_div_fmas_f32 v3, v3, v28, v29
	v_div_fixup_f32 v7, v3, v7, v27
	v_fma_f32 v3, -v23, v30, 1.0
	v_fmac_f32_e32 v30, v3, v30
	v_div_scale_f32 v3, vcc, v24, v6, v24
	v_mul_f32_e32 v27, v3, v30
	v_fma_f32 v28, -v23, v27, v3
	v_fmac_f32_e32 v27, v28, v30
	v_fma_f32 v3, -v23, v27, v3
	v_lshlrev_b32_e32 v23, 16, v8
	v_div_fmas_f32 v3, v3, v30, v27
	v_and_b32_e32 v8, 0xffff0000, v8
	v_mul_f32_e32 v27, 0xbfb8aa3b, v23
	v_exp_f32_e32 v28, v27
	v_mul_f32_e32 v27, 0xbfb8aa3b, v8
	v_exp_f32_e32 v29, v27
	v_div_fixup_f32 v6, v3, v6, v24
	v_pk_fma_f32 v[6:7], v[12:13], v[6:7], 0 op_sel_hi:[1,1,0]
	v_lshlrev_b32_e32 v12, 16, v4
	v_cvt_pk_bf16_f32 v3, v6, v7
	v_pk_add_f32 v[6:7], v[28:29], 1.0 op_sel_hi:[1,0]
	v_and_b32_e32 v13, 0xffff0000, v4
	v_div_scale_f32 v24, s[0:1], v7, v7, v8
	v_rcp_f32_e32 v27, v24
	v_pk_mul_f32 v[12:13], v[22:23], v[12:13] op_sel_hi:[0,1]
	v_fma_f32 v4, -v24, v27, 1.0
	v_fmac_f32_e32 v27, v4, v27
	v_div_scale_f32 v4, vcc, v8, v7, v8
	v_mul_f32_e32 v28, v4, v27
	v_fma_f32 v29, -v24, v28, v4
	v_fmac_f32_e32 v28, v29, v27
	v_fma_f32 v4, -v24, v28, v4
	v_div_scale_f32 v24, s[0:1], v6, v6, v23
	v_rcp_f32_e32 v29, v24
	v_div_fmas_f32 v4, v4, v27, v28
	v_div_fixup_f32 v7, v4, v7, v8
	v_fma_f32 v4, -v24, v29, 1.0
	v_fmac_f32_e32 v29, v4, v29
	v_div_scale_f32 v4, vcc, v23, v6, v23
	v_mul_f32_e32 v8, v4, v29
	v_fma_f32 v27, -v24, v8, v4
	v_fmac_f32_e32 v8, v27, v29
	v_fma_f32 v4, -v24, v8, v4
	v_lshlrev_b32_e32 v24, 16, v9
	v_and_b32_e32 v27, 0xffff0000, v9
	v_div_fmas_f32 v4, v4, v29, v8
	v_mul_f32_e32 v8, 0xbfb8aa3b, v24
	v_mul_f32_e32 v9, 0xbfb8aa3b, v27
	v_exp_f32_e32 v8, v8
	v_exp_f32_e32 v9, v9
	v_div_fixup_f32 v6, v4, v6, v23
	v_pk_fma_f32 v[6:7], v[12:13], v[6:7], 0 op_sel_hi:[1,1,0]
	s_nop 0
	v_cvt_pk_bf16_f32 v4, v6, v7
	v_pk_add_f32 v[6:7], v[8:9], 1.0 op_sel_hi:[1,0]
	v_lshlrev_b32_e32 v8, 16, v5
	v_div_scale_f32 v12, s[0:1], v7, v7, v27
	v_rcp_f32_e32 v13, v12
	v_and_b32_e32 v9, 0xffff0000, v5
	v_pk_mul_f32 v[8:9], v[22:23], v[8:9] op_sel_hi:[0,1]
	v_fma_f32 v5, -v12, v13, 1.0
	v_fmac_f32_e32 v13, v5, v13
	v_div_scale_f32 v5, vcc, v27, v7, v27
	v_mul_f32_e32 v22, v5, v13
	v_fma_f32 v23, -v12, v22, v5
	v_fmac_f32_e32 v22, v23, v13
	v_fma_f32 v5, -v12, v22, v5
	v_div_scale_f32 v12, s[0:1], v6, v6, v24
	v_rcp_f32_e32 v23, v12
	v_div_fmas_f32 v5, v5, v13, v22
	v_div_fixup_f32 v7, v5, v7, v27
	v_fma_f32 v5, -v12, v23, 1.0
	v_fmac_f32_e32 v23, v5, v23
	v_div_scale_f32 v5, vcc, v24, v6, v24
	v_mul_f32_e32 v13, v5, v23
	v_fma_f32 v22, -v12, v13, v5
	v_fmac_f32_e32 v13, v22, v23
	v_fma_f32 v5, -v12, v13, v5
	v_div_fmas_f32 v5, v5, v23, v13
	v_div_fixup_f32 v6, v5, v6, v24
	v_pk_fma_f32 v[6:7], v[8:9], v[6:7], 0 op_sel_hi:[1,1,0]
	s_nop 0
	v_cvt_pk_bf16_f32 v5, v6, v7
	v_lshl_add_u64 v[6:7], v[10:11], 0, v[14:15]
	global_store_dwordx4 v[6:7], v[2:5], off
	ds_read_b128 v[6:9], v26 offset:2176
	s_nop 0
	v_add_u32_e32 v2, 8, v25
	v_ashrrev_i32_e32 v2, 3, v2
	v_ashrrev_i32_e32 v3, 31, v2
	v_lshl_add_u64 v[2:3], s[80:81], 0, v[2:3]
	v_mad_u64_u32 v[4:5], s[0:1], v2, s76, v[16:17]
	v_mad_i32_i24 v5, v3, s76, v5
	v_lshl_add_u64 v[4:5], v[4:5], 0, v[0:1]
	v_lshl_add_u64 v[4:5], v[4:5], 0, v[14:15]
	global_load_dwordx4 v[10:13], v[4:5], off
	v_mad_u64_u32 v[4:5], s[0:1], v2, s77, v[18:19]
	v_mad_i32_i24 v5, v3, s77, v5
	v_lshl_add_u64 v[4:5], v[4:5], 0, v[20:21]
	global_load_dword v24, v[4:5], off
	v_lshlrev_b64 v[2:3], 13, v[2:3]
	v_lshl_add_u64 v[2:3], s[44:45], 0, v[2:3]
	v_lshl_add_u64 v[22:23], v[2:3], 0, v[0:1]
	s_waitcnt vmcnt(1)
	v_lshlrev_b32_e32 v27, 16, v10
	v_and_b32_e32 v10, 0xffff0000, v10
	v_mul_f32_e32 v4, 0xbfb8aa3b, v27
	v_mul_f32_e32 v5, 0xbfb8aa3b, v10
	v_exp_f32_e32 v4, v4
	v_exp_f32_e32 v5, v5
	s_nop 0
	v_pk_add_f32 v[28:29], v[4:5], 1.0 op_sel_hi:[1,0]
	s_nop 0
	v_div_scale_f32 v32, s[0:1], v29, v29, v10
	v_rcp_f32_e32 v33, v32
	ds_read_b128 v[2:5], v26 offset:3264
	s_waitcnt lgkmcnt(1)
	v_lshlrev_b32_e32 v30, 16, v6
	v_and_b32_e32 v31, 0xffff0000, v6
	v_fma_f32 v6, -v32, v33, 1.0
	v_fmac_f32_e32 v33, v6, v33
	v_div_scale_f32 v6, vcc, v10, v29, v10
	v_mul_f32_e32 v34, v6, v33
	v_fma_f32 v35, -v32, v34, v6
	v_fmac_f32_e32 v34, v35, v33
	v_fma_f32 v6, -v32, v34, v6
	v_div_scale_f32 v32, s[0:1], v28, v28, v27
	v_rcp_f32_e32 v35, v32
	v_div_fmas_f32 v6, v6, v33, v34
	v_div_fixup_f32 v29, v6, v29, v10
	s_waitcnt vmcnt(0)
	v_pk_mul_f32 v[30:31], v[24:25], v[30:31] op_sel_hi:[0,1]
	v_fma_f32 v6, -v32, v35, 1.0
	v_fmac_f32_e32 v35, v6, v35
	v_div_scale_f32 v6, vcc, v27, v28, v27
	v_mul_f32_e32 v10, v6, v35
	v_fma_f32 v33, -v32, v10, v6
	v_fmac_f32_e32 v10, v33, v35
	v_fma_f32 v6, -v32, v10, v6
	v_lshlrev_b32_e32 v32, 16, v11
	v_and_b32_e32 v33, 0xffff0000, v11
	v_div_fmas_f32 v6, v6, v35, v10
	v_mul_f32_e32 v10, 0xbfb8aa3b, v32
	v_mul_f32_e32 v11, 0xbfb8aa3b, v33
	v_exp_f32_e32 v10, v10
	v_exp_f32_e32 v11, v11
	v_div_fixup_f32 v28, v6, v28, v27
	v_pk_fma_f32 v[28:29], v[30:31], v[28:29], 0 op_sel_hi:[1,1,0]
	v_pk_add_f32 v[10:11], v[10:11], 1.0 op_sel_hi:[1,0]
	s_nop 0
	v_div_scale_f32 v27, s[0:1], v11, v11, v33
	v_rcp_f32_e32 v30, v27
	v_cvt_pk_bf16_f32 v6, v28, v29
	v_lshlrev_b32_e32 v28, 16, v7
	v_and_b32_e32 v29, 0xffff0000, v7
	v_fma_f32 v7, -v27, v30, 1.0
	v_fmac_f32_e32 v30, v7, v30
	v_div_scale_f32 v7, vcc, v33, v11, v33
	v_mul_f32_e32 v31, v7, v30
	v_fma_f32 v34, -v27, v31, v7
	v_fmac_f32_e32 v31, v34, v30
	v_fma_f32 v7, -v27, v31, v7
	v_div_scale_f32 v27, s[0:1], v10, v10, v32
	v_rcp_f32_e32 v34, v27
	v_div_fmas_f32 v7, v7, v30, v31
	v_div_fixup_f32 v11, v7, v11, v33
	v_pk_mul_f32 v[28:29], v[24:25], v[28:29] op_sel_hi:[0,1]
	v_fma_f32 v7, -v27, v34, 1.0
	v_fmac_f32_e32 v34, v7, v34
	v_div_scale_f32 v7, vcc, v32, v10, v32
	v_mul_f32_e32 v30, v7, v34
	v_fma_f32 v31, -v27, v30, v7
	v_fmac_f32_e32 v30, v31, v34
	v_fma_f32 v7, -v27, v30, v7
	v_lshlrev_b32_e32 v27, 16, v12
	v_and_b32_e32 v12, 0xffff0000, v12
	v_div_fmas_f32 v7, v7, v34, v30
	v_mul_f32_e32 v30, 0xbfb8aa3b, v27
	v_mul_f32_e32 v31, 0xbfb8aa3b, v12
	v_exp_f32_e32 v30, v30
	v_exp_f32_e32 v31, v31
	v_div_fixup_f32 v10, v7, v10, v32
	v_pk_fma_f32 v[10:11], v[28:29], v[10:11], 0 op_sel_hi:[1,1,0]
	v_lshlrev_b32_e32 v28, 16, v8
	v_cvt_pk_bf16_f32 v7, v10, v11
	v_pk_add_f32 v[10:11], v[30:31], 1.0 op_sel_hi:[1,0]
	v_and_b32_e32 v29, 0xffff0000, v8
	v_div_scale_f32 v30, s[0:1], v11, v11, v12
	v_rcp_f32_e32 v31, v30
	v_pk_mul_f32 v[28:29], v[24:25], v[28:29] op_sel_hi:[0,1]
	v_fma_f32 v8, -v30, v31, 1.0
	v_fmac_f32_e32 v31, v8, v31
	v_div_scale_f32 v8, vcc, v12, v11, v12
	v_mul_f32_e32 v32, v8, v31
	v_fma_f32 v33, -v30, v32, v8
	v_fmac_f32_e32 v32, v33, v31
	v_fma_f32 v8, -v30, v32, v8
	v_div_scale_f32 v30, s[0:1], v10, v10, v27
	v_rcp_f32_e32 v33, v30
	v_div_fmas_f32 v8, v8, v31, v32
	v_div_fixup_f32 v11, v8, v11, v12
	v_fma_f32 v8, -v30, v33, 1.0
	v_fmac_f32_e32 v33, v8, v33
	v_div_scale_f32 v8, vcc, v27, v10, v27
	v_mul_f32_e32 v12, v8, v33
	v_fma_f32 v31, -v30, v12, v8
	v_fmac_f32_e32 v12, v31, v33
	v_fma_f32 v8, -v30, v12, v8
	v_lshlrev_b32_e32 v30, 16, v13
	v_and_b32_e32 v31, 0xffff0000, v13
	v_div_fmas_f32 v8, v8, v33, v12
	v_mul_f32_e32 v12, 0xbfb8aa3b, v30
	v_mul_f32_e32 v13, 0xbfb8aa3b, v31
	v_exp_f32_e32 v12, v12
	v_exp_f32_e32 v13, v13
	v_div_fixup_f32 v10, v8, v10, v27
	v_pk_fma_f32 v[10:11], v[28:29], v[10:11], 0 op_sel_hi:[1,1,0]
	s_nop 0
	v_cvt_pk_bf16_f32 v8, v10, v11
	v_pk_add_f32 v[10:11], v[12:13], 1.0 op_sel_hi:[1,0]
	v_lshlrev_b32_e32 v12, 16, v9
	v_div_scale_f32 v27, s[0:1], v11, v11, v31
	v_rcp_f32_e32 v28, v27
	v_and_b32_e32 v13, 0xffff0000, v9
	v_pk_mul_f32 v[12:13], v[24:25], v[12:13] op_sel_hi:[0,1]
	v_fma_f32 v9, -v27, v28, 1.0
	v_fmac_f32_e32 v28, v9, v28
	v_div_scale_f32 v9, vcc, v31, v11, v31
	v_mul_f32_e32 v24, v9, v28
	v_fma_f32 v29, -v27, v24, v9
	v_fmac_f32_e32 v24, v29, v28
	v_fma_f32 v9, -v27, v24, v9
	v_div_scale_f32 v27, s[0:1], v10, v10, v30
	v_rcp_f32_e32 v29, v27
	v_div_fmas_f32 v9, v9, v28, v24
	v_div_fixup_f32 v11, v9, v11, v31
	v_fma_f32 v9, -v27, v29, 1.0
	v_fmac_f32_e32 v29, v9, v29
	v_div_scale_f32 v9, vcc, v30, v10, v30
	v_mul_f32_e32 v24, v9, v29
	v_fma_f32 v28, -v27, v24, v9
	v_fmac_f32_e32 v24, v28, v29
	v_fma_f32 v9, -v27, v24, v9
	v_div_fmas_f32 v9, v9, v29, v24
	v_div_fixup_f32 v10, v9, v10, v30
	v_pk_fma_f32 v[10:11], v[12:13], v[10:11], 0 op_sel_hi:[1,1,0]
	v_mov_b32_e32 v13, v1
	v_cvt_pk_bf16_f32 v9, v10, v11
	v_lshl_add_u64 v[10:11], v[22:23], 0, v[14:15]
	global_store_dwordx4 v[10:11], v[6:9], off
	v_mov_b32_e32 v29, v1
	s_nop 0
	v_add_u32_e32 v8, 12, v25
	v_ashrrev_i32_e32 v6, 3, v8
	v_ashrrev_i32_e32 v7, 31, v6
	v_lshl_add_u64 v[10:11], s[80:81], 0, v[6:7]
	v_and_or_b32 v24, v8, 7, s34
	v_mad_u64_u32 v[6:7], s[0:1], v10, s76, v[16:17]
	v_mad_i32_i24 v7, v11, s76, v7
	v_lshlrev_b32_e32 v12, 8, v24
	v_lshl_add_u64 v[6:7], v[6:7], 0, v[12:13]
	v_lshl_add_u64 v[6:7], v[6:7], 0, v[14:15]
	global_load_dwordx4 v[6:9], v[6:7], off
	v_mad_u64_u32 v[22:23], s[0:1], v10, s77, v[18:19]
	v_mad_i32_i24 v23, v11, s77, v23
	v_lshlrev_b32_e32 v28, 2, v24
	v_lshl_add_u64 v[22:23], v[22:23], 0, v[28:29]
	global_load_dword v22, v[22:23], off
	v_lshlrev_b64 v[10:11], 13, v[10:11]
	v_lshl_add_u64 v[10:11], s[44:45], 0, v[10:11]
	v_lshl_add_u64 v[10:11], v[10:11], 0, v[12:13]
	s_waitcnt vmcnt(1)
	v_lshlrev_b32_e32 v23, 16, v6
	v_and_b32_e32 v6, 0xffff0000, v6
	v_mul_f32_e32 v24, 0xbfb8aa3b, v23
	v_exp_f32_e32 v28, v24
	v_mul_f32_e32 v24, 0xbfb8aa3b, v6
	v_exp_f32_e32 v29, v24
	s_nop 0
	v_pk_add_f32 v[12:13], v[28:29], 1.0 op_sel_hi:[1,0]
	s_nop 0
	v_div_scale_f32 v24, s[0:1], v13, v13, v6
	v_rcp_f32_e32 v27, v24
	s_waitcnt lgkmcnt(0)
	v_lshlrev_b32_e32 v28, 16, v2
	v_and_b32_e32 v29, 0xffff0000, v2
	s_waitcnt vmcnt(0)
	v_pk_mul_f32 v[28:29], v[22:23], v[28:29] op_sel_hi:[0,1]
	v_fma_f32 v2, -v24, v27, 1.0
	v_fmac_f32_e32 v27, v2, v27
	v_div_scale_f32 v2, vcc, v6, v13, v6
	v_mul_f32_e32 v30, v2, v27
	v_fma_f32 v31, -v24, v30, v2
	v_fmac_f32_e32 v30, v31, v27
	v_fma_f32 v2, -v24, v30, v2
	v_div_scale_f32 v24, s[0:1], v12, v12, v23
	v_rcp_f32_e32 v31, v24
	v_div_fmas_f32 v2, v2, v27, v30
	v_div_fixup_f32 v13, v2, v13, v6
	v_fma_f32 v2, -v24, v31, 1.0
	v_fmac_f32_e32 v31, v2, v31
	v_div_scale_f32 v2, vcc, v23, v12, v23
	v_mul_f32_e32 v6, v2, v31
	v_fma_f32 v27, -v24, v6, v2
	v_fmac_f32_e32 v6, v27, v31
	v_fma_f32 v2, -v24, v6, v2
	v_lshlrev_b32_e32 v24, 16, v7
	v_and_b32_e32 v27, 0xffff0000, v7
	v_div_fmas_f32 v2, v2, v31, v6
	v_mul_f32_e32 v6, 0xbfb8aa3b, v24
	v_mul_f32_e32 v7, 0xbfb8aa3b, v27
	v_exp_f32_e32 v6, v6
	v_exp_f32_e32 v7, v7
	v_div_fixup_f32 v12, v2, v12, v23
	v_pk_fma_f32 v[12:13], v[28:29], v[12:13], 0 op_sel_hi:[1,1,0]
	v_pk_add_f32 v[6:7], v[6:7], 1.0 op_sel_hi:[1,0]
	s_nop 0
	v_div_scale_f32 v23, s[0:1], v7, v7, v27
	v_rcp_f32_e32 v28, v23
	v_cvt_pk_bf16_f32 v2, v12, v13
	v_lshlrev_b32_e32 v12, 16, v3
	v_and_b32_e32 v13, 0xffff0000, v3
	v_fma_f32 v3, -v23, v28, 1.0
	v_fmac_f32_e32 v28, v3, v28
	v_div_scale_f32 v3, vcc, v27, v7, v27
	v_mul_f32_e32 v29, v3, v28
	v_fma_f32 v30, -v23, v29, v3
	v_fmac_f32_e32 v29, v30, v28
	v_pk_mul_f32 v[12:13], v[22:23], v[12:13] op_sel_hi:[0,1]
	v_fma_f32 v3, -v23, v29, v3
	v_div_scale_f32 v23, s[0:1], v6, v6, v24
	v_rcp_f32_e32 v30, v23
	v_div_fmas_f32 v3, v3, v28, v29
	v_div_fixup_f32 v7, v3, v7, v27
	v_fma_f32 v3, -v23, v30, 1.0
	v_fmac_f32_e32 v30, v3, v30
	v_div_scale_f32 v3, vcc, v24, v6, v24
	v_mul_f32_e32 v27, v3, v30
	v_fma_f32 v28, -v23, v27, v3
	v_fmac_f32_e32 v27, v28, v30
	v_fma_f32 v3, -v23, v27, v3
	v_lshlrev_b32_e32 v23, 16, v8
	v_div_fmas_f32 v3, v3, v30, v27
	v_and_b32_e32 v8, 0xffff0000, v8
	v_mul_f32_e32 v27, 0xbfb8aa3b, v23
	v_exp_f32_e32 v28, v27
	v_mul_f32_e32 v27, 0xbfb8aa3b, v8
	v_exp_f32_e32 v29, v27
	v_div_fixup_f32 v6, v3, v6, v24
	v_pk_fma_f32 v[6:7], v[12:13], v[6:7], 0 op_sel_hi:[1,1,0]
	v_lshlrev_b32_e32 v12, 16, v4
	v_cvt_pk_bf16_f32 v3, v6, v7
	v_pk_add_f32 v[6:7], v[28:29], 1.0 op_sel_hi:[1,0]
	v_and_b32_e32 v13, 0xffff0000, v4
	v_div_scale_f32 v24, s[0:1], v7, v7, v8
	v_rcp_f32_e32 v27, v24
	v_pk_mul_f32 v[12:13], v[22:23], v[12:13] op_sel_hi:[0,1]
	v_fma_f32 v4, -v24, v27, 1.0
	v_fmac_f32_e32 v27, v4, v27
	v_div_scale_f32 v4, vcc, v8, v7, v8
	v_mul_f32_e32 v28, v4, v27
	v_fma_f32 v29, -v24, v28, v4
	v_fmac_f32_e32 v28, v29, v27
	v_fma_f32 v4, -v24, v28, v4
	v_div_scale_f32 v24, s[0:1], v6, v6, v23
	v_rcp_f32_e32 v29, v24
	v_div_fmas_f32 v4, v4, v27, v28
	v_div_fixup_f32 v7, v4, v7, v8
	v_fma_f32 v4, -v24, v29, 1.0
	v_fmac_f32_e32 v29, v4, v29
	v_div_scale_f32 v4, vcc, v23, v6, v23
	v_mul_f32_e32 v8, v4, v29
	v_fma_f32 v27, -v24, v8, v4
	v_fmac_f32_e32 v8, v27, v29
	v_fma_f32 v4, -v24, v8, v4
	v_lshlrev_b32_e32 v24, 16, v9
	v_and_b32_e32 v27, 0xffff0000, v9
	v_div_fmas_f32 v4, v4, v29, v8
	v_mul_f32_e32 v8, 0xbfb8aa3b, v24
	v_mul_f32_e32 v9, 0xbfb8aa3b, v27
	v_exp_f32_e32 v8, v8
	v_exp_f32_e32 v9, v9
	v_div_fixup_f32 v6, v4, v6, v23
	v_pk_fma_f32 v[6:7], v[12:13], v[6:7], 0 op_sel_hi:[1,1,0]
	s_nop 0
	v_cvt_pk_bf16_f32 v4, v6, v7
	v_pk_add_f32 v[6:7], v[8:9], 1.0 op_sel_hi:[1,0]
	v_lshlrev_b32_e32 v8, 16, v5
	v_div_scale_f32 v12, s[0:1], v7, v7, v27
	v_rcp_f32_e32 v13, v12
	v_and_b32_e32 v9, 0xffff0000, v5
	v_pk_mul_f32 v[8:9], v[22:23], v[8:9] op_sel_hi:[0,1]
	v_fma_f32 v5, -v12, v13, 1.0
	v_fmac_f32_e32 v13, v5, v13
	v_div_scale_f32 v5, vcc, v27, v7, v27
	v_mul_f32_e32 v22, v5, v13
	v_fma_f32 v23, -v12, v22, v5
	v_fmac_f32_e32 v22, v23, v13
	v_fma_f32 v5, -v12, v22, v5
	v_div_scale_f32 v12, s[0:1], v6, v6, v24
	v_rcp_f32_e32 v23, v12
	v_div_fmas_f32 v5, v5, v13, v22
	v_div_fixup_f32 v7, v5, v7, v27
	v_fma_f32 v5, -v12, v23, 1.0
	v_fmac_f32_e32 v23, v5, v23
	v_div_scale_f32 v5, vcc, v24, v6, v24
	v_mul_f32_e32 v13, v5, v23
	v_fma_f32 v22, -v12, v13, v5
	v_fmac_f32_e32 v13, v22, v23
	v_fma_f32 v5, -v12, v13, v5
	v_div_fmas_f32 v5, v5, v23, v13
	v_div_fixup_f32 v6, v5, v6, v24
	v_pk_fma_f32 v[6:7], v[8:9], v[6:7], 0 op_sel_hi:[1,1,0]
	s_nop 0
	v_cvt_pk_bf16_f32 v5, v6, v7
	v_lshl_add_u64 v[6:7], v[10:11], 0, v[14:15]
	global_store_dwordx4 v[6:7], v[2:5], off
	ds_read_b128 v[6:9], v26 offset:4352
	s_nop 0
	v_add_u32_e32 v2, 16, v25
	v_ashrrev_i32_e32 v2, 3, v2
	v_ashrrev_i32_e32 v3, 31, v2
	v_lshl_add_u64 v[2:3], s[80:81], 0, v[2:3]
	v_mad_u64_u32 v[4:5], s[0:1], v2, s76, v[16:17]
	v_mad_i32_i24 v5, v3, s76, v5
	v_lshl_add_u64 v[4:5], v[4:5], 0, v[0:1]
	v_lshl_add_u64 v[4:5], v[4:5], 0, v[14:15]
	global_load_dwordx4 v[10:13], v[4:5], off
	v_mad_u64_u32 v[4:5], s[0:1], v2, s77, v[18:19]
	v_mad_i32_i24 v5, v3, s77, v5
	v_lshl_add_u64 v[4:5], v[4:5], 0, v[20:21]
	global_load_dword v24, v[4:5], off
	v_lshlrev_b64 v[2:3], 13, v[2:3]
	v_lshl_add_u64 v[2:3], s[44:45], 0, v[2:3]
	v_lshl_add_u64 v[22:23], v[2:3], 0, v[0:1]
	s_waitcnt vmcnt(1)
	v_lshlrev_b32_e32 v27, 16, v10
	v_and_b32_e32 v10, 0xffff0000, v10
	v_mul_f32_e32 v4, 0xbfb8aa3b, v27
	v_mul_f32_e32 v5, 0xbfb8aa3b, v10
	v_exp_f32_e32 v4, v4
	v_exp_f32_e32 v5, v5
	s_nop 0
	v_pk_add_f32 v[28:29], v[4:5], 1.0 op_sel_hi:[1,0]
	s_nop 0
	v_div_scale_f32 v32, s[0:1], v29, v29, v10
	v_rcp_f32_e32 v33, v32
	ds_read_b128 v[2:5], v26 offset:5440
	s_waitcnt lgkmcnt(1)
	v_lshlrev_b32_e32 v30, 16, v6
	v_and_b32_e32 v31, 0xffff0000, v6
	v_fma_f32 v6, -v32, v33, 1.0
	v_fmac_f32_e32 v33, v6, v33
	v_div_scale_f32 v6, vcc, v10, v29, v10
	v_mul_f32_e32 v34, v6, v33
	v_fma_f32 v35, -v32, v34, v6
	v_fmac_f32_e32 v34, v35, v33
	v_fma_f32 v6, -v32, v34, v6
	v_div_scale_f32 v32, s[0:1], v28, v28, v27
	v_rcp_f32_e32 v35, v32
	v_div_fmas_f32 v6, v6, v33, v34
	v_div_fixup_f32 v29, v6, v29, v10
	s_waitcnt vmcnt(0)
	v_pk_mul_f32 v[30:31], v[24:25], v[30:31] op_sel_hi:[0,1]
	v_fma_f32 v6, -v32, v35, 1.0
	v_fmac_f32_e32 v35, v6, v35
	v_div_scale_f32 v6, vcc, v27, v28, v27
	v_mul_f32_e32 v10, v6, v35
	v_fma_f32 v33, -v32, v10, v6
	v_fmac_f32_e32 v10, v33, v35
	v_fma_f32 v6, -v32, v10, v6
	v_lshlrev_b32_e32 v32, 16, v11
	v_and_b32_e32 v33, 0xffff0000, v11
	v_div_fmas_f32 v6, v6, v35, v10
	v_mul_f32_e32 v10, 0xbfb8aa3b, v32
	v_mul_f32_e32 v11, 0xbfb8aa3b, v33
	v_exp_f32_e32 v10, v10
	v_exp_f32_e32 v11, v11
	v_div_fixup_f32 v28, v6, v28, v27
	v_pk_fma_f32 v[28:29], v[30:31], v[28:29], 0 op_sel_hi:[1,1,0]
	v_pk_add_f32 v[10:11], v[10:11], 1.0 op_sel_hi:[1,0]
	s_nop 0
	v_div_scale_f32 v27, s[0:1], v11, v11, v33
	v_rcp_f32_e32 v30, v27
	v_cvt_pk_bf16_f32 v6, v28, v29
	v_lshlrev_b32_e32 v28, 16, v7
	v_and_b32_e32 v29, 0xffff0000, v7
	v_fma_f32 v7, -v27, v30, 1.0
	v_fmac_f32_e32 v30, v7, v30
	v_div_scale_f32 v7, vcc, v33, v11, v33
	v_mul_f32_e32 v31, v7, v30
	v_fma_f32 v34, -v27, v31, v7
	v_fmac_f32_e32 v31, v34, v30
	v_fma_f32 v7, -v27, v31, v7
	v_div_scale_f32 v27, s[0:1], v10, v10, v32
	v_rcp_f32_e32 v34, v27
	v_div_fmas_f32 v7, v7, v30, v31
	v_div_fixup_f32 v11, v7, v11, v33
	v_pk_mul_f32 v[28:29], v[24:25], v[28:29] op_sel_hi:[0,1]
	v_fma_f32 v7, -v27, v34, 1.0
	v_fmac_f32_e32 v34, v7, v34
	v_div_scale_f32 v7, vcc, v32, v10, v32
	v_mul_f32_e32 v30, v7, v34
	v_fma_f32 v31, -v27, v30, v7
	v_fmac_f32_e32 v30, v31, v34
	v_fma_f32 v7, -v27, v30, v7
	v_lshlrev_b32_e32 v27, 16, v12
	v_and_b32_e32 v12, 0xffff0000, v12
	v_div_fmas_f32 v7, v7, v34, v30
	v_mul_f32_e32 v30, 0xbfb8aa3b, v27
	v_mul_f32_e32 v31, 0xbfb8aa3b, v12
	v_exp_f32_e32 v30, v30
	v_exp_f32_e32 v31, v31
	v_div_fixup_f32 v10, v7, v10, v32
	v_pk_fma_f32 v[10:11], v[28:29], v[10:11], 0 op_sel_hi:[1,1,0]
	v_lshlrev_b32_e32 v28, 16, v8
	v_cvt_pk_bf16_f32 v7, v10, v11
	v_pk_add_f32 v[10:11], v[30:31], 1.0 op_sel_hi:[1,0]
	v_and_b32_e32 v29, 0xffff0000, v8
	v_div_scale_f32 v30, s[0:1], v11, v11, v12
	v_rcp_f32_e32 v31, v30
	v_pk_mul_f32 v[28:29], v[24:25], v[28:29] op_sel_hi:[0,1]
	v_fma_f32 v8, -v30, v31, 1.0
	v_fmac_f32_e32 v31, v8, v31
	v_div_scale_f32 v8, vcc, v12, v11, v12
	v_mul_f32_e32 v32, v8, v31
	v_fma_f32 v33, -v30, v32, v8
	v_fmac_f32_e32 v32, v33, v31
	v_fma_f32 v8, -v30, v32, v8
	v_div_scale_f32 v30, s[0:1], v10, v10, v27
	v_rcp_f32_e32 v33, v30
	v_div_fmas_f32 v8, v8, v31, v32
	v_div_fixup_f32 v11, v8, v11, v12
	v_fma_f32 v8, -v30, v33, 1.0
	v_fmac_f32_e32 v33, v8, v33
	v_div_scale_f32 v8, vcc, v27, v10, v27
	v_mul_f32_e32 v12, v8, v33
	v_fma_f32 v31, -v30, v12, v8
	v_fmac_f32_e32 v12, v31, v33
	v_fma_f32 v8, -v30, v12, v8
	v_lshlrev_b32_e32 v30, 16, v13
	v_and_b32_e32 v31, 0xffff0000, v13
	v_div_fmas_f32 v8, v8, v33, v12
	v_mul_f32_e32 v12, 0xbfb8aa3b, v30
	v_mul_f32_e32 v13, 0xbfb8aa3b, v31
	v_exp_f32_e32 v12, v12
	v_exp_f32_e32 v13, v13
	v_div_fixup_f32 v10, v8, v10, v27
	v_pk_fma_f32 v[10:11], v[28:29], v[10:11], 0 op_sel_hi:[1,1,0]
	s_nop 0
	v_cvt_pk_bf16_f32 v8, v10, v11
	v_pk_add_f32 v[10:11], v[12:13], 1.0 op_sel_hi:[1,0]
	v_lshlrev_b32_e32 v12, 16, v9
	v_div_scale_f32 v27, s[0:1], v11, v11, v31
	v_rcp_f32_e32 v28, v27
	v_and_b32_e32 v13, 0xffff0000, v9
	v_pk_mul_f32 v[12:13], v[24:25], v[12:13] op_sel_hi:[0,1]
	v_fma_f32 v9, -v27, v28, 1.0
	v_fmac_f32_e32 v28, v9, v28
	v_div_scale_f32 v9, vcc, v31, v11, v31
	v_mul_f32_e32 v24, v9, v28
	v_fma_f32 v29, -v27, v24, v9
	v_fmac_f32_e32 v24, v29, v28
	v_fma_f32 v9, -v27, v24, v9
	v_div_scale_f32 v27, s[0:1], v10, v10, v30
	v_rcp_f32_e32 v29, v27
	v_div_fmas_f32 v9, v9, v28, v24
	v_div_fixup_f32 v11, v9, v11, v31
	v_fma_f32 v9, -v27, v29, 1.0
	v_fmac_f32_e32 v29, v9, v29
	v_div_scale_f32 v9, vcc, v30, v10, v30
	v_mul_f32_e32 v24, v9, v29
	v_fma_f32 v28, -v27, v24, v9
	v_fmac_f32_e32 v24, v28, v29
	v_fma_f32 v9, -v27, v24, v9
	v_div_fmas_f32 v9, v9, v29, v24
	v_div_fixup_f32 v10, v9, v10, v30
	v_pk_fma_f32 v[10:11], v[12:13], v[10:11], 0 op_sel_hi:[1,1,0]
	v_mov_b32_e32 v13, v1
	v_cvt_pk_bf16_f32 v9, v10, v11
	v_lshl_add_u64 v[10:11], v[22:23], 0, v[14:15]
	global_store_dwordx4 v[10:11], v[6:9], off
	v_mov_b32_e32 v29, v1
	s_nop 0
	v_add_u32_e32 v8, 20, v25
	v_ashrrev_i32_e32 v6, 3, v8
	v_ashrrev_i32_e32 v7, 31, v6
	v_lshl_add_u64 v[10:11], s[80:81], 0, v[6:7]
	v_and_or_b32 v24, v8, 7, s34
	v_mad_u64_u32 v[6:7], s[0:1], v10, s76, v[16:17]
	v_mad_i32_i24 v7, v11, s76, v7
	v_lshlrev_b32_e32 v12, 8, v24
	v_lshl_add_u64 v[6:7], v[6:7], 0, v[12:13]
	v_lshl_add_u64 v[6:7], v[6:7], 0, v[14:15]
	global_load_dwordx4 v[6:9], v[6:7], off
	v_mad_u64_u32 v[22:23], s[0:1], v10, s77, v[18:19]
	v_mad_i32_i24 v23, v11, s77, v23
	v_lshlrev_b32_e32 v28, 2, v24
	v_lshl_add_u64 v[22:23], v[22:23], 0, v[28:29]
	global_load_dword v22, v[22:23], off
	v_lshlrev_b64 v[10:11], 13, v[10:11]
	v_lshl_add_u64 v[10:11], s[44:45], 0, v[10:11]
	v_lshl_add_u64 v[10:11], v[10:11], 0, v[12:13]
	s_waitcnt vmcnt(1)
	v_lshlrev_b32_e32 v23, 16, v6
	v_and_b32_e32 v6, 0xffff0000, v6
	v_mul_f32_e32 v24, 0xbfb8aa3b, v23
	v_exp_f32_e32 v28, v24
	v_mul_f32_e32 v24, 0xbfb8aa3b, v6
	v_exp_f32_e32 v29, v24
	s_nop 0
	v_pk_add_f32 v[12:13], v[28:29], 1.0 op_sel_hi:[1,0]
	s_nop 0
	v_div_scale_f32 v24, s[0:1], v13, v13, v6
	v_rcp_f32_e32 v27, v24
	s_waitcnt lgkmcnt(0)
	v_lshlrev_b32_e32 v28, 16, v2
	v_and_b32_e32 v29, 0xffff0000, v2
	s_waitcnt vmcnt(0)
	v_pk_mul_f32 v[28:29], v[22:23], v[28:29] op_sel_hi:[0,1]
	v_fma_f32 v2, -v24, v27, 1.0
	v_fmac_f32_e32 v27, v2, v27
	v_div_scale_f32 v2, vcc, v6, v13, v6
	v_mul_f32_e32 v30, v2, v27
	v_fma_f32 v31, -v24, v30, v2
	v_fmac_f32_e32 v30, v31, v27
	v_fma_f32 v2, -v24, v30, v2
	v_div_scale_f32 v24, s[0:1], v12, v12, v23
	v_rcp_f32_e32 v31, v24
	v_div_fmas_f32 v2, v2, v27, v30
	v_div_fixup_f32 v13, v2, v13, v6
	v_fma_f32 v2, -v24, v31, 1.0
	v_fmac_f32_e32 v31, v2, v31
	v_div_scale_f32 v2, vcc, v23, v12, v23
	v_mul_f32_e32 v6, v2, v31
	v_fma_f32 v27, -v24, v6, v2
	v_fmac_f32_e32 v6, v27, v31
	v_fma_f32 v2, -v24, v6, v2
	v_lshlrev_b32_e32 v24, 16, v7
	v_and_b32_e32 v27, 0xffff0000, v7
	v_div_fmas_f32 v2, v2, v31, v6
	v_mul_f32_e32 v6, 0xbfb8aa3b, v24
	v_mul_f32_e32 v7, 0xbfb8aa3b, v27
	v_exp_f32_e32 v6, v6
	v_exp_f32_e32 v7, v7
	v_div_fixup_f32 v12, v2, v12, v23
	v_pk_fma_f32 v[12:13], v[28:29], v[12:13], 0 op_sel_hi:[1,1,0]
	v_pk_add_f32 v[6:7], v[6:7], 1.0 op_sel_hi:[1,0]
	s_nop 0
	v_div_scale_f32 v23, s[0:1], v7, v7, v27
	v_rcp_f32_e32 v28, v23
	v_cvt_pk_bf16_f32 v2, v12, v13
	v_lshlrev_b32_e32 v12, 16, v3
	v_and_b32_e32 v13, 0xffff0000, v3
	v_fma_f32 v3, -v23, v28, 1.0
	v_fmac_f32_e32 v28, v3, v28
	v_div_scale_f32 v3, vcc, v27, v7, v27
	v_mul_f32_e32 v29, v3, v28
	v_fma_f32 v30, -v23, v29, v3
	v_fmac_f32_e32 v29, v30, v28
	v_pk_mul_f32 v[12:13], v[22:23], v[12:13] op_sel_hi:[0,1]
	v_fma_f32 v3, -v23, v29, v3
	v_div_scale_f32 v23, s[0:1], v6, v6, v24
	v_rcp_f32_e32 v30, v23
	v_div_fmas_f32 v3, v3, v28, v29
	v_div_fixup_f32 v7, v3, v7, v27
	v_fma_f32 v3, -v23, v30, 1.0
	v_fmac_f32_e32 v30, v3, v30
	v_div_scale_f32 v3, vcc, v24, v6, v24
	v_mul_f32_e32 v27, v3, v30
	v_fma_f32 v28, -v23, v27, v3
	v_fmac_f32_e32 v27, v28, v30
	v_fma_f32 v3, -v23, v27, v3
	v_lshlrev_b32_e32 v23, 16, v8
	v_div_fmas_f32 v3, v3, v30, v27
	v_and_b32_e32 v8, 0xffff0000, v8
	v_mul_f32_e32 v27, 0xbfb8aa3b, v23
	v_exp_f32_e32 v28, v27
	v_mul_f32_e32 v27, 0xbfb8aa3b, v8
	v_exp_f32_e32 v29, v27
	v_div_fixup_f32 v6, v3, v6, v24
	v_pk_fma_f32 v[6:7], v[12:13], v[6:7], 0 op_sel_hi:[1,1,0]
	v_lshlrev_b32_e32 v12, 16, v4
	v_cvt_pk_bf16_f32 v3, v6, v7
	v_pk_add_f32 v[6:7], v[28:29], 1.0 op_sel_hi:[1,0]
	v_and_b32_e32 v13, 0xffff0000, v4
	v_div_scale_f32 v24, s[0:1], v7, v7, v8
	v_rcp_f32_e32 v27, v24
	v_pk_mul_f32 v[12:13], v[22:23], v[12:13] op_sel_hi:[0,1]
	v_fma_f32 v4, -v24, v27, 1.0
	v_fmac_f32_e32 v27, v4, v27
	v_div_scale_f32 v4, vcc, v8, v7, v8
	v_mul_f32_e32 v28, v4, v27
	v_fma_f32 v29, -v24, v28, v4
	v_fmac_f32_e32 v28, v29, v27
	v_fma_f32 v4, -v24, v28, v4
	v_div_scale_f32 v24, s[0:1], v6, v6, v23
	v_rcp_f32_e32 v29, v24
	v_div_fmas_f32 v4, v4, v27, v28
	v_div_fixup_f32 v7, v4, v7, v8
	v_fma_f32 v4, -v24, v29, 1.0
	v_fmac_f32_e32 v29, v4, v29
	v_div_scale_f32 v4, vcc, v23, v6, v23
	v_mul_f32_e32 v8, v4, v29
	v_fma_f32 v27, -v24, v8, v4
	v_fmac_f32_e32 v8, v27, v29
	v_fma_f32 v4, -v24, v8, v4
	v_lshlrev_b32_e32 v24, 16, v9
	v_and_b32_e32 v27, 0xffff0000, v9
	v_div_fmas_f32 v4, v4, v29, v8
	v_mul_f32_e32 v8, 0xbfb8aa3b, v24
	v_mul_f32_e32 v9, 0xbfb8aa3b, v27
	v_exp_f32_e32 v8, v8
	v_exp_f32_e32 v9, v9
	v_div_fixup_f32 v6, v4, v6, v23
	v_pk_fma_f32 v[6:7], v[12:13], v[6:7], 0 op_sel_hi:[1,1,0]
	s_nop 0
	v_cvt_pk_bf16_f32 v4, v6, v7
	v_pk_add_f32 v[6:7], v[8:9], 1.0 op_sel_hi:[1,0]
	v_lshlrev_b32_e32 v8, 16, v5
	v_div_scale_f32 v12, s[0:1], v7, v7, v27
	v_rcp_f32_e32 v13, v12
	v_and_b32_e32 v9, 0xffff0000, v5
	v_pk_mul_f32 v[8:9], v[22:23], v[8:9] op_sel_hi:[0,1]
	v_fma_f32 v5, -v12, v13, 1.0
	v_fmac_f32_e32 v13, v5, v13
	v_div_scale_f32 v5, vcc, v27, v7, v27
	v_mul_f32_e32 v22, v5, v13
	v_fma_f32 v23, -v12, v22, v5
	v_fmac_f32_e32 v22, v23, v13
	v_fma_f32 v5, -v12, v22, v5
	v_div_scale_f32 v12, s[0:1], v6, v6, v24
	v_rcp_f32_e32 v23, v12
	v_div_fmas_f32 v5, v5, v13, v22
	v_div_fixup_f32 v7, v5, v7, v27
	v_fma_f32 v5, -v12, v23, 1.0
	v_fmac_f32_e32 v23, v5, v23
	v_div_scale_f32 v5, vcc, v24, v6, v24
	v_mul_f32_e32 v13, v5, v23
	v_fma_f32 v22, -v12, v13, v5
	v_fmac_f32_e32 v13, v22, v23
	v_fma_f32 v5, -v12, v13, v5
	v_div_fmas_f32 v5, v5, v23, v13
	v_div_fixup_f32 v6, v5, v6, v24
	v_pk_fma_f32 v[6:7], v[8:9], v[6:7], 0 op_sel_hi:[1,1,0]
	s_nop 0
	v_cvt_pk_bf16_f32 v5, v6, v7
	v_lshl_add_u64 v[6:7], v[10:11], 0, v[14:15]
	global_store_dwordx4 v[6:7], v[2:5], off
	ds_read_b128 v[6:9], v26 offset:6528
	s_nop 0
	v_add_u32_e32 v2, 24, v25
	v_ashrrev_i32_e32 v2, 3, v2
	v_ashrrev_i32_e32 v3, 31, v2
	v_lshl_add_u64 v[2:3], s[80:81], 0, v[2:3]
	v_mad_u64_u32 v[4:5], s[0:1], v2, s76, v[16:17]
	v_mad_i32_i24 v5, v3, s76, v5
	v_lshl_add_u64 v[4:5], v[4:5], 0, v[0:1]
	v_lshl_add_u64 v[4:5], v[4:5], 0, v[14:15]
	global_load_dwordx4 v[10:13], v[4:5], off
	v_mad_u64_u32 v[4:5], s[0:1], v2, s77, v[18:19]
	v_mad_i32_i24 v5, v3, s77, v5
	v_lshl_add_u64 v[4:5], v[4:5], 0, v[20:21]
	global_load_dword v22, v[4:5], off
	v_lshlrev_b64 v[2:3], 13, v[2:3]
	v_lshl_add_u64 v[2:3], s[44:45], 0, v[2:3]
	v_lshl_add_u64 v[20:21], v[2:3], 0, v[0:1]
	s_waitcnt vmcnt(1)
	v_lshlrev_b32_e32 v23, 16, v10
	v_and_b32_e32 v10, 0xffff0000, v10
	v_mul_f32_e32 v4, 0xbfb8aa3b, v23
	v_mul_f32_e32 v5, 0xbfb8aa3b, v10
	v_exp_f32_e32 v4, v4
	v_exp_f32_e32 v5, v5
	s_nop 0
	v_pk_add_f32 v[28:29], v[4:5], 1.0 op_sel_hi:[1,0]
	s_nop 0
	v_div_scale_f32 v0, s[0:1], v29, v29, v10
	v_rcp_f32_e32 v24, v0
	ds_read_b128 v[2:5], v26 offset:7616
	s_waitcnt lgkmcnt(1)
	v_lshlrev_b32_e32 v26, 16, v6
	v_and_b32_e32 v27, 0xffff0000, v6
	v_fma_f32 v6, -v0, v24, 1.0
	v_fmac_f32_e32 v24, v6, v24
	v_div_scale_f32 v6, vcc, v10, v29, v10
	v_mul_f32_e32 v30, v6, v24
	v_fma_f32 v31, -v0, v30, v6
	v_fmac_f32_e32 v30, v31, v24
	v_fma_f32 v0, -v0, v30, v6
	v_div_scale_f32 v6, s[0:1], v28, v28, v23
	v_rcp_f32_e32 v31, v6
	v_div_fmas_f32 v0, v0, v24, v30
	v_div_fixup_f32 v29, v0, v29, v10
	v_and_b32_e32 v30, 0xffff0000, v11
	v_fma_f32 v0, -v6, v31, 1.0
	v_fmac_f32_e32 v31, v0, v31
	v_div_scale_f32 v0, vcc, v23, v28, v23
	v_mul_f32_e32 v10, v0, v31
	v_fma_f32 v24, -v6, v10, v0
	v_fmac_f32_e32 v10, v24, v31
	v_lshlrev_b32_e32 v24, 16, v11
	v_fma_f32 v0, -v6, v10, v0
	v_mul_f32_e32 v6, 0xbfb8aa3b, v24
	v_div_fmas_f32 v0, v0, v31, v10
	v_exp_f32_e32 v10, v6
	v_mul_f32_e32 v6, 0xbfb8aa3b, v30
	v_exp_f32_e32 v11, v6
	v_div_fixup_f32 v28, v0, v28, v23
	s_waitcnt vmcnt(0)
	v_pk_mul_f32 v[26:27], v[22:23], v[26:27] op_sel_hi:[0,1]
	v_pk_fma_f32 v[26:27], v[26:27], v[28:29], 0 op_sel_hi:[1,1,0]
	v_pk_add_f32 v[10:11], v[10:11], 1.0 op_sel_hi:[1,0]
	v_cvt_pk_bf16_f32 v6, v26, v27
	v_div_scale_f32 v0, s[0:1], v11, v11, v30
	v_rcp_f32_e32 v23, v0
	v_lshlrev_b32_e32 v26, 16, v7
	v_and_b32_e32 v27, 0xffff0000, v7
	v_fma_f32 v7, -v0, v23, 1.0
	v_pk_mul_f32 v[26:27], v[22:23], v[26:27] op_sel_hi:[0,1]
	v_fmac_f32_e32 v23, v7, v23
	v_div_scale_f32 v7, vcc, v30, v11, v30
	v_mul_f32_e32 v28, v7, v23
	v_fma_f32 v29, -v0, v28, v7
	v_fmac_f32_e32 v28, v29, v23
	v_fma_f32 v0, -v0, v28, v7
	v_div_scale_f32 v7, s[0:1], v10, v10, v24
	v_rcp_f32_e32 v29, v7
	v_div_fmas_f32 v0, v0, v23, v28
	v_div_fixup_f32 v11, v0, v11, v30
	v_fma_f32 v0, -v7, v29, 1.0
	v_fmac_f32_e32 v29, v0, v29
	v_div_scale_f32 v0, vcc, v24, v10, v24
	v_mul_f32_e32 v23, v0, v29
	v_fma_f32 v28, -v7, v23, v0
	v_fmac_f32_e32 v23, v28, v29
	v_fma_f32 v0, -v7, v23, v0
	v_div_fmas_f32 v0, v0, v29, v23
	v_lshlrev_b32_e32 v23, 16, v12
	v_and_b32_e32 v12, 0xffff0000, v12
	v_mul_f32_e32 v7, 0xbfb8aa3b, v23
	v_exp_f32_e32 v28, v7
	v_mul_f32_e32 v7, 0xbfb8aa3b, v12
	v_exp_f32_e32 v29, v7
	v_div_fixup_f32 v10, v0, v10, v24
	v_pk_fma_f32 v[10:11], v[26:27], v[10:11], 0 op_sel_hi:[1,1,0]
	v_lshlrev_b32_e32 v26, 16, v8
	v_cvt_pk_bf16_f32 v7, v10, v11
	v_pk_add_f32 v[10:11], v[28:29], 1.0 op_sel_hi:[1,0]
	v_and_b32_e32 v27, 0xffff0000, v8
	v_div_scale_f32 v0, s[0:1], v11, v11, v12
	v_rcp_f32_e32 v24, v0
	v_pk_mul_f32 v[26:27], v[22:23], v[26:27] op_sel_hi:[0,1]
	v_fma_f32 v8, -v0, v24, 1.0
	v_fmac_f32_e32 v24, v8, v24
	v_div_scale_f32 v8, vcc, v12, v11, v12
	v_mul_f32_e32 v28, v8, v24
	v_fma_f32 v29, -v0, v28, v8
	v_fmac_f32_e32 v28, v29, v24
	v_fma_f32 v0, -v0, v28, v8
	v_div_scale_f32 v8, s[0:1], v10, v10, v23
	v_rcp_f32_e32 v29, v8
	v_div_fmas_f32 v0, v0, v24, v28
	v_div_fixup_f32 v11, v0, v11, v12
	v_and_b32_e32 v28, 0xffff0000, v13
	v_fma_f32 v0, -v8, v29, 1.0
	v_fmac_f32_e32 v29, v0, v29
	v_div_scale_f32 v0, vcc, v23, v10, v23
	v_mul_f32_e32 v12, v0, v29
	v_fma_f32 v24, -v8, v12, v0
	v_fmac_f32_e32 v12, v24, v29
	v_lshlrev_b32_e32 v24, 16, v13
	v_fma_f32 v0, -v8, v12, v0
	v_mul_f32_e32 v8, 0xbfb8aa3b, v24
	v_div_fmas_f32 v0, v0, v29, v12
	v_exp_f32_e32 v12, v8
	v_mul_f32_e32 v8, 0xbfb8aa3b, v28
	v_exp_f32_e32 v13, v8
	v_div_fixup_f32 v10, v0, v10, v23
	v_pk_fma_f32 v[10:11], v[26:27], v[10:11], 0 op_sel_hi:[1,1,0]
	s_nop 0
	v_cvt_pk_bf16_f32 v8, v10, v11
	v_pk_add_f32 v[10:11], v[12:13], 1.0 op_sel_hi:[1,0]
	v_lshlrev_b32_e32 v12, 16, v9
	v_div_scale_f32 v0, s[0:1], v11, v11, v28
	v_rcp_f32_e32 v23, v0
	v_and_b32_e32 v13, 0xffff0000, v9
	v_fma_f32 v9, -v0, v23, 1.0
	v_pk_mul_f32 v[12:13], v[22:23], v[12:13] op_sel_hi:[0,1]
	v_fmac_f32_e32 v23, v9, v23
	v_div_scale_f32 v9, vcc, v28, v11, v28
	v_mul_f32_e32 v22, v9, v23
	v_fma_f32 v26, -v0, v22, v9
	v_fmac_f32_e32 v22, v26, v23
	v_fma_f32 v0, -v0, v22, v9
	v_div_scale_f32 v9, s[0:1], v10, v10, v24
	v_rcp_f32_e32 v26, v9
	v_div_fmas_f32 v0, v0, v23, v22
	v_div_fixup_f32 v11, v0, v11, v28
	v_fma_f32 v0, -v9, v26, 1.0
	v_fmac_f32_e32 v26, v0, v26
	v_div_scale_f32 v0, vcc, v24, v10, v24
	v_mul_f32_e32 v22, v0, v26
	v_fma_f32 v23, -v9, v22, v0
	v_fmac_f32_e32 v22, v23, v26
	v_fma_f32 v0, -v9, v22, v0
	v_div_fmas_f32 v0, v0, v26, v22
	v_div_fixup_f32 v10, v0, v10, v24
	v_pk_fma_f32 v[10:11], v[12:13], v[10:11], 0 op_sel_hi:[1,1,0]
	v_add_u32_e32 v0, 28, v25
	v_cvt_pk_bf16_f32 v9, v10, v11
	v_lshl_add_u64 v[10:11], v[20:21], 0, v[14:15]
	global_store_dwordx4 v[10:11], v[6:9], off
	v_and_or_b32 v20, v0, 7, s34
	s_nop 0
	v_ashrrev_i32_e32 v6, 3, v0
	v_ashrrev_i32_e32 v7, 31, v6
	v_lshl_add_u64 v[10:11], s[80:81], 0, v[6:7]
	v_mad_u64_u32 v[6:7], s[0:1], v10, s76, v[16:17]
	v_mad_i32_i24 v7, v11, s76, v7
	v_lshlrev_b32_e32 v0, 8, v20
	v_lshl_add_u64 v[6:7], v[6:7], 0, v[0:1]
	v_lshl_add_u64 v[6:7], v[6:7], 0, v[14:15]
	global_load_dwordx4 v[6:9], v[6:7], off
	v_mad_u64_u32 v[12:13], s[0:1], v10, s77, v[18:19]
	v_mad_i32_i24 v13, v11, s77, v13
	v_lshlrev_b32_e32 v16, 2, v20
	v_mov_b32_e32 v17, v1
	v_lshl_add_u64 v[12:13], v[12:13], 0, v[16:17]
	global_load_dword v12, v[12:13], off
	v_lshlrev_b64 v[10:11], 13, v[10:11]
	v_lshl_add_u64 v[10:11], s[44:45], 0, v[10:11]
	v_lshl_add_u64 v[10:11], v[10:11], 0, v[0:1]
	s_waitcnt lgkmcnt(0)
	v_lshlrev_b32_e32 v18, 16, v2
	v_and_b32_e32 v19, 0xffff0000, v2
	s_waitcnt vmcnt(1)
	v_lshlrev_b32_e32 v13, 16, v6
	v_and_b32_e32 v6, 0xffff0000, v6
	v_mul_f32_e32 v16, 0xbfb8aa3b, v13
	v_mul_f32_e32 v17, 0xbfb8aa3b, v6
	v_exp_f32_e32 v16, v16
	v_exp_f32_e32 v17, v17
	s_waitcnt vmcnt(0)
	v_pk_mul_f32 v[18:19], v[12:13], v[18:19] op_sel_hi:[0,1]
	v_pk_add_f32 v[16:17], v[16:17], 1.0 op_sel_hi:[1,0]
	s_nop 0
	v_div_scale_f32 v0, s[0:1], v17, v17, v6
	v_rcp_f32_e32 v20, v0
	s_nop 0
	v_fma_f32 v2, -v0, v20, 1.0
	v_fmac_f32_e32 v20, v2, v20
	v_div_scale_f32 v2, vcc, v6, v17, v6
	v_mul_f32_e32 v21, v2, v20
	v_fma_f32 v22, -v0, v21, v2
	v_fmac_f32_e32 v21, v22, v20
	v_fma_f32 v0, -v0, v21, v2
	v_div_scale_f32 v2, s[0:1], v16, v16, v13
	v_rcp_f32_e32 v22, v2
	v_div_fmas_f32 v0, v0, v20, v21
	v_div_fixup_f32 v17, v0, v17, v6
	v_and_b32_e32 v21, 0xffff0000, v7
	v_fma_f32 v0, -v2, v22, 1.0
	v_fmac_f32_e32 v22, v0, v22
	v_div_scale_f32 v0, vcc, v13, v16, v13
	v_mul_f32_e32 v6, v0, v22
	v_fma_f32 v20, -v2, v6, v0
	v_fmac_f32_e32 v6, v20, v22
	v_lshlrev_b32_e32 v20, 16, v7
	v_fma_f32 v0, -v2, v6, v0
	v_mul_f32_e32 v2, 0xbfb8aa3b, v20
	v_div_fmas_f32 v0, v0, v22, v6
	v_exp_f32_e32 v6, v2
	v_mul_f32_e32 v2, 0xbfb8aa3b, v21
	v_exp_f32_e32 v7, v2
	v_div_fixup_f32 v16, v0, v16, v13
	v_pk_fma_f32 v[16:17], v[18:19], v[16:17], 0 op_sel_hi:[1,1,0]
	v_pk_add_f32 v[6:7], v[6:7], 1.0 op_sel_hi:[1,0]
	s_nop 0
	v_div_scale_f32 v0, s[0:1], v7, v7, v21
	v_rcp_f32_e32 v13, v0
	v_cvt_pk_bf16_f32 v2, v16, v17
	v_lshlrev_b32_e32 v16, 16, v3
	v_and_b32_e32 v17, 0xffff0000, v3
	v_fma_f32 v3, -v0, v13, 1.0
	v_pk_mul_f32 v[16:17], v[12:13], v[16:17] op_sel_hi:[0,1]
	v_fmac_f32_e32 v13, v3, v13
	v_div_scale_f32 v3, vcc, v21, v7, v21
	v_mul_f32_e32 v18, v3, v13
	v_fma_f32 v19, -v0, v18, v3
	v_fmac_f32_e32 v18, v19, v13
	v_fma_f32 v0, -v0, v18, v3
	v_div_scale_f32 v3, s[0:1], v6, v6, v20
	v_rcp_f32_e32 v19, v3
	v_div_fmas_f32 v0, v0, v13, v18
	v_div_fixup_f32 v7, v0, v7, v21
	v_fma_f32 v0, -v3, v19, 1.0
	v_fmac_f32_e32 v19, v0, v19
	v_div_scale_f32 v0, vcc, v20, v6, v20
	v_mul_f32_e32 v13, v0, v19
	v_fma_f32 v18, -v3, v13, v0
	v_fmac_f32_e32 v13, v18, v19
	v_fma_f32 v0, -v3, v13, v0
	v_div_fmas_f32 v0, v0, v19, v13
	v_lshlrev_b32_e32 v13, 16, v8
	v_and_b32_e32 v8, 0xffff0000, v8
	v_mul_f32_e32 v3, 0xbfb8aa3b, v13
	v_exp_f32_e32 v18, v3
	v_mul_f32_e32 v3, 0xbfb8aa3b, v8
	v_exp_f32_e32 v19, v3
	v_div_fixup_f32 v6, v0, v6, v20
	v_pk_fma_f32 v[6:7], v[16:17], v[6:7], 0 op_sel_hi:[1,1,0]
	v_lshlrev_b32_e32 v16, 16, v4
	v_cvt_pk_bf16_f32 v3, v6, v7
	v_pk_add_f32 v[6:7], v[18:19], 1.0 op_sel_hi:[1,0]
	v_and_b32_e32 v17, 0xffff0000, v4
	v_div_scale_f32 v0, s[0:1], v7, v7, v8
	v_rcp_f32_e32 v18, v0
	v_pk_mul_f32 v[16:17], v[12:13], v[16:17] op_sel_hi:[0,1]
	v_fma_f32 v4, -v0, v18, 1.0
	v_fmac_f32_e32 v18, v4, v18
	v_div_scale_f32 v4, vcc, v8, v7, v8
	v_mul_f32_e32 v19, v4, v18
	v_fma_f32 v20, -v0, v19, v4
	v_fmac_f32_e32 v19, v20, v18
	v_fma_f32 v0, -v0, v19, v4
	v_div_scale_f32 v4, s[0:1], v6, v6, v13
	v_rcp_f32_e32 v20, v4
	v_div_fmas_f32 v0, v0, v18, v19
	v_div_fixup_f32 v7, v0, v7, v8
	v_and_b32_e32 v19, 0xffff0000, v9
	v_fma_f32 v0, -v4, v20, 1.0
	v_fmac_f32_e32 v20, v0, v20
	v_div_scale_f32 v0, vcc, v13, v6, v13
	v_mul_f32_e32 v8, v0, v20
	v_fma_f32 v18, -v4, v8, v0
	v_fmac_f32_e32 v8, v18, v20
	v_lshlrev_b32_e32 v18, 16, v9
	v_fma_f32 v0, -v4, v8, v0
	v_mul_f32_e32 v4, 0xbfb8aa3b, v18
	v_div_fmas_f32 v0, v0, v20, v8
	v_exp_f32_e32 v8, v4
	v_mul_f32_e32 v4, 0xbfb8aa3b, v19
	v_exp_f32_e32 v9, v4
	v_div_fixup_f32 v6, v0, v6, v13
	v_pk_fma_f32 v[6:7], v[16:17], v[6:7], 0 op_sel_hi:[1,1,0]
	s_nop 0
	v_cvt_pk_bf16_f32 v4, v6, v7
	v_pk_add_f32 v[6:7], v[8:9], 1.0 op_sel_hi:[1,0]
	v_lshlrev_b32_e32 v8, 16, v5
	v_div_scale_f32 v0, s[0:1], v7, v7, v19
	v_rcp_f32_e32 v13, v0
	v_and_b32_e32 v9, 0xffff0000, v5
	v_fma_f32 v5, -v0, v13, 1.0
	v_pk_mul_f32 v[8:9], v[12:13], v[8:9] op_sel_hi:[0,1]
	v_fmac_f32_e32 v13, v5, v13
	v_div_scale_f32 v5, vcc, v19, v7, v19
	v_mul_f32_e32 v12, v5, v13
	v_fma_f32 v16, -v0, v12, v5
	v_fmac_f32_e32 v12, v16, v13
	v_fma_f32 v0, -v0, v12, v5
	v_div_scale_f32 v5, s[0:1], v6, v6, v18
	v_rcp_f32_e32 v16, v5
	v_div_fmas_f32 v0, v0, v13, v12
	v_div_fixup_f32 v7, v0, v7, v19
	v_fma_f32 v0, -v5, v16, 1.0
	v_fmac_f32_e32 v16, v0, v16
	v_div_scale_f32 v0, vcc, v18, v6, v18
	v_mul_f32_e32 v12, v0, v16
	v_fma_f32 v13, -v5, v12, v0
	v_fmac_f32_e32 v12, v13, v16
	v_fma_f32 v0, -v5, v12, v0
	v_div_fmas_f32 v0, v0, v16, v12
	v_div_fixup_f32 v6, v0, v6, v18
	v_pk_fma_f32 v[6:7], v[8:9], v[6:7], 0 op_sel_hi:[1,1,0]
	v_add_u32_e32 v0, s67, v196
	v_cvt_pk_bf16_f32 v5, v6, v7
	v_lshl_add_u64 v[6:7], v[10:11], 0, v[14:15]
	global_store_dwordx4 v[6:7], v[2:5], off
	v_mov_b32_e32 v6, -1.0
	s_nop 0
	v_ashrrev_i32_e32 v3, 6, v0
	v_add_u32_e32 v2, -2, v3
	v_cmp_gt_i32_e32 vcc, v150, v3
	v_cmp_le_i32_e64 s[0:1], v150, v3
	v_mov_b32_e32 v0, -1.0
	s_barrier
	s_and_saveexec_b64 s[12:13], s[0:1]
	s_cbranch_execz .LBB0_1168
	v_readlane_b32 s14, v255, 29
	v_cmp_le_i32_e64 s[0:1], v150, v2
	v_readlane_b32 s15, v255, 30
	s_and_b64 s[14:15], s[14:15], s[0:1]
	v_mov_b32_e32 v6, 0x4e6e6b28
	s_and_saveexec_b64 s[0:1], s[14:15]
	s_cbranch_execz .LBB0_1167
	v_add_u32_e32 v4, -4, v197
	ds_read2_b32 v[4:5], v4 offset1:1
	s_waitcnt lgkmcnt(0)
	v_add_f32_e32 v6, v4, v5
	ds_read2_b32 v[4:5], v197 offset0:1 offset1:2
	s_waitcnt lgkmcnt(0)
	v_add_f32_e32 v4, v6, v4
	v_add_f32_e32 v4, v4, v5
	ds_read_b32 v5, v197 offset:12
	s_waitcnt lgkmcnt(0)
	v_add_f32_e32 v6, v4, v5

.LBB0_1210:
	s_bitcmp1_b32 s16, 0
	v_lshrrev_b64 v[10:11], v0, v[170:171]
	s_cselect_b32 s27, 0x8c00, 0
	v_and_b32_e32 v10, 1, v10
	v_add_u32_e32 v234, s27, v219
	v_cmp_eq_u32_e32 vcc, 1, v10
	v_cmp_ne_u32_e64 s[0:1], 0, v10
	ds_read_b128 v[82:85], v234
	ds_read_b128 v[142:145], v234 offset:32
	ds_read_b128 v[138:141], v234 offset:64
	ds_read_b128 v[10:13], v234 offset:96
	s_cmp_lg_u64 s[0:1], 0
	s_cselect_b64 s[22:23], -1, 0
	s_and_b64 s[16:17], s[12:13], vcc
	v_lshl_or_b32 v233, v0, 6, v188
	v_cndmask_b32_e64 v169, 0, v168, s[16:17]
	v_add_u32_e32 v81, s27, v220
	s_mov_b64 vcc, s[0:1]
	s_cbranch_vccz .LBB0_1214
	s_waitcnt lgkmcnt(3)
	v_mfma_f32_32x32x16_bf16 v[82:97], v[82:85], v[122:125], 0
	s_waitcnt lgkmcnt(2)
	v_mfma_f32_32x32x16_bf16 v[82:97], v[142:145], v[126:129], v[82:97]
	s_waitcnt lgkmcnt(1)
	v_mfma_f32_32x32x16_bf16 v[82:97], v[138:141], v[98:101], v[82:97]
	ds_read_b128 v[138:141], v234 offset:128
	ds_read_b128 v[142:145], v234 offset:160
	ds_read_b128 v[236:239], v234 offset:192
	ds_read_b128 v[240:243], v234 offset:224
	s_waitcnt lgkmcnt(4)
	v_mfma_f32_32x32x16_bf16 v[82:97], v[10:13], v[102:105], v[82:97]
	s_waitcnt lgkmcnt(3)
	v_mfma_f32_32x32x16_bf16 v[82:97], v[138:141], v[106:109], v[82:97]
	v_cndmask_b32_e64 v0, v230, v233, s[16:17]
	v_cmp_le_u32_e32 vcc, v0, v169
	v_or_b32_e32 v208, 10, v0
	v_or_b32_e32 v209, 11, v0
	v_or_b32_e32 v210, 16, v0
	v_or_b32_e32 v211, 17, v0
	ds_read_b128 v[138:141], v81 offset:17408
	ds_read_b128 v[10:13], v81 offset:22016
	s_waitcnt lgkmcnt(4)
	v_mfma_f32_32x32x16_bf16 v[82:97], v[142:145], v[110:113], v[82:97]
	v_or_b32_e32 v142, 2, v0
	v_or_b32_e32 v143, 3, v0
	v_or_b32_e32 v144, 8, v0
	v_or_b32_e32 v145, 9, v0
	s_waitcnt lgkmcnt(3)
	v_mfma_f32_32x32x16_bf16 v[82:97], v[236:239], v[114:117], v[82:97]
	s_waitcnt lgkmcnt(2)
	v_mfma_f32_32x32x16_bf16 v[82:97], v[240:243], v[118:121], v[82:97]
	s_cmp_eq_u64 s[14:15], 0
	s_nop 10
	s_cbranch_scc0 .Lself0_slow
	v_cndmask_b32_e64 v237, v231, v82, s[16:17]
	v_cndmask_b32_e64 v238, v231, v83, s[16:17]
	v_cndmask_b32_e64 v239, v231, v84, s[16:17]
	v_cndmask_b32_e64 v240, v231, v85, s[16:17]
	v_cndmask_b32_e64 v142, v231, v86, s[16:17]
	v_cndmask_b32_e64 v143, v231, v87, s[16:17]
	v_cndmask_b32_e64 v144, v231, v88, s[16:17]
	v_cndmask_b32_e64 v145, v231, v89, s[16:17]
	v_cndmask_b32_e64 v244, v231, v90, s[16:17]
	v_cndmask_b32_e64 v241, v231, v91, s[16:17]
	v_cndmask_b32_e64 v242, v231, v92, s[16:17]
	v_cndmask_b32_e64 v243, v231, v93, s[16:17]
	v_cndmask_b32_e64 v90, v231, v94, s[16:17]
	v_cndmask_b32_e64 v91, v231, v95, s[16:17]
	v_max_f32_e32 v82, v237, v237
	v_cndmask_b32_e64 v92, v231, v96, s[16:17]
	v_max_f32_e32 v0, v238, v238
	v_max_f32_e32 v0, v82, v0
	v_max3_f32 v0, v0, v239, v240
	v_max3_f32 v0, v0, v142, v143
	v_max3_f32 v0, v0, v144, v145
	v_max3_f32 v0, v0, v244, v241
	v_max3_f32 v0, v0, v242, v243
	v_cndmask_b32_e64 v93, v231, v97, s[16:17]
	v_max3_f32 v0, v0, v90, v91
	v_max3_f32 v0, v0, v92, v93

.Lself0_slow:
	v_cndmask_b32_e32 v237, v231, v82, vcc
	v_cmp_lt_u32_e32 vcc, v0, v169
	v_or_b32_e32 v82, 18, v0
	s_nop 0
	v_cndmask_b32_e32 v238, v231, v83, vcc
	v_cmp_le_u32_e32 vcc, v142, v169
	s_nop 1
	v_cndmask_b32_e32 v239, v231, v84, vcc
	v_cmp_le_u32_e32 vcc, v143, v169
	s_nop 1
	v_cndmask_b32_e32 v240, v231, v85, vcc
	v_cmp_le_u32_e32 vcc, v144, v169
	s_nop 1
	v_cndmask_b32_e32 v142, v231, v86, vcc
	v_cmp_le_u32_e32 vcc, v145, v169
	s_nop 1
	v_cndmask_b32_e32 v143, v231, v87, vcc
	v_cmp_le_u32_e32 vcc, v208, v169
	s_nop 1
	v_cndmask_b32_e32 v144, v231, v88, vcc
	v_cmp_le_u32_e32 vcc, v209, v169
	s_nop 1
	v_cndmask_b32_e32 v145, v231, v89, vcc
	v_cmp_le_u32_e32 vcc, v210, v169
	s_nop 1
	v_cndmask_b32_e32 v244, v231, v90, vcc
	v_cmp_le_u32_e32 vcc, v211, v169
	s_nop 1
	v_cndmask_b32_e32 v241, v231, v91, vcc
	v_cmp_le_u32_e32 vcc, v82, v169
	v_or_b32_e32 v82, 19, v0
	s_nop 0
	v_cndmask_b32_e32 v242, v231, v92, vcc
	v_cmp_le_u32_e32 vcc, v82, v169
	v_or_b32_e32 v82, 24, v0
	s_nop 0
	v_cndmask_b32_e32 v243, v231, v93, vcc
	v_cmp_le_u32_e32 vcc, v82, v169
	v_or_b32_e32 v82, 25, v0
	s_nop 0
	v_cndmask_b32_e32 v90, v231, v94, vcc
	v_cmp_le_u32_e32 vcc, v82, v169
	v_or_b32_e32 v82, 26, v0
	v_or_b32_e32 v0, 27, v0
	v_cndmask_b32_e32 v91, v231, v95, vcc
	v_cmp_le_u32_e32 vcc, v82, v169
	v_max_f32_e32 v82, v237, v237
	s_nop 0
	v_cndmask_b32_e32 v92, v231, v96, vcc
	v_cmp_le_u32_e32 vcc, v0, v169
	v_max_f32_e32 v0, v238, v238
	v_max_f32_e32 v0, v82, v0
	v_max3_f32 v0, v0, v239, v240
	v_max3_f32 v0, v0, v142, v143
	v_max3_f32 v0, v0, v144, v145
	v_max3_f32 v0, v0, v244, v241
	v_max3_f32 v0, v0, v242, v243
	v_cndmask_b32_e32 v93, v231, v97, vcc
	v_max3_f32 v0, v0, v90, v91
	v_max3_f32 v0, v0, v92, v93
	s_branch .Lself0_join
.Lself1_slow:
	v_cndmask_b32_e32 v144, v231, v82, vcc
	v_cmp_lt_u32_e32 vcc, v0, v169
	v_or_b32_e32 v82, 17, v0
	s_nop 0
	v_cndmask_b32_e32 v145, v231, v83, vcc
	v_cmp_le_u32_e32 vcc, v14, v169
	s_nop 1
	v_cndmask_b32_e32 v233, v231, v84, vcc
	v_cmp_le_u32_e32 vcc, v15, v169
	s_nop 1
	v_cndmask_b32_e32 v234, v231, v85, vcc
	v_cmp_le_u32_e32 vcc, v142, v169
	s_nop 1
	v_cndmask_b32_e32 v14, v231, v86, vcc
	v_cmp_le_u32_e32 vcc, v143, v169
	s_nop 1
	v_cndmask_b32_e32 v15, v231, v87, vcc
	v_cmp_le_u32_e32 vcc, v208, v169
	s_nop 1
	v_cndmask_b32_e32 v142, v231, v88, vcc
	v_cmp_le_u32_e32 vcc, v209, v169
	s_nop 1
	v_cndmask_b32_e32 v143, v231, v89, vcc
	v_cmp_le_u32_e32 vcc, v210, v169
	s_nop 1
	v_cndmask_b32_e32 v237, v231, v90, vcc
	v_cmp_le_u32_e32 vcc, v82, v169
	v_or_b32_e32 v82, 18, v0
	s_nop 0
	v_cndmask_b32_e32 v238, v231, v91, vcc
	v_cmp_le_u32_e32 vcc, v82, v169
	v_or_b32_e32 v82, 19, v0
	s_nop 0
	v_cndmask_b32_e32 v239, v231, v92, vcc
	v_cmp_le_u32_e32 vcc, v82, v169
	v_or_b32_e32 v82, 24, v0
	s_nop 0
	v_cndmask_b32_e32 v240, v231, v93, vcc
	v_cmp_le_u32_e32 vcc, v82, v169
	v_or_b32_e32 v82, 25, v0
	s_nop 0
	v_cndmask_b32_e32 v90, v231, v94, vcc
	v_cmp_le_u32_e32 vcc, v82, v169
	v_or_b32_e32 v82, 26, v0
	v_or_b32_e32 v0, 27, v0
	v_cndmask_b32_e32 v91, v231, v95, vcc
	v_cmp_le_u32_e32 vcc, v82, v169
	v_max_f32_e32 v82, v144, v144
	s_nop 0
	v_cndmask_b32_e32 v92, v231, v96, vcc
	v_cmp_le_u32_e32 vcc, v0, v169
	v_max_f32_e32 v0, v145, v145
	v_max_f32_e32 v0, v82, v0
	v_max3_f32 v0, v0, v233, v234
	v_max3_f32 v0, v0, v14, v15
	v_max3_f32 v0, v0, v142, v143
	v_max3_f32 v0, v0, v237, v238
	v_max3_f32 v0, v0, v239, v240
	v_cndmask_b32_e32 v93, v231, v97, vcc
	v_max3_f32 v0, v0, v90, v91
	v_max3_f32 v0, v0, v92, v93
	s_branch .Lself1_join

.LBB0_1217:
	s_andn2_b64 vcc, exec, s[22:23]
	s_cbranch_vccnz .LBB0_1221
	s_waitcnt lgkmcnt(3)
	v_mfma_f32_32x32x16_bf16 v[82:97], v[82:85], v[122:125], 0
	s_waitcnt lgkmcnt(2)
	v_mfma_f32_32x32x16_bf16 v[82:97], v[142:145], v[126:129], v[82:97]
	s_waitcnt lgkmcnt(1)
	v_mfma_f32_32x32x16_bf16 v[82:97], v[138:141], v[98:101], v[82:97]
	ds_read_b128 v[138:141], v234 offset:8832
	ds_read_b128 v[142:145], v234 offset:8864
	ds_read_b128 v[238:241], v234 offset:8896
	ds_read_b128 v[242:245], v234 offset:8928
	s_waitcnt lgkmcnt(4)
	v_mfma_f32_32x32x16_bf16 v[82:97], v[10:13], v[102:105], v[82:97]
	s_waitcnt lgkmcnt(3)
	v_mfma_f32_32x32x16_bf16 v[82:97], v[138:141], v[106:109], v[82:97]
	v_or_b32_e32 v0, 32, v233
	v_cndmask_b32_e64 v0, v230, v0, s[16:17]
	v_cmp_le_u32_e32 vcc, v0, v169
	v_or_b32_e32 v14, 2, v0
	v_or_b32_e32 v15, 3, v0
	v_or_b32_e32 v208, 10, v0
	v_or_b32_e32 v209, 11, v0
	s_waitcnt lgkmcnt(2)
	v_mfma_f32_32x32x16_bf16 v[82:97], v[142:145], v[110:113], v[82:97]
	v_or_b32_e32 v142, 8, v0
	v_or_b32_e32 v143, 9, v0
	v_or_b32_e32 v210, 16, v0
	ds_read_b128 v[138:141], v81 offset:17472
	ds_read_b128 v[10:13], v81 offset:22080
	s_waitcnt lgkmcnt(3)
	v_mfma_f32_32x32x16_bf16 v[82:97], v[238:241], v[114:117], v[82:97]
	s_waitcnt lgkmcnt(2)
	v_mfma_f32_32x32x16_bf16 v[82:97], v[242:245], v[118:121], v[82:97]
	s_cmp_eq_u64 s[14:15], 0
	s_nop 10
	s_cbranch_scc0 .Lself1_slow
	v_cndmask_b32_e64 v144, v231, v82, s[16:17]
	v_cndmask_b32_e64 v145, v231, v83, s[16:17]
	v_cndmask_b32_e64 v233, v231, v84, s[16:17]
	v_cndmask_b32_e64 v234, v231, v85, s[16:17]
	v_cndmask_b32_e64 v14, v231, v86, s[16:17]
	v_cndmask_b32_e64 v15, v231, v87, s[16:17]
	v_cndmask_b32_e64 v142, v231, v88, s[16:17]
	v_cndmask_b32_e64 v143, v231, v89, s[16:17]
	v_cndmask_b32_e64 v237, v231, v90, s[16:17]
	v_cndmask_b32_e64 v238, v231, v91, s[16:17]
	v_cndmask_b32_e64 v239, v231, v92, s[16:17]
	v_cndmask_b32_e64 v240, v231, v93, s[16:17]
	v_cndmask_b32_e64 v90, v231, v94, s[16:17]
	v_cndmask_b32_e64 v91, v231, v95, s[16:17]
	v_max_f32_e32 v82, v144, v144
	v_cndmask_b32_e64 v92, v231, v96, s[16:17]
	v_max_f32_e32 v0, v145, v145
	v_max_f32_e32 v0, v82, v0
	v_max3_f32 v0, v0, v233, v234
	v_max3_f32 v0, v0, v14, v15
	v_max3_f32 v0, v0, v142, v143
	v_max3_f32 v0, v0, v237, v238
	v_max3_f32 v0, v0, v239, v240
	v_cndmask_b32_e64 v93, v231, v97, s[16:17]
	v_max3_f32 v0, v0, v90, v91
	v_max3_f32 v0, v0, v92, v93

.LBB0_1229:
	ds_bpermute_b32 v0, v191, v80
	s_waitcnt vmcnt(0)
	v_mov_b32_e32 v8, v177
	s_waitcnt lgkmcnt(0)
	v_add_f32_e32 v0, v80, v0
	v_div_scale_f32 v2, s[0:1], v0, v0, 1.0
	v_rcp_f32_e32 v3, v2
	v_div_scale_f32 v5, vcc, 1.0, v0, 1.0
	v_and_b32_e32 v4, 31, v8
	v_fma_f32 v6, -v2, v3, 1.0
	v_fmac_f32_e32 v3, v6, v3
	v_mul_f32_e32 v6, v5, v3
	v_fma_f32 v7, -v2, v6, v5
	v_fmac_f32_e32 v6, v7, v3
	v_fma_f32 v2, -v2, v6, v5
	v_div_fmas_f32 v2, v2, v3, v6
	v_div_fixup_f32 v2, v2, v0, 1.0
	v_cmp_lt_f32_e32 vcc, 0, v0
	v_mul_u32_u24_e32 v6, 0x110, v4
	s_nop 0
	v_cndmask_b32_e32 v0, 0, v2, vcc
	v_pk_mul_f32 v[2:3], v[64:65], v[0:1] op_sel_hi:[1,0]
	v_pk_mul_f32 v[4:5], v[66:67], v[0:1] op_sel_hi:[1,0]
	v_cvt_pk_bf16_f32 v2, v2, v3
	v_cvt_pk_bf16_f32 v3, v4, v5
	v_ashrrev_i32_e32 v4, 2, v8
	v_and_b32_e32 v4, -8, v4
	v_add3_u32 v9, s95, v6, v4
	v_pk_mul_f32 v[4:5], v[68:69], v[0:1] op_sel_hi:[1,0]
	v_pk_mul_f32 v[6:7], v[70:71], v[0:1] op_sel_hi:[1,0]
	v_cvt_pk_bf16_f32 v4, v4, v5
	v_cvt_pk_bf16_f32 v5, v6, v7
	ds_write2_b64 v9, v[2:3], v[4:5] offset1:2
	v_pk_mul_f32 v[2:3], v[72:73], v[0:1] op_sel_hi:[1,0]
	v_pk_mul_f32 v[4:5], v[74:75], v[0:1] op_sel_hi:[1,0]
	v_cvt_pk_bf16_f32 v2, v2, v3
	v_cvt_pk_bf16_f32 v3, v4, v5
	v_pk_mul_f32 v[4:5], v[76:77], v[0:1] op_sel_hi:[1,0]
	v_pk_mul_f32 v[6:7], v[78:79], v[0:1] op_sel_hi:[1,0]
	v_cvt_pk_bf16_f32 v4, v4, v5
	v_cvt_pk_bf16_f32 v5, v6, v7
	ds_write2_b64 v9, v[2:3], v[4:5] offset0:4 offset1:6
	v_pk_mul_f32 v[2:3], v[48:49], v[0:1] op_sel_hi:[1,0]
	v_pk_mul_f32 v[4:5], v[50:51], v[0:1] op_sel_hi:[1,0]
	v_cvt_pk_bf16_f32 v2, v2, v3
	v_cvt_pk_bf16_f32 v3, v4, v5
	v_pk_mul_f32 v[4:5], v[52:53], v[0:1] op_sel_hi:[1,0]
	v_pk_mul_f32 v[6:7], v[54:55], v[0:1] op_sel_hi:[1,0]
	v_cvt_pk_bf16_f32 v4, v4, v5
	v_cvt_pk_bf16_f32 v5, v6, v7
	ds_write2_b64 v9, v[2:3], v[4:5] offset0:8 offset1:10
	v_pk_mul_f32 v[2:3], v[56:57], v[0:1] op_sel_hi:[1,0]
	v_pk_mul_f32 v[4:5], v[58:59], v[0:1] op_sel_hi:[1,0]
	v_cvt_pk_bf16_f32 v2, v2, v3
	v_cvt_pk_bf16_f32 v3, v4, v5
	v_pk_mul_f32 v[4:5], v[60:61], v[0:1] op_sel_hi:[1,0]
	v_pk_mul_f32 v[6:7], v[62:63], v[0:1] op_sel_hi:[1,0]
	v_cvt_pk_bf16_f32 v4, v4, v5
	v_cvt_pk_bf16_f32 v5, v6, v7
	ds_write2_b64 v9, v[2:3], v[4:5] offset0:12 offset1:14
	v_pk_mul_f32 v[2:3], v[32:33], v[0:1] op_sel_hi:[1,0]
	v_pk_mul_f32 v[4:5], v[34:35], v[0:1] op_sel_hi:[1,0]
	v_cvt_pk_bf16_f32 v2, v2, v3
	v_cvt_pk_bf16_f32 v3, v4, v5
	v_pk_mul_f32 v[4:5], v[36:37], v[0:1] op_sel_hi:[1,0]
	v_pk_mul_f32 v[6:7], v[38:39], v[0:1] op_sel_hi:[1,0]
	v_cvt_pk_bf16_f32 v4, v4, v5
	v_cvt_pk_bf16_f32 v5, v6, v7
	ds_write2_b64 v9, v[2:3], v[4:5] offset0:16 offset1:18
	v_pk_mul_f32 v[2:3], v[40:41], v[0:1] op_sel_hi:[1,0]
	v_pk_mul_f32 v[4:5], v[42:43], v[0:1] op_sel_hi:[1,0]
	v_cvt_pk_bf16_f32 v2, v2, v3
	v_cvt_pk_bf16_f32 v3, v4, v5
	v_pk_mul_f32 v[4:5], v[44:45], v[0:1] op_sel_hi:[1,0]
	v_pk_mul_f32 v[6:7], v[46:47], v[0:1] op_sel_hi:[1,0]
	v_cvt_pk_bf16_f32 v4, v4, v5
	v_cvt_pk_bf16_f32 v5, v6, v7
	ds_write2_b64 v9, v[2:3], v[4:5] offset0:20 offset1:22
	v_pk_mul_f32 v[2:3], v[16:17], v[0:1] op_sel_hi:[1,0]
	v_pk_mul_f32 v[4:5], v[18:19], v[0:1] op_sel_hi:[1,0]
	v_cvt_pk_bf16_f32 v2, v2, v3
	v_cvt_pk_bf16_f32 v3, v4, v5
	v_pk_mul_f32 v[4:5], v[20:21], v[0:1] op_sel_hi:[1,0]
	v_pk_mul_f32 v[6:7], v[22:23], v[0:1] op_sel_hi:[1,0]
	v_cvt_pk_bf16_f32 v4, v4, v5
	v_cvt_pk_bf16_f32 v5, v6, v7
	ds_write2_b64 v9, v[2:3], v[4:5] offset0:24 offset1:26
	v_pk_mul_f32 v[2:3], v[24:25], v[0:1] op_sel_hi:[1,0]
	v_pk_mul_f32 v[4:5], v[26:27], v[0:1] op_sel_hi:[1,0]
	v_cvt_pk_bf16_f32 v2, v2, v3
	v_cvt_pk_bf16_f32 v3, v4, v5
	v_pk_mul_f32 v[4:5], v[28:29], v[0:1] op_sel_hi:[1,0]
	v_pk_mul_f32 v[6:7], v[30:31], v[0:1] op_sel_hi:[1,0]
	v_cvt_pk_bf16_f32 v4, v4, v5
	v_cvt_pk_bf16_f32 v5, v6, v7
	ds_write2_b64 v9, v[2:3], v[4:5] offset0:28 offset1:30
	v_ashrrev_i32_e32 v2, 7, v8
	v_ashrrev_i32_e32 v3, 31, v2
	v_ashrrev_i32_e32 v29, 4, v8
	v_lshl_add_u64 v[2:3], s[80:81], 0, v[2:3]
	v_mov_b64_e32 v[20:21], s[48:49]
	v_lshlrev_b32_e32 v0, 4, v8
	v_and_or_b32 v6, v29, 7, s34
	v_mad_u64_u32 v[4:5], s[0:1], v2, s76, v[20:21]
	v_and_b32_e32 v18, 0xf0, v0
	v_mad_i32_i24 v5, v3, s76, v5
	v_lshlrev_b32_e32 v0, 8, v6
	v_lshl_add_u64 v[4:5], v[4:5], 0, v[0:1]
	v_mov_b32_e32 v19, v1
	v_lshl_add_u64 v[4:5], v[4:5], 0, v[18:19]
	v_add_co_u32_e32 v4, vcc, s35, v4
	s_waitcnt lgkmcnt(0)
	v_mov_b64_e32 v[22:23], s[50:51]
	s_nop 0
	v_addc_co_u32_e32 v5, vcc, 0, v5, vcc
	global_load_dwordx4 v[10:13], v[4:5], off
	global_load_dwordx4 v[40:43], v[4:5], off offset:1024
	v_add_co_u32_e32 v68, vcc, 0x6000, v4
	s_nop 1
	v_addc_co_u32_e32 v69, vcc, 0, v5, vcc
	global_load_dwordx4 v[44:47], v[68:69], off
	global_load_dwordx4 v[48:51], v[68:69], off offset:1024
	v_add_co_u32_e32 v68, vcc, 0xc000, v4
	s_nop 1
	v_addc_co_u32_e32 v69, vcc, 0, v5, vcc
	global_load_dwordx4 v[52:55], v[68:69], off
	global_load_dwordx4 v[56:59], v[68:69], off offset:1024
	v_add_co_u32_e32 v68, vcc, 0x12000, v4
	s_nop 1
	v_addc_co_u32_e32 v69, vcc, 0, v5, vcc
	global_load_dwordx4 v[60:63], v[68:69], off
	global_load_dwordx4 v[64:67], v[68:69], off offset:1024
	v_mad_u64_u32 v[4:5], s[0:1], v2, s77, v[22:23]
	v_mad_i32_i24 v5, v3, s77, v5
	v_lshlrev_b64 v[2:3], 13, v[2:3]
	v_lshl_add_u64 v[2:3], s[44:45], 0, v[2:3]
	v_lshlrev_b32_e32 v24, 2, v6
	v_mov_b32_e32 v25, v1
	v_lshl_add_u64 v[2:3], v[2:3], 0, v[0:1]
	v_lshl_add_u64 v[4:5], v[4:5], 0, v[24:25]
	v_lshl_add_u64 v[26:27], v[2:3], 0, v[18:19]
	global_load_dword v28, v[4:5], off offset:128
	global_load_dwordx4 v[6:9], v[26:27], off
	v_mul_lo_u32 v4, v29, s94
	v_add3_u32 v30, s95, v18, v4
	ds_read_b128 v[14:17], v30
	s_waitcnt vmcnt(2)
	v_lshlrev_b32_e32 v31, 16, v10
	v_and_b32_e32 v10, 0xffff0000, v10
	v_mul_f32_e32 v2, 0xbfb8aa3b, v31
	v_mul_f32_e32 v3, 0xbfb8aa3b, v10
	v_exp_f32_e32 v2, v2
	v_exp_f32_e32 v3, v3
	s_nop 0
	v_pk_add_f32 v[32:33], v[2:3], 1.0 op_sel_hi:[1,0]
	s_nop 0
	v_div_scale_f32 v36, s[0:1], v33, v33, v10
	v_rcp_f32_e32 v37, v36
	ds_read_b128 v[2:5], v30 offset:1088
	s_waitcnt lgkmcnt(1)
	v_lshlrev_b32_e32 v34, 16, v14
	v_and_b32_e32 v35, 0xffff0000, v14
	v_fma_f32 v14, -v36, v37, 1.0
	v_fmac_f32_e32 v37, v14, v37
	v_div_scale_f32 v14, vcc, v10, v33, v10
	v_mul_f32_e32 v38, v14, v37
	v_fma_f32 v39, -v36, v38, v14
	v_fmac_f32_e32 v38, v39, v37
	v_fma_f32 v14, -v36, v38, v14
	v_div_scale_f32 v36, s[0:1], v32, v32, v31
	v_rcp_f32_e32 v39, v36
	v_div_fmas_f32 v14, v14, v37, v38
	v_div_fixup_f32 v33, v14, v33, v10
	v_and_b32_e32 v38, 0xffff0000, v11
	v_fma_f32 v10, -v36, v39, 1.0
	v_fmac_f32_e32 v39, v10, v39
	v_div_scale_f32 v10, vcc, v31, v32, v31
	v_mul_f32_e32 v14, v10, v39
	v_fma_f32 v37, -v36, v14, v10
	v_fmac_f32_e32 v14, v37, v39
	v_fma_f32 v10, -v36, v14, v10
	v_div_fmas_f32 v10, v10, v39, v14
	v_div_fixup_f32 v32, v10, v32, v31
	v_lshlrev_b32_e32 v31, 16, v11
	v_mul_f32_e32 v11, 0xbfb8aa3b, v31
	v_exp_f32_e32 v36, v11
	v_mul_f32_e32 v11, 0xbfb8aa3b, v38
	v_exp_f32_e32 v37, v11
	s_waitcnt vmcnt(1)
	v_pk_mul_f32 v[34:35], v[28:29], v[34:35] op_sel_hi:[0,1]
	s_waitcnt vmcnt(0)
	v_lshlrev_b32_e32 v10, 16, v6
	v_and_b32_e32 v11, 0xffff0000, v6
	v_pk_fma_f32 v[10:11], v[34:35], v[32:33], v[10:11]
	v_lshlrev_b32_e32 v14, 16, v15
	v_cvt_pk_bf16_f32 v6, v10, v11
	v_pk_add_f32 v[10:11], v[36:37], 1.0 op_sel_hi:[1,0]
	v_and_b32_e32 v15, 0xffff0000, v15
	v_div_scale_f32 v32, s[0:1], v11, v11, v38
	v_rcp_f32_e32 v33, v32
	v_pk_mul_f32 v[14:15], v[28:29], v[14:15] op_sel_hi:[0,1]
	v_fma_f32 v34, -v32, v33, 1.0
	v_fmac_f32_e32 v33, v34, v33
	v_div_scale_f32 v34, vcc, v38, v11, v38
	v_mul_f32_e32 v35, v34, v33
	v_fma_f32 v36, -v32, v35, v34
	v_fmac_f32_e32 v35, v36, v33
	v_fma_f32 v32, -v32, v35, v34
	v_div_scale_f32 v34, s[0:1], v10, v10, v31
	v_rcp_f32_e32 v36, v34
	v_div_fmas_f32 v32, v32, v33, v35
	v_div_fixup_f32 v11, v32, v11, v38
	v_fma_f32 v32, -v34, v36, 1.0
	v_fmac_f32_e32 v36, v32, v36
	v_div_scale_f32 v32, vcc, v31, v10, v31
	v_mul_f32_e32 v33, v32, v36
	v_fma_f32 v35, -v34, v33, v32
	v_fmac_f32_e32 v33, v35, v36
	v_fma_f32 v32, -v34, v33, v32
	v_div_fmas_f32 v32, v32, v36, v33
	v_div_fixup_f32 v10, v32, v10, v31
	v_lshlrev_b32_e32 v31, 16, v12
	v_and_b32_e32 v12, 0xffff0000, v12
	v_mul_f32_e32 v33, 0xbfb8aa3b, v31
	v_exp_f32_e32 v34, v33
	v_mul_f32_e32 v33, 0xbfb8aa3b, v12
	v_exp_f32_e32 v35, v33
	v_lshlrev_b32_e32 v32, 16, v7
	v_and_b32_e32 v33, 0xffff0000, v7
	v_pk_fma_f32 v[10:11], v[14:15], v[10:11], v[32:33]
	v_lshlrev_b32_e32 v14, 16, v16
	v_cvt_pk_bf16_f32 v7, v10, v11
	v_pk_add_f32 v[10:11], v[34:35], 1.0 op_sel_hi:[1,0]
	v_and_b32_e32 v15, 0xffff0000, v16
	v_div_scale_f32 v32, s[0:1], v11, v11, v12
	v_rcp_f32_e32 v33, v32
	v_pk_mul_f32 v[14:15], v[28:29], v[14:15] op_sel_hi:[0,1]
	v_fma_f32 v16, -v32, v33, 1.0
	v_fmac_f32_e32 v33, v16, v33
	v_div_scale_f32 v16, vcc, v12, v11, v12
	v_mul_f32_e32 v34, v16, v33
	v_fma_f32 v35, -v32, v34, v16
	v_fmac_f32_e32 v34, v35, v33
	v_fma_f32 v16, -v32, v34, v16
	v_div_scale_f32 v32, s[0:1], v10, v10, v31
	v_rcp_f32_e32 v35, v32
	v_div_fmas_f32 v16, v16, v33, v34
	v_div_fixup_f32 v11, v16, v11, v12
	v_fma_f32 v12, -v32, v35, 1.0
	v_fmac_f32_e32 v35, v12, v35
	v_div_scale_f32 v12, vcc, v31, v10, v31
	v_mul_f32_e32 v16, v12, v35
	v_fma_f32 v33, -v32, v16, v12
	v_fmac_f32_e32 v16, v33, v35
	v_fma_f32 v12, -v32, v16, v12
	v_div_fmas_f32 v12, v12, v35, v16
	v_lshlrev_b32_e32 v16, 16, v13
	v_div_fixup_f32 v10, v12, v10, v31
	v_and_b32_e32 v31, 0xffff0000, v13
	v_mul_f32_e32 v13, 0xbfb8aa3b, v16
	v_exp_f32_e32 v32, v13
	v_mul_f32_e32 v13, 0xbfb8aa3b, v31
	v_exp_f32_e32 v33, v13
	v_lshlrev_b32_e32 v12, 16, v8
	v_and_b32_e32 v13, 0xffff0000, v8
	v_pk_fma_f32 v[10:11], v[14:15], v[10:11], v[12:13]
	v_lshlrev_b32_e32 v12, 16, v17
	v_cvt_pk_bf16_f32 v8, v10, v11
	v_pk_add_f32 v[10:11], v[32:33], 1.0 op_sel_hi:[1,0]
	v_and_b32_e32 v13, 0xffff0000, v17
	v_div_scale_f32 v14, s[0:1], v11, v11, v31
	v_rcp_f32_e32 v15, v14
	v_pk_mul_f32 v[12:13], v[28:29], v[12:13] op_sel_hi:[0,1]
	s_waitcnt lgkmcnt(0)
	v_and_b32_e32 v33, 0xffff0000, v2
	v_fma_f32 v17, -v14, v15, 1.0
	v_fmac_f32_e32 v15, v17, v15
	v_div_scale_f32 v17, vcc, v31, v11, v31
	v_mul_f32_e32 v28, v17, v15
	v_fma_f32 v32, -v14, v28, v17
	v_fmac_f32_e32 v28, v32, v15
	v_fma_f32 v14, -v14, v28, v17
	v_div_scale_f32 v17, s[0:1], v10, v10, v16
	v_rcp_f32_e32 v32, v17
	v_div_fmas_f32 v14, v14, v15, v28
	v_div_fixup_f32 v11, v14, v11, v31
	v_fma_f32 v14, -v17, v32, 1.0
	v_fmac_f32_e32 v32, v14, v32
	v_div_scale_f32 v14, vcc, v16, v10, v16
	v_mul_f32_e32 v15, v14, v32
	v_fma_f32 v28, -v17, v15, v14
	v_fmac_f32_e32 v15, v28, v32
	v_fma_f32 v14, -v17, v15, v14
	v_div_fmas_f32 v14, v14, v32, v15
	v_div_fixup_f32 v10, v14, v10, v16
	v_lshlrev_b32_e32 v14, 16, v9
	v_and_b32_e32 v15, 0xffff0000, v9
	v_pk_fma_f32 v[10:11], v[12:13], v[10:11], v[14:15]
	v_mov_b32_e32 v13, v1
	v_cvt_pk_bf16_f32 v9, v10, v11
	global_store_dwordx4 v[26:27], v[6:9], off
	v_mov_b32_e32 v17, v1
	v_lshlrev_b32_e32 v32, 16, v2
	v_add_u32_e32 v8, 4, v29
	v_ashrrev_i32_e32 v6, 3, v8
	v_ashrrev_i32_e32 v7, 31, v6
	v_lshl_add_u64 v[10:11], s[80:81], 0, v[6:7]
	v_and_or_b32 v16, v8, 7, s34
	v_mad_u64_u32 v[6:7], s[0:1], v10, s76, v[20:21]
	v_mad_i32_i24 v7, v11, s76, v7
	v_lshlrev_b32_e32 v12, 8, v16
	v_lshl_add_u64 v[6:7], v[6:7], 0, v[12:13]
	v_lshl_add_u64 v[6:7], v[6:7], 0, v[18:19]
	v_add_co_u32_e32 v6, vcc, s35, v6
	v_mad_u64_u32 v[14:15], s[0:1], v10, s77, v[22:23]
	s_nop 0
	v_addc_co_u32_e32 v7, vcc, 0, v7, vcc
	global_load_dwordx4 v[6:9], v[6:7], off
	v_mad_i32_i24 v15, v11, s77, v15
	v_lshlrev_b32_e32 v16, 2, v16
	v_lshl_add_u64 v[14:15], v[14:15], 0, v[16:17]
	global_load_dword v14, v[14:15], off offset:128
	v_lshlrev_b64 v[10:11], 13, v[10:11]
	v_lshl_add_u64 v[10:11], s[44:45], 0, v[10:11]
	v_lshl_add_u64 v[10:11], v[10:11], 0, v[12:13]
	v_lshl_add_u64 v[16:17], v[10:11], 0, v[18:19]
	global_load_dwordx4 v[10:13], v[16:17], off
	s_waitcnt vmcnt(2)
	v_lshlrev_b32_e32 v15, 16, v6
	v_and_b32_e32 v6, 0xffff0000, v6
	v_mul_f32_e32 v26, 0xbfb8aa3b, v15
	v_mul_f32_e32 v27, 0xbfb8aa3b, v6
	v_exp_f32_e32 v26, v26
	v_exp_f32_e32 v27, v27
	s_waitcnt vmcnt(1)
	v_pk_mul_f32 v[32:33], v[14:15], v[32:33] op_sel_hi:[0,1]
	v_pk_add_f32 v[26:27], v[26:27], 1.0 op_sel_hi:[1,0]
	s_nop 0
	v_div_scale_f32 v28, s[0:1], v27, v27, v6
	v_rcp_f32_e32 v31, v28
	s_nop 0
	v_fma_f32 v2, -v28, v31, 1.0
	v_fmac_f32_e32 v31, v2, v31
	v_div_scale_f32 v2, vcc, v6, v27, v6
	v_mul_f32_e32 v34, v2, v31
	v_fma_f32 v35, -v28, v34, v2
	v_fmac_f32_e32 v34, v35, v31
	v_fma_f32 v2, -v28, v34, v2
	v_div_scale_f32 v28, s[0:1], v26, v26, v15
	v_rcp_f32_e32 v35, v28
	v_div_fmas_f32 v2, v2, v31, v34
	v_div_fixup_f32 v27, v2, v27, v6
	v_fma_f32 v2, -v28, v35, 1.0
	v_fmac_f32_e32 v35, v2, v35
	v_div_scale_f32 v2, vcc, v15, v26, v15
	v_mul_f32_e32 v6, v2, v35
	v_fma_f32 v31, -v28, v6, v2
	v_fmac_f32_e32 v6, v31, v35
	v_fma_f32 v2, -v28, v6, v2
	v_div_fmas_f32 v2, v2, v35, v6
	v_div_fixup_f32 v26, v2, v26, v15
	v_lshlrev_b32_e32 v15, 16, v7
	v_and_b32_e32 v28, 0xffff0000, v7
	v_mul_f32_e32 v2, 0xbfb8aa3b, v15
	v_exp_f32_e32 v34, v2
	v_mul_f32_e32 v2, 0xbfb8aa3b, v28
	v_exp_f32_e32 v35, v2
	s_waitcnt vmcnt(0)
	v_lshlrev_b32_e32 v6, 16, v10
	v_and_b32_e32 v7, 0xffff0000, v10
	v_pk_fma_f32 v[6:7], v[32:33], v[26:27], v[6:7]
	v_lshlrev_b32_e32 v26, 16, v3
	v_cvt_pk_bf16_f32 v2, v6, v7
	v_pk_add_f32 v[6:7], v[34:35], 1.0 op_sel_hi:[1,0]
	v_and_b32_e32 v27, 0xffff0000, v3
	v_div_scale_f32 v10, s[0:1], v7, v7, v28
	v_rcp_f32_e32 v31, v10
	v_pk_mul_f32 v[26:27], v[14:15], v[26:27] op_sel_hi:[0,1]
	v_fma_f32 v3, -v10, v31, 1.0
	v_fmac_f32_e32 v31, v3, v31
	v_div_scale_f32 v3, vcc, v28, v7, v28
	v_mul_f32_e32 v32, v3, v31
	v_fma_f32 v33, -v10, v32, v3
	v_fmac_f32_e32 v32, v33, v31
	v_fma_f32 v3, -v10, v32, v3
	v_div_scale_f32 v10, s[0:1], v6, v6, v15
	v_rcp_f32_e32 v33, v10
	v_div_fmas_f32 v3, v3, v31, v32
	v_div_fixup_f32 v7, v3, v7, v28
	v_fma_f32 v3, -v10, v33, 1.0
	v_fmac_f32_e32 v33, v3, v33
	v_div_scale_f32 v3, vcc, v15, v6, v15
	v_mul_f32_e32 v28, v3, v33
	v_fma_f32 v31, -v10, v28, v3
	v_fmac_f32_e32 v28, v31, v33
	v_fma_f32 v3, -v10, v28, v3
	v_div_fmas_f32 v3, v3, v33, v28
	v_div_fixup_f32 v6, v3, v6, v15
	v_lshlrev_b32_e32 v15, 16, v8
	v_and_b32_e32 v8, 0xffff0000, v8
	v_mul_f32_e32 v3, 0xbfb8aa3b, v15
	v_exp_f32_e32 v32, v3
	v_mul_f32_e32 v3, 0xbfb8aa3b, v8
	v_exp_f32_e32 v33, v3
	v_lshlrev_b32_e32 v10, 16, v11
	v_and_b32_e32 v11, 0xffff0000, v11
	v_pk_fma_f32 v[6:7], v[26:27], v[6:7], v[10:11]
	v_lshlrev_b32_e32 v10, 16, v4
	v_cvt_pk_bf16_f32 v3, v6, v7
	v_pk_add_f32 v[6:7], v[32:33], 1.0 op_sel_hi:[1,0]
	v_and_b32_e32 v11, 0xffff0000, v4
	v_div_scale_f32 v26, s[0:1], v7, v7, v8
	v_rcp_f32_e32 v27, v26
	v_pk_mul_f32 v[10:11], v[14:15], v[10:11] op_sel_hi:[0,1]
	v_fma_f32 v4, -v26, v27, 1.0
	v_fmac_f32_e32 v27, v4, v27
	v_div_scale_f32 v4, vcc, v8, v7, v8
	v_mul_f32_e32 v28, v4, v27
	v_fma_f32 v31, -v26, v28, v4
	v_fmac_f32_e32 v28, v31, v27
	v_fma_f32 v4, -v26, v28, v4
	v_div_scale_f32 v26, s[0:1], v6, v6, v15
	v_rcp_f32_e32 v31, v26
	v_div_fmas_f32 v4, v4, v27, v28
	v_div_fixup_f32 v7, v4, v7, v8
	v_and_b32_e32 v28, 0xffff0000, v9
	v_fma_f32 v4, -v26, v31, 1.0
	v_fmac_f32_e32 v31, v4, v31
	v_div_scale_f32 v4, vcc, v15, v6, v15
	v_mul_f32_e32 v8, v4, v31
	v_fma_f32 v27, -v26, v8, v4
	v_fmac_f32_e32 v8, v27, v31
	v_fma_f32 v4, -v26, v8, v4
	v_div_fmas_f32 v4, v4, v31, v8
	v_div_fixup_f32 v6, v4, v6, v15
	v_lshlrev_b32_e32 v15, 16, v9
	v_mul_f32_e32 v4, 0xbfb8aa3b, v15
	v_exp_f32_e32 v26, v4
	v_mul_f32_e32 v4, 0xbfb8aa3b, v28
	v_exp_f32_e32 v27, v4
	v_lshlrev_b32_e32 v8, 16, v12
	v_and_b32_e32 v9, 0xffff0000, v12
	v_pk_fma_f32 v[6:7], v[10:11], v[6:7], v[8:9]
	v_lshlrev_b32_e32 v8, 16, v5
	v_cvt_pk_bf16_f32 v4, v6, v7
	v_pk_add_f32 v[6:7], v[26:27], 1.0 op_sel_hi:[1,0]
	v_and_b32_e32 v9, 0xffff0000, v5
	v_div_scale_f32 v10, s[0:1], v7, v7, v28
	v_rcp_f32_e32 v11, v10
	v_pk_mul_f32 v[8:9], v[14:15], v[8:9] op_sel_hi:[0,1]
	v_fma_f32 v5, -v10, v11, 1.0
	v_fmac_f32_e32 v11, v5, v11
	v_div_scale_f32 v5, vcc, v28, v7, v28
	v_mul_f32_e32 v12, v5, v11
	v_fma_f32 v14, -v10, v12, v5
	v_fmac_f32_e32 v12, v14, v11
	v_fma_f32 v5, -v10, v12, v5
	v_div_scale_f32 v10, s[0:1], v6, v6, v15
	v_rcp_f32_e32 v14, v10
	v_div_fmas_f32 v5, v5, v11, v12
	v_div_fixup_f32 v7, v5, v7, v28
	v_fma_f32 v5, -v10, v14, 1.0
	v_fmac_f32_e32 v14, v5, v14
	v_div_scale_f32 v5, vcc, v15, v6, v15
	v_mul_f32_e32 v11, v5, v14
	v_fma_f32 v12, -v10, v11, v5
	v_fmac_f32_e32 v11, v12, v14
	v_fma_f32 v5, -v10, v11, v5
	v_div_fmas_f32 v5, v5, v14, v11
	v_div_fixup_f32 v6, v5, v6, v15
	v_lshlrev_b32_e32 v10, 16, v13
	v_and_b32_e32 v11, 0xffff0000, v13
	v_pk_fma_f32 v[6:7], v[8:9], v[6:7], v[10:11]
	s_nop 0
	v_cvt_pk_bf16_f32 v5, v6, v7
	global_store_dwordx4 v[16:17], v[2:5], off
	ds_read_b128 v[14:17], v30 offset:2176
	s_nop 0
	v_add_u32_e32 v2, 8, v29
	v_ashrrev_i32_e32 v2, 3, v2
	v_ashrrev_i32_e32 v3, 31, v2
	v_lshl_add_u64 v[2:3], s[80:81], 0, v[2:3]
	v_mad_u64_u32 v[4:5], s[0:1], v2, s76, v[20:21]
	v_mad_i32_i24 v5, v3, s76, v5
	v_lshl_add_u64 v[4:5], v[4:5], 0, v[0:1]
	v_lshl_add_u64 v[4:5], v[4:5], 0, v[18:19]
	v_add_co_u32_e32 v4, vcc, s35, v4
	s_nop 1
	v_addc_co_u32_e32 v5, vcc, 0, v5, vcc
	global_load_dwordx4 v[10:13], v[4:5], off
	v_mad_u64_u32 v[4:5], s[0:1], v2, s77, v[22:23]
	v_mad_i32_i24 v5, v3, s77, v5
	v_lshlrev_b64 v[2:3], 13, v[2:3]
	v_lshl_add_u64 v[2:3], s[44:45], 0, v[2:3]
	v_lshl_add_u64 v[2:3], v[2:3], 0, v[0:1]
	v_lshl_add_u64 v[4:5], v[4:5], 0, v[24:25]
	v_lshl_add_u64 v[26:27], v[2:3], 0, v[18:19]
	global_load_dword v28, v[4:5], off offset:128
	global_load_dwordx4 v[6:9], v[26:27], off
	s_waitcnt vmcnt(2)
	v_lshlrev_b32_e32 v31, 16, v10
	v_and_b32_e32 v10, 0xffff0000, v10
	v_mul_f32_e32 v2, 0xbfb8aa3b, v31
	v_mul_f32_e32 v3, 0xbfb8aa3b, v10
	v_exp_f32_e32 v2, v2
	v_exp_f32_e32 v3, v3
	s_nop 0
	v_pk_add_f32 v[32:33], v[2:3], 1.0 op_sel_hi:[1,0]
	s_nop 0
	v_div_scale_f32 v36, s[0:1], v33, v33, v10
	v_rcp_f32_e32 v37, v36
	ds_read_b128 v[2:5], v30 offset:3264
	s_waitcnt lgkmcnt(1)
	v_lshlrev_b32_e32 v34, 16, v14
	v_and_b32_e32 v35, 0xffff0000, v14
	v_fma_f32 v14, -v36, v37, 1.0
	v_fmac_f32_e32 v37, v14, v37
	v_div_scale_f32 v14, vcc, v10, v33, v10
	v_mul_f32_e32 v38, v14, v37
	v_fma_f32 v39, -v36, v38, v14
	v_fmac_f32_e32 v38, v39, v37
	v_fma_f32 v14, -v36, v38, v14
	v_div_scale_f32 v36, s[0:1], v32, v32, v31
	v_rcp_f32_e32 v39, v36
	v_div_fmas_f32 v14, v14, v37, v38
	v_div_fixup_f32 v33, v14, v33, v10
	v_and_b32_e32 v38, 0xffff0000, v11
	v_fma_f32 v10, -v36, v39, 1.0
	v_fmac_f32_e32 v39, v10, v39
	v_div_scale_f32 v10, vcc, v31, v32, v31
	v_mul_f32_e32 v14, v10, v39
	v_fma_f32 v37, -v36, v14, v10
	v_fmac_f32_e32 v14, v37, v39
	v_fma_f32 v10, -v36, v14, v10
	v_div_fmas_f32 v10, v10, v39, v14
	v_div_fixup_f32 v32, v10, v32, v31
	v_lshlrev_b32_e32 v31, 16, v11
	v_mul_f32_e32 v11, 0xbfb8aa3b, v31
	v_exp_f32_e32 v36, v11
	v_mul_f32_e32 v11, 0xbfb8aa3b, v38
	v_exp_f32_e32 v37, v11
	s_waitcnt vmcnt(1)
	v_pk_mul_f32 v[34:35], v[28:29], v[34:35] op_sel_hi:[0,1]
	s_waitcnt vmcnt(0)
	v_lshlrev_b32_e32 v10, 16, v6
	v_and_b32_e32 v11, 0xffff0000, v6
	v_pk_fma_f32 v[10:11], v[34:35], v[32:33], v[10:11]
	v_lshlrev_b32_e32 v14, 16, v15
	v_cvt_pk_bf16_f32 v6, v10, v11
	v_pk_add_f32 v[10:11], v[36:37], 1.0 op_sel_hi:[1,0]
	v_and_b32_e32 v15, 0xffff0000, v15
	v_div_scale_f32 v32, s[0:1], v11, v11, v38
	v_rcp_f32_e32 v33, v32
	v_pk_mul_f32 v[14:15], v[28:29], v[14:15] op_sel_hi:[0,1]
	v_fma_f32 v34, -v32, v33, 1.0
	v_fmac_f32_e32 v33, v34, v33
	v_div_scale_f32 v34, vcc, v38, v11, v38
	v_mul_f32_e32 v35, v34, v33
	v_fma_f32 v36, -v32, v35, v34
	v_fmac_f32_e32 v35, v36, v33
	v_fma_f32 v32, -v32, v35, v34
	v_div_scale_f32 v34, s[0:1], v10, v10, v31
	v_rcp_f32_e32 v36, v34
	v_div_fmas_f32 v32, v32, v33, v35
	v_div_fixup_f32 v11, v32, v11, v38
	v_fma_f32 v32, -v34, v36, 1.0
	v_fmac_f32_e32 v36, v32, v36
	v_div_scale_f32 v32, vcc, v31, v10, v31
	v_mul_f32_e32 v33, v32, v36
	v_fma_f32 v35, -v34, v33, v32
	v_fmac_f32_e32 v33, v35, v36
	v_fma_f32 v32, -v34, v33, v32
	v_div_fmas_f32 v32, v32, v36, v33
	v_div_fixup_f32 v10, v32, v10, v31
	v_lshlrev_b32_e32 v31, 16, v12
	v_and_b32_e32 v12, 0xffff0000, v12
	v_mul_f32_e32 v33, 0xbfb8aa3b, v31
	v_exp_f32_e32 v34, v33
	v_mul_f32_e32 v33, 0xbfb8aa3b, v12
	v_exp_f32_e32 v35, v33
	v_lshlrev_b32_e32 v32, 16, v7
	v_and_b32_e32 v33, 0xffff0000, v7
	v_pk_fma_f32 v[10:11], v[14:15], v[10:11], v[32:33]
	v_lshlrev_b32_e32 v14, 16, v16
	v_cvt_pk_bf16_f32 v7, v10, v11
	v_pk_add_f32 v[10:11], v[34:35], 1.0 op_sel_hi:[1,0]
	v_and_b32_e32 v15, 0xffff0000, v16
	v_div_scale_f32 v32, s[0:1], v11, v11, v12
	v_rcp_f32_e32 v33, v32
	v_pk_mul_f32 v[14:15], v[28:29], v[14:15] op_sel_hi:[0,1]
	v_fma_f32 v16, -v32, v33, 1.0
	v_fmac_f32_e32 v33, v16, v33
	v_div_scale_f32 v16, vcc, v12, v11, v12
	v_mul_f32_e32 v34, v16, v33
	v_fma_f32 v35, -v32, v34, v16
	v_fmac_f32_e32 v34, v35, v33
	v_fma_f32 v16, -v32, v34, v16
	v_div_scale_f32 v32, s[0:1], v10, v10, v31
	v_rcp_f32_e32 v35, v32
	v_div_fmas_f32 v16, v16, v33, v34
	v_div_fixup_f32 v11, v16, v11, v12
	v_fma_f32 v12, -v32, v35, 1.0
	v_fmac_f32_e32 v35, v12, v35
	v_div_scale_f32 v12, vcc, v31, v10, v31
	v_mul_f32_e32 v16, v12, v35
	v_fma_f32 v33, -v32, v16, v12
	v_fmac_f32_e32 v16, v33, v35
	v_fma_f32 v12, -v32, v16, v12
	v_div_fmas_f32 v12, v12, v35, v16
	v_lshlrev_b32_e32 v16, 16, v13
	v_div_fixup_f32 v10, v12, v10, v31
	v_and_b32_e32 v31, 0xffff0000, v13
	v_mul_f32_e32 v13, 0xbfb8aa3b, v16
	v_exp_f32_e32 v32, v13
	v_mul_f32_e32 v13, 0xbfb8aa3b, v31
	v_exp_f32_e32 v33, v13
	v_lshlrev_b32_e32 v12, 16, v8
	v_and_b32_e32 v13, 0xffff0000, v8
	v_pk_fma_f32 v[10:11], v[14:15], v[10:11], v[12:13]
	v_lshlrev_b32_e32 v12, 16, v17
	v_cvt_pk_bf16_f32 v8, v10, v11
	v_pk_add_f32 v[10:11], v[32:33], 1.0 op_sel_hi:[1,0]
	v_and_b32_e32 v13, 0xffff0000, v17
	v_div_scale_f32 v14, s[0:1], v11, v11, v31
	v_rcp_f32_e32 v15, v14
	v_pk_mul_f32 v[12:13], v[28:29], v[12:13] op_sel_hi:[0,1]
	s_waitcnt lgkmcnt(0)
	v_and_b32_e32 v33, 0xffff0000, v2
	v_fma_f32 v17, -v14, v15, 1.0
	v_fmac_f32_e32 v15, v17, v15
	v_div_scale_f32 v17, vcc, v31, v11, v31
	v_mul_f32_e32 v28, v17, v15
	v_fma_f32 v32, -v14, v28, v17
	v_fmac_f32_e32 v28, v32, v15
	v_fma_f32 v14, -v14, v28, v17
	v_div_scale_f32 v17, s[0:1], v10, v10, v16
	v_rcp_f32_e32 v32, v17
	v_div_fmas_f32 v14, v14, v15, v28
	v_div_fixup_f32 v11, v14, v11, v31
	v_fma_f32 v14, -v17, v32, 1.0
	v_fmac_f32_e32 v32, v14, v32
	v_div_scale_f32 v14, vcc, v16, v10, v16
	v_mul_f32_e32 v15, v14, v32
	v_fma_f32 v28, -v17, v15, v14
	v_fmac_f32_e32 v15, v28, v32
	v_fma_f32 v14, -v17, v15, v14
	v_div_fmas_f32 v14, v14, v32, v15
	v_div_fixup_f32 v10, v14, v10, v16
	v_lshlrev_b32_e32 v14, 16, v9
	v_and_b32_e32 v15, 0xffff0000, v9
	v_pk_fma_f32 v[10:11], v[12:13], v[10:11], v[14:15]
	v_mov_b32_e32 v13, v1
	v_cvt_pk_bf16_f32 v9, v10, v11
	global_store_dwordx4 v[26:27], v[6:9], off
	v_mov_b32_e32 v17, v1
	v_lshlrev_b32_e32 v32, 16, v2
	v_add_u32_e32 v8, 12, v29
	v_ashrrev_i32_e32 v6, 3, v8
	v_ashrrev_i32_e32 v7, 31, v6
	v_lshl_add_u64 v[10:11], s[80:81], 0, v[6:7]
	v_and_or_b32 v16, v8, 7, s34
	v_mad_u64_u32 v[6:7], s[0:1], v10, s76, v[20:21]
	v_mad_i32_i24 v7, v11, s76, v7
	v_lshlrev_b32_e32 v12, 8, v16
	v_lshl_add_u64 v[6:7], v[6:7], 0, v[12:13]
	v_lshl_add_u64 v[6:7], v[6:7], 0, v[18:19]
	v_add_co_u32_e32 v6, vcc, s35, v6
	v_mad_u64_u32 v[14:15], s[0:1], v10, s77, v[22:23]
	s_nop 0
	v_addc_co_u32_e32 v7, vcc, 0, v7, vcc
	global_load_dwordx4 v[6:9], v[6:7], off
	v_mad_i32_i24 v15, v11, s77, v15
	v_lshlrev_b32_e32 v16, 2, v16
	v_lshl_add_u64 v[14:15], v[14:15], 0, v[16:17]
	global_load_dword v14, v[14:15], off offset:128
	v_lshlrev_b64 v[10:11], 13, v[10:11]
	v_lshl_add_u64 v[10:11], s[44:45], 0, v[10:11]
	v_lshl_add_u64 v[10:11], v[10:11], 0, v[12:13]
	v_lshl_add_u64 v[16:17], v[10:11], 0, v[18:19]
	global_load_dwordx4 v[10:13], v[16:17], off
	s_waitcnt vmcnt(2)
	v_lshlrev_b32_e32 v15, 16, v6
	v_and_b32_e32 v6, 0xffff0000, v6
	v_mul_f32_e32 v26, 0xbfb8aa3b, v15
	v_mul_f32_e32 v27, 0xbfb8aa3b, v6
	v_exp_f32_e32 v26, v26
	v_exp_f32_e32 v27, v27
	s_waitcnt vmcnt(1)
	v_pk_mul_f32 v[32:33], v[14:15], v[32:33] op_sel_hi:[0,1]
	v_pk_add_f32 v[26:27], v[26:27], 1.0 op_sel_hi:[1,0]
	s_nop 0
	v_div_scale_f32 v28, s[0:1], v27, v27, v6
	v_rcp_f32_e32 v31, v28
	s_nop 0
	v_fma_f32 v2, -v28, v31, 1.0
	v_fmac_f32_e32 v31, v2, v31
	v_div_scale_f32 v2, vcc, v6, v27, v6
	v_mul_f32_e32 v34, v2, v31
	v_fma_f32 v35, -v28, v34, v2
	v_fmac_f32_e32 v34, v35, v31
	v_fma_f32 v2, -v28, v34, v2
	v_div_scale_f32 v28, s[0:1], v26, v26, v15
	v_rcp_f32_e32 v35, v28
	v_div_fmas_f32 v2, v2, v31, v34
	v_div_fixup_f32 v27, v2, v27, v6
	v_fma_f32 v2, -v28, v35, 1.0
	v_fmac_f32_e32 v35, v2, v35
	v_div_scale_f32 v2, vcc, v15, v26, v15
	v_mul_f32_e32 v6, v2, v35
	v_fma_f32 v31, -v28, v6, v2
	v_fmac_f32_e32 v6, v31, v35
	v_fma_f32 v2, -v28, v6, v2
	v_div_fmas_f32 v2, v2, v35, v6
	v_div_fixup_f32 v26, v2, v26, v15
	v_lshlrev_b32_e32 v15, 16, v7
	v_and_b32_e32 v28, 0xffff0000, v7
	v_mul_f32_e32 v2, 0xbfb8aa3b, v15
	v_exp_f32_e32 v34, v2
	v_mul_f32_e32 v2, 0xbfb8aa3b, v28
	v_exp_f32_e32 v35, v2
	s_waitcnt vmcnt(0)
	v_lshlrev_b32_e32 v6, 16, v10
	v_and_b32_e32 v7, 0xffff0000, v10
	v_pk_fma_f32 v[6:7], v[32:33], v[26:27], v[6:7]
	v_lshlrev_b32_e32 v26, 16, v3
	v_cvt_pk_bf16_f32 v2, v6, v7
	v_pk_add_f32 v[6:7], v[34:35], 1.0 op_sel_hi:[1,0]
	v_and_b32_e32 v27, 0xffff0000, v3
	v_div_scale_f32 v10, s[0:1], v7, v7, v28
	v_rcp_f32_e32 v31, v10
	v_pk_mul_f32 v[26:27], v[14:15], v[26:27] op_sel_hi:[0,1]
	v_fma_f32 v3, -v10, v31, 1.0
	v_fmac_f32_e32 v31, v3, v31
	v_div_scale_f32 v3, vcc, v28, v7, v28
	v_mul_f32_e32 v32, v3, v31
	v_fma_f32 v33, -v10, v32, v3
	v_fmac_f32_e32 v32, v33, v31
	v_fma_f32 v3, -v10, v32, v3
	v_div_scale_f32 v10, s[0:1], v6, v6, v15
	v_rcp_f32_e32 v33, v10
	v_div_fmas_f32 v3, v3, v31, v32
	v_div_fixup_f32 v7, v3, v7, v28
	v_fma_f32 v3, -v10, v33, 1.0
	v_fmac_f32_e32 v33, v3, v33
	v_div_scale_f32 v3, vcc, v15, v6, v15
	v_mul_f32_e32 v28, v3, v33
	v_fma_f32 v31, -v10, v28, v3
	v_fmac_f32_e32 v28, v31, v33
	v_fma_f32 v3, -v10, v28, v3
	v_div_fmas_f32 v3, v3, v33, v28
	v_div_fixup_f32 v6, v3, v6, v15
	v_lshlrev_b32_e32 v15, 16, v8
	v_and_b32_e32 v8, 0xffff0000, v8
	v_mul_f32_e32 v3, 0xbfb8aa3b, v15
	v_exp_f32_e32 v32, v3
	v_mul_f32_e32 v3, 0xbfb8aa3b, v8
	v_exp_f32_e32 v33, v3
	v_lshlrev_b32_e32 v10, 16, v11
	v_and_b32_e32 v11, 0xffff0000, v11
	v_pk_fma_f32 v[6:7], v[26:27], v[6:7], v[10:11]
	v_lshlrev_b32_e32 v10, 16, v4
	v_cvt_pk_bf16_f32 v3, v6, v7
	v_pk_add_f32 v[6:7], v[32:33], 1.0 op_sel_hi:[1,0]
	v_and_b32_e32 v11, 0xffff0000, v4
	v_div_scale_f32 v26, s[0:1], v7, v7, v8
	v_rcp_f32_e32 v27, v26
	v_pk_mul_f32 v[10:11], v[14:15], v[10:11] op_sel_hi:[0,1]
	v_fma_f32 v4, -v26, v27, 1.0
	v_fmac_f32_e32 v27, v4, v27
	v_div_scale_f32 v4, vcc, v8, v7, v8
	v_mul_f32_e32 v28, v4, v27
	v_fma_f32 v31, -v26, v28, v4
	v_fmac_f32_e32 v28, v31, v27
	v_fma_f32 v4, -v26, v28, v4
	v_div_scale_f32 v26, s[0:1], v6, v6, v15
	v_rcp_f32_e32 v31, v26
	v_div_fmas_f32 v4, v4, v27, v28
	v_div_fixup_f32 v7, v4, v7, v8
	v_and_b32_e32 v28, 0xffff0000, v9
	v_fma_f32 v4, -v26, v31, 1.0
	v_fmac_f32_e32 v31, v4, v31
	v_div_scale_f32 v4, vcc, v15, v6, v15
	v_mul_f32_e32 v8, v4, v31
	v_fma_f32 v27, -v26, v8, v4
	v_fmac_f32_e32 v8, v27, v31
	v_fma_f32 v4, -v26, v8, v4
	v_div_fmas_f32 v4, v4, v31, v8
	v_div_fixup_f32 v6, v4, v6, v15
	v_lshlrev_b32_e32 v15, 16, v9
	v_mul_f32_e32 v4, 0xbfb8aa3b, v15
	v_exp_f32_e32 v26, v4
	v_mul_f32_e32 v4, 0xbfb8aa3b, v28
	v_exp_f32_e32 v27, v4
	v_lshlrev_b32_e32 v8, 16, v12
	v_and_b32_e32 v9, 0xffff0000, v12
	v_pk_fma_f32 v[6:7], v[10:11], v[6:7], v[8:9]
	v_lshlrev_b32_e32 v8, 16, v5
	v_cvt_pk_bf16_f32 v4, v6, v7
	v_pk_add_f32 v[6:7], v[26:27], 1.0 op_sel_hi:[1,0]
	v_and_b32_e32 v9, 0xffff0000, v5
	v_div_scale_f32 v10, s[0:1], v7, v7, v28
	v_rcp_f32_e32 v11, v10
	v_pk_mul_f32 v[8:9], v[14:15], v[8:9] op_sel_hi:[0,1]
	v_fma_f32 v5, -v10, v11, 1.0
	v_fmac_f32_e32 v11, v5, v11
	v_div_scale_f32 v5, vcc, v28, v7, v28
	v_mul_f32_e32 v12, v5, v11
	v_fma_f32 v14, -v10, v12, v5
	v_fmac_f32_e32 v12, v14, v11
	v_fma_f32 v5, -v10, v12, v5
	v_div_scale_f32 v10, s[0:1], v6, v6, v15
	v_rcp_f32_e32 v14, v10
	v_div_fmas_f32 v5, v5, v11, v12
	v_div_fixup_f32 v7, v5, v7, v28
	v_fma_f32 v5, -v10, v14, 1.0
	v_fmac_f32_e32 v14, v5, v14
	v_div_scale_f32 v5, vcc, v15, v6, v15
	v_mul_f32_e32 v11, v5, v14
	v_fma_f32 v12, -v10, v11, v5
	v_fmac_f32_e32 v11, v12, v14
	v_fma_f32 v5, -v10, v11, v5
	v_div_fmas_f32 v5, v5, v14, v11
	v_div_fixup_f32 v6, v5, v6, v15
	v_lshlrev_b32_e32 v10, 16, v13
	v_and_b32_e32 v11, 0xffff0000, v13
	v_pk_fma_f32 v[6:7], v[8:9], v[6:7], v[10:11]
	s_nop 0
	v_cvt_pk_bf16_f32 v5, v6, v7
	global_store_dwordx4 v[16:17], v[2:5], off
	ds_read_b128 v[14:17], v30 offset:4352
	s_nop 0
	v_add_u32_e32 v2, 16, v29
	v_ashrrev_i32_e32 v2, 3, v2
	v_ashrrev_i32_e32 v3, 31, v2
	v_lshl_add_u64 v[2:3], s[80:81], 0, v[2:3]
	v_mad_u64_u32 v[4:5], s[0:1], v2, s76, v[20:21]
	v_mad_i32_i24 v5, v3, s76, v5
	v_lshl_add_u64 v[4:5], v[4:5], 0, v[0:1]
	v_lshl_add_u64 v[4:5], v[4:5], 0, v[18:19]
	v_add_co_u32_e32 v4, vcc, s35, v4
	s_nop 1
	v_addc_co_u32_e32 v5, vcc, 0, v5, vcc
	global_load_dwordx4 v[10:13], v[4:5], off
	v_mad_u64_u32 v[4:5], s[0:1], v2, s77, v[22:23]
	v_mad_i32_i24 v5, v3, s77, v5
	v_lshlrev_b64 v[2:3], 13, v[2:3]
	v_lshl_add_u64 v[2:3], s[44:45], 0, v[2:3]
	v_lshl_add_u64 v[2:3], v[2:3], 0, v[0:1]
	v_lshl_add_u64 v[4:5], v[4:5], 0, v[24:25]
	v_lshl_add_u64 v[26:27], v[2:3], 0, v[18:19]
	global_load_dword v28, v[4:5], off offset:128
	global_load_dwordx4 v[6:9], v[26:27], off
	s_waitcnt vmcnt(2)
	v_lshlrev_b32_e32 v31, 16, v10
	v_and_b32_e32 v10, 0xffff0000, v10
	v_mul_f32_e32 v2, 0xbfb8aa3b, v31
	v_mul_f32_e32 v3, 0xbfb8aa3b, v10
	v_exp_f32_e32 v2, v2
	v_exp_f32_e32 v3, v3
	s_nop 0
	v_pk_add_f32 v[32:33], v[2:3], 1.0 op_sel_hi:[1,0]
	s_nop 0
	v_div_scale_f32 v36, s[0:1], v33, v33, v10
	v_rcp_f32_e32 v37, v36
	ds_read_b128 v[2:5], v30 offset:5440
	s_waitcnt lgkmcnt(1)
	v_lshlrev_b32_e32 v34, 16, v14
	v_and_b32_e32 v35, 0xffff0000, v14
	v_fma_f32 v14, -v36, v37, 1.0
	v_fmac_f32_e32 v37, v14, v37
	v_div_scale_f32 v14, vcc, v10, v33, v10
	v_mul_f32_e32 v38, v14, v37
	v_fma_f32 v39, -v36, v38, v14
	v_fmac_f32_e32 v38, v39, v37
	v_fma_f32 v14, -v36, v38, v14
	v_div_scale_f32 v36, s[0:1], v32, v32, v31
	v_rcp_f32_e32 v39, v36
	v_div_fmas_f32 v14, v14, v37, v38
	v_div_fixup_f32 v33, v14, v33, v10
	v_and_b32_e32 v38, 0xffff0000, v11
	v_fma_f32 v10, -v36, v39, 1.0
	v_fmac_f32_e32 v39, v10, v39
	v_div_scale_f32 v10, vcc, v31, v32, v31
	v_mul_f32_e32 v14, v10, v39
	v_fma_f32 v37, -v36, v14, v10
	v_fmac_f32_e32 v14, v37, v39
	v_fma_f32 v10, -v36, v14, v10
	v_div_fmas_f32 v10, v10, v39, v14
	v_div_fixup_f32 v32, v10, v32, v31
	v_lshlrev_b32_e32 v31, 16, v11
	v_mul_f32_e32 v11, 0xbfb8aa3b, v31
	v_exp_f32_e32 v36, v11
	v_mul_f32_e32 v11, 0xbfb8aa3b, v38
	v_exp_f32_e32 v37, v11
	s_waitcnt vmcnt(1)
	v_pk_mul_f32 v[34:35], v[28:29], v[34:35] op_sel_hi:[0,1]
	s_waitcnt vmcnt(0)
	v_lshlrev_b32_e32 v10, 16, v6
	v_and_b32_e32 v11, 0xffff0000, v6
	v_pk_fma_f32 v[10:11], v[34:35], v[32:33], v[10:11]
	v_lshlrev_b32_e32 v14, 16, v15
	v_cvt_pk_bf16_f32 v6, v10, v11
	v_pk_add_f32 v[10:11], v[36:37], 1.0 op_sel_hi:[1,0]
	v_and_b32_e32 v15, 0xffff0000, v15
	v_div_scale_f32 v32, s[0:1], v11, v11, v38
	v_rcp_f32_e32 v33, v32
	v_pk_mul_f32 v[14:15], v[28:29], v[14:15] op_sel_hi:[0,1]
	v_fma_f32 v34, -v32, v33, 1.0
	v_fmac_f32_e32 v33, v34, v33
	v_div_scale_f32 v34, vcc, v38, v11, v38
	v_mul_f32_e32 v35, v34, v33
	v_fma_f32 v36, -v32, v35, v34
	v_fmac_f32_e32 v35, v36, v33
	v_fma_f32 v32, -v32, v35, v34
	v_div_scale_f32 v34, s[0:1], v10, v10, v31
	v_rcp_f32_e32 v36, v34
	v_div_fmas_f32 v32, v32, v33, v35
	v_div_fixup_f32 v11, v32, v11, v38
	v_fma_f32 v32, -v34, v36, 1.0
	v_fmac_f32_e32 v36, v32, v36
	v_div_scale_f32 v32, vcc, v31, v10, v31
	v_mul_f32_e32 v33, v32, v36
	v_fma_f32 v35, -v34, v33, v32
	v_fmac_f32_e32 v33, v35, v36
	v_fma_f32 v32, -v34, v33, v32
	v_div_fmas_f32 v32, v32, v36, v33
	v_div_fixup_f32 v10, v32, v10, v31
	v_lshlrev_b32_e32 v31, 16, v12
	v_and_b32_e32 v12, 0xffff0000, v12
	v_mul_f32_e32 v33, 0xbfb8aa3b, v31
	v_exp_f32_e32 v34, v33
	v_mul_f32_e32 v33, 0xbfb8aa3b, v12
	v_exp_f32_e32 v35, v33
	v_lshlrev_b32_e32 v32, 16, v7
	v_and_b32_e32 v33, 0xffff0000, v7
	v_pk_fma_f32 v[10:11], v[14:15], v[10:11], v[32:33]
	v_lshlrev_b32_e32 v14, 16, v16
	v_cvt_pk_bf16_f32 v7, v10, v11
	v_pk_add_f32 v[10:11], v[34:35], 1.0 op_sel_hi:[1,0]
	v_and_b32_e32 v15, 0xffff0000, v16
	v_div_scale_f32 v32, s[0:1], v11, v11, v12
	v_rcp_f32_e32 v33, v32
	v_pk_mul_f32 v[14:15], v[28:29], v[14:15] op_sel_hi:[0,1]
	v_fma_f32 v16, -v32, v33, 1.0
	v_fmac_f32_e32 v33, v16, v33
	v_div_scale_f32 v16, vcc, v12, v11, v12
	v_mul_f32_e32 v34, v16, v33
	v_fma_f32 v35, -v32, v34, v16
	v_fmac_f32_e32 v34, v35, v33
	v_fma_f32 v16, -v32, v34, v16
	v_div_scale_f32 v32, s[0:1], v10, v10, v31
	v_rcp_f32_e32 v35, v32
	v_div_fmas_f32 v16, v16, v33, v34
	v_div_fixup_f32 v11, v16, v11, v12
	v_fma_f32 v12, -v32, v35, 1.0
	v_fmac_f32_e32 v35, v12, v35
	v_div_scale_f32 v12, vcc, v31, v10, v31
	v_mul_f32_e32 v16, v12, v35
	v_fma_f32 v33, -v32, v16, v12
	v_fmac_f32_e32 v16, v33, v35
	v_fma_f32 v12, -v32, v16, v12
	v_div_fmas_f32 v12, v12, v35, v16
	v_lshlrev_b32_e32 v16, 16, v13
	v_div_fixup_f32 v10, v12, v10, v31
	v_and_b32_e32 v31, 0xffff0000, v13
	v_mul_f32_e32 v13, 0xbfb8aa3b, v16
	v_exp_f32_e32 v32, v13
	v_mul_f32_e32 v13, 0xbfb8aa3b, v31
	v_exp_f32_e32 v33, v13
	v_lshlrev_b32_e32 v12, 16, v8
	v_and_b32_e32 v13, 0xffff0000, v8
	v_pk_fma_f32 v[10:11], v[14:15], v[10:11], v[12:13]
	v_lshlrev_b32_e32 v12, 16, v17
	v_cvt_pk_bf16_f32 v8, v10, v11
	v_pk_add_f32 v[10:11], v[32:33], 1.0 op_sel_hi:[1,0]
	v_and_b32_e32 v13, 0xffff0000, v17
	v_div_scale_f32 v14, s[0:1], v11, v11, v31
	v_rcp_f32_e32 v15, v14
	v_pk_mul_f32 v[12:13], v[28:29], v[12:13] op_sel_hi:[0,1]
	s_waitcnt lgkmcnt(0)
	v_and_b32_e32 v33, 0xffff0000, v2
	v_fma_f32 v17, -v14, v15, 1.0
	v_fmac_f32_e32 v15, v17, v15
	v_div_scale_f32 v17, vcc, v31, v11, v31
	v_mul_f32_e32 v28, v17, v15
	v_fma_f32 v32, -v14, v28, v17
	v_fmac_f32_e32 v28, v32, v15
	v_fma_f32 v14, -v14, v28, v17
	v_div_scale_f32 v17, s[0:1], v10, v10, v16
	v_rcp_f32_e32 v32, v17
	v_div_fmas_f32 v14, v14, v15, v28
	v_div_fixup_f32 v11, v14, v11, v31
	v_fma_f32 v14, -v17, v32, 1.0
	v_fmac_f32_e32 v32, v14, v32
	v_div_scale_f32 v14, vcc, v16, v10, v16
	v_mul_f32_e32 v15, v14, v32
	v_fma_f32 v28, -v17, v15, v14
	v_fmac_f32_e32 v15, v28, v32
	v_fma_f32 v14, -v17, v15, v14
	v_div_fmas_f32 v14, v14, v32, v15
	v_div_fixup_f32 v10, v14, v10, v16
	v_lshlrev_b32_e32 v14, 16, v9
	v_and_b32_e32 v15, 0xffff0000, v9
	v_pk_fma_f32 v[10:11], v[12:13], v[10:11], v[14:15]
	v_mov_b32_e32 v13, v1
	v_cvt_pk_bf16_f32 v9, v10, v11
	global_store_dwordx4 v[26:27], v[6:9], off
	v_mov_b32_e32 v17, v1
	v_lshlrev_b32_e32 v32, 16, v2
	v_add_u32_e32 v8, 20, v29
	v_ashrrev_i32_e32 v6, 3, v8
	v_ashrrev_i32_e32 v7, 31, v6
	v_lshl_add_u64 v[10:11], s[80:81], 0, v[6:7]
	v_and_or_b32 v16, v8, 7, s34
	v_mad_u64_u32 v[6:7], s[0:1], v10, s76, v[20:21]
	v_mad_i32_i24 v7, v11, s76, v7
	v_lshlrev_b32_e32 v12, 8, v16
	v_lshl_add_u64 v[6:7], v[6:7], 0, v[12:13]
	v_lshl_add_u64 v[6:7], v[6:7], 0, v[18:19]
	v_add_co_u32_e32 v6, vcc, s35, v6
	v_mad_u64_u32 v[14:15], s[0:1], v10, s77, v[22:23]
	s_nop 0
	v_addc_co_u32_e32 v7, vcc, 0, v7, vcc
	global_load_dwordx4 v[6:9], v[6:7], off
	v_mad_i32_i24 v15, v11, s77, v15
	v_lshlrev_b32_e32 v16, 2, v16
	v_lshl_add_u64 v[14:15], v[14:15], 0, v[16:17]
	global_load_dword v14, v[14:15], off offset:128
	v_lshlrev_b64 v[10:11], 13, v[10:11]
	v_lshl_add_u64 v[10:11], s[44:45], 0, v[10:11]
	v_lshl_add_u64 v[10:11], v[10:11], 0, v[12:13]
	v_lshl_add_u64 v[16:17], v[10:11], 0, v[18:19]
	global_load_dwordx4 v[10:13], v[16:17], off
	s_waitcnt vmcnt(2)
	v_lshlrev_b32_e32 v15, 16, v6
	v_and_b32_e32 v6, 0xffff0000, v6
	v_mul_f32_e32 v26, 0xbfb8aa3b, v15
	v_mul_f32_e32 v27, 0xbfb8aa3b, v6
	v_exp_f32_e32 v26, v26
	v_exp_f32_e32 v27, v27
	s_waitcnt vmcnt(1)
	v_pk_mul_f32 v[32:33], v[14:15], v[32:33] op_sel_hi:[0,1]
	v_pk_add_f32 v[26:27], v[26:27], 1.0 op_sel_hi:[1,0]
	s_nop 0
	v_div_scale_f32 v28, s[0:1], v27, v27, v6
	v_rcp_f32_e32 v31, v28
	s_nop 0
	v_fma_f32 v2, -v28, v31, 1.0
	v_fmac_f32_e32 v31, v2, v31
	v_div_scale_f32 v2, vcc, v6, v27, v6
	v_mul_f32_e32 v34, v2, v31
	v_fma_f32 v35, -v28, v34, v2
	v_fmac_f32_e32 v34, v35, v31
	v_fma_f32 v2, -v28, v34, v2
	v_div_scale_f32 v28, s[0:1], v26, v26, v15
	v_rcp_f32_e32 v35, v28
	v_div_fmas_f32 v2, v2, v31, v34
	v_div_fixup_f32 v27, v2, v27, v6
	v_fma_f32 v2, -v28, v35, 1.0
	v_fmac_f32_e32 v35, v2, v35
	v_div_scale_f32 v2, vcc, v15, v26, v15
	v_mul_f32_e32 v6, v2, v35
	v_fma_f32 v31, -v28, v6, v2
	v_fmac_f32_e32 v6, v31, v35
	v_fma_f32 v2, -v28, v6, v2
	v_div_fmas_f32 v2, v2, v35, v6
	v_div_fixup_f32 v26, v2, v26, v15
	v_lshlrev_b32_e32 v15, 16, v7
	v_and_b32_e32 v28, 0xffff0000, v7
	v_mul_f32_e32 v2, 0xbfb8aa3b, v15
	v_exp_f32_e32 v34, v2
	v_mul_f32_e32 v2, 0xbfb8aa3b, v28
	v_exp_f32_e32 v35, v2
	s_waitcnt vmcnt(0)
	v_lshlrev_b32_e32 v6, 16, v10
	v_and_b32_e32 v7, 0xffff0000, v10
	v_pk_fma_f32 v[6:7], v[32:33], v[26:27], v[6:7]
	v_lshlrev_b32_e32 v26, 16, v3
	v_cvt_pk_bf16_f32 v2, v6, v7
	v_pk_add_f32 v[6:7], v[34:35], 1.0 op_sel_hi:[1,0]
	v_and_b32_e32 v27, 0xffff0000, v3
	v_div_scale_f32 v10, s[0:1], v7, v7, v28
	v_rcp_f32_e32 v31, v10
	v_pk_mul_f32 v[26:27], v[14:15], v[26:27] op_sel_hi:[0,1]
	v_fma_f32 v3, -v10, v31, 1.0
	v_fmac_f32_e32 v31, v3, v31
	v_div_scale_f32 v3, vcc, v28, v7, v28
	v_mul_f32_e32 v32, v3, v31
	v_fma_f32 v33, -v10, v32, v3
	v_fmac_f32_e32 v32, v33, v31
	v_fma_f32 v3, -v10, v32, v3
	v_div_scale_f32 v10, s[0:1], v6, v6, v15
	v_rcp_f32_e32 v33, v10
	v_div_fmas_f32 v3, v3, v31, v32
	v_div_fixup_f32 v7, v3, v7, v28
	v_fma_f32 v3, -v10, v33, 1.0
	v_fmac_f32_e32 v33, v3, v33
	v_div_scale_f32 v3, vcc, v15, v6, v15
	v_mul_f32_e32 v28, v3, v33
	v_fma_f32 v31, -v10, v28, v3
	v_fmac_f32_e32 v28, v31, v33
	v_fma_f32 v3, -v10, v28, v3
	v_div_fmas_f32 v3, v3, v33, v28
	v_div_fixup_f32 v6, v3, v6, v15
	v_lshlrev_b32_e32 v15, 16, v8
	v_and_b32_e32 v8, 0xffff0000, v8
	v_mul_f32_e32 v3, 0xbfb8aa3b, v15
	v_exp_f32_e32 v32, v3
	v_mul_f32_e32 v3, 0xbfb8aa3b, v8
	v_exp_f32_e32 v33, v3
	v_lshlrev_b32_e32 v10, 16, v11
	v_and_b32_e32 v11, 0xffff0000, v11
	v_pk_fma_f32 v[6:7], v[26:27], v[6:7], v[10:11]
	v_lshlrev_b32_e32 v10, 16, v4
	v_cvt_pk_bf16_f32 v3, v6, v7
	v_pk_add_f32 v[6:7], v[32:33], 1.0 op_sel_hi:[1,0]
	v_and_b32_e32 v11, 0xffff0000, v4
	v_div_scale_f32 v26, s[0:1], v7, v7, v8
	v_rcp_f32_e32 v27, v26
	v_pk_mul_f32 v[10:11], v[14:15], v[10:11] op_sel_hi:[0,1]
	v_fma_f32 v4, -v26, v27, 1.0
	v_fmac_f32_e32 v27, v4, v27
	v_div_scale_f32 v4, vcc, v8, v7, v8
	v_mul_f32_e32 v28, v4, v27
	v_fma_f32 v31, -v26, v28, v4
	v_fmac_f32_e32 v28, v31, v27
	v_fma_f32 v4, -v26, v28, v4
	v_div_scale_f32 v26, s[0:1], v6, v6, v15
	v_rcp_f32_e32 v31, v26
	v_div_fmas_f32 v4, v4, v27, v28
	v_div_fixup_f32 v7, v4, v7, v8
	v_and_b32_e32 v28, 0xffff0000, v9
	v_fma_f32 v4, -v26, v31, 1.0
	v_fmac_f32_e32 v31, v4, v31
	v_div_scale_f32 v4, vcc, v15, v6, v15
	v_mul_f32_e32 v8, v4, v31
	v_fma_f32 v27, -v26, v8, v4
	v_fmac_f32_e32 v8, v27, v31
	v_fma_f32 v4, -v26, v8, v4
	v_div_fmas_f32 v4, v4, v31, v8
	v_div_fixup_f32 v6, v4, v6, v15
	v_lshlrev_b32_e32 v15, 16, v9
	v_mul_f32_e32 v4, 0xbfb8aa3b, v15
	v_exp_f32_e32 v26, v4
	v_mul_f32_e32 v4, 0xbfb8aa3b, v28
	v_exp_f32_e32 v27, v4
	v_lshlrev_b32_e32 v8, 16, v12
	v_and_b32_e32 v9, 0xffff0000, v12
	v_pk_fma_f32 v[6:7], v[10:11], v[6:7], v[8:9]
	v_lshlrev_b32_e32 v8, 16, v5
	v_cvt_pk_bf16_f32 v4, v6, v7
	v_pk_add_f32 v[6:7], v[26:27], 1.0 op_sel_hi:[1,0]
	v_and_b32_e32 v9, 0xffff0000, v5
	v_div_scale_f32 v10, s[0:1], v7, v7, v28
	v_rcp_f32_e32 v11, v10
	v_pk_mul_f32 v[8:9], v[14:15], v[8:9] op_sel_hi:[0,1]
	v_fma_f32 v5, -v10, v11, 1.0
	v_fmac_f32_e32 v11, v5, v11
	v_div_scale_f32 v5, vcc, v28, v7, v28
	v_mul_f32_e32 v12, v5, v11
	v_fma_f32 v14, -v10, v12, v5
	v_fmac_f32_e32 v12, v14, v11
	v_fma_f32 v5, -v10, v12, v5
	v_div_scale_f32 v10, s[0:1], v6, v6, v15
	v_rcp_f32_e32 v14, v10
	v_div_fmas_f32 v5, v5, v11, v12
	v_div_fixup_f32 v7, v5, v7, v28
	v_fma_f32 v5, -v10, v14, 1.0
	v_fmac_f32_e32 v14, v5, v14
	v_div_scale_f32 v5, vcc, v15, v6, v15
	v_mul_f32_e32 v11, v5, v14
	v_fma_f32 v12, -v10, v11, v5
	v_fmac_f32_e32 v11, v12, v14
	v_fma_f32 v5, -v10, v11, v5
	v_div_fmas_f32 v5, v5, v14, v11
	v_div_fixup_f32 v6, v5, v6, v15
	v_lshlrev_b32_e32 v10, 16, v13
	v_and_b32_e32 v11, 0xffff0000, v13
	v_pk_fma_f32 v[6:7], v[8:9], v[6:7], v[10:11]
	s_nop 0
	v_cvt_pk_bf16_f32 v5, v6, v7
	global_store_dwordx4 v[16:17], v[2:5], off
	ds_read_b128 v[14:17], v30 offset:6528
	s_nop 0
	v_add_u32_e32 v2, 24, v29
	v_ashrrev_i32_e32 v2, 3, v2
	v_ashrrev_i32_e32 v3, 31, v2
	v_lshl_add_u64 v[2:3], s[80:81], 0, v[2:3]
	v_mad_u64_u32 v[4:5], s[0:1], v2, s76, v[20:21]
	v_mad_i32_i24 v5, v3, s76, v5
	v_lshl_add_u64 v[4:5], v[4:5], 0, v[0:1]
	v_lshl_add_u64 v[4:5], v[4:5], 0, v[18:19]
	v_add_co_u32_e32 v4, vcc, s35, v4
	s_nop 1
	v_addc_co_u32_e32 v5, vcc, 0, v5, vcc
	global_load_dwordx4 v[10:13], v[4:5], off
	v_mad_u64_u32 v[4:5], s[0:1], v2, s77, v[22:23]
	v_mad_i32_i24 v5, v3, s77, v5
	v_lshl_add_u64 v[4:5], v[4:5], 0, v[24:25]
	global_load_dword v26, v[4:5], off offset:128
	v_lshlrev_b64 v[2:3], 13, v[2:3]
	v_lshl_add_u64 v[2:3], s[44:45], 0, v[2:3]
	v_lshl_add_u64 v[2:3], v[2:3], 0, v[0:1]
	v_lshl_add_u64 v[24:25], v[2:3], 0, v[18:19]
	global_load_dwordx4 v[6:9], v[24:25], off
	s_waitcnt vmcnt(2)
	v_lshlrev_b32_e32 v0, 16, v10
	v_and_b32_e32 v10, 0xffff0000, v10
	v_mul_f32_e32 v2, 0xbfb8aa3b, v0
	v_mul_f32_e32 v3, 0xbfb8aa3b, v10
	v_exp_f32_e32 v2, v2
	v_exp_f32_e32 v3, v3
	s_nop 0
	v_pk_add_f32 v[32:33], v[2:3], 1.0 op_sel_hi:[1,0]
	s_nop 0
	v_div_scale_f32 v27, s[0:1], v33, v33, v10
	v_rcp_f32_e32 v28, v27
	ds_read_b128 v[2:5], v30 offset:7616
	s_waitcnt lgkmcnt(1)
	v_lshlrev_b32_e32 v30, 16, v14
	v_and_b32_e32 v31, 0xffff0000, v14
	v_fma_f32 v14, -v27, v28, 1.0
	v_fmac_f32_e32 v28, v14, v28
	v_div_scale_f32 v14, vcc, v10, v33, v10
	v_mul_f32_e32 v34, v14, v28
	v_fma_f32 v35, -v27, v34, v14
	v_fmac_f32_e32 v34, v35, v28
	s_waitcnt vmcnt(1)
	v_pk_mul_f32 v[30:31], v[26:27], v[30:31] op_sel_hi:[0,1]
	v_fma_f32 v14, -v27, v34, v14
	v_div_scale_f32 v27, s[0:1], v32, v32, v0
	v_rcp_f32_e32 v35, v27
	v_div_fmas_f32 v14, v14, v28, v34
	v_div_fixup_f32 v33, v14, v33, v10
	v_fma_f32 v10, -v27, v35, 1.0
	v_fmac_f32_e32 v35, v10, v35
	v_div_scale_f32 v10, vcc, v0, v32, v0
	v_mul_f32_e32 v14, v10, v35
	v_fma_f32 v28, -v27, v14, v10
	v_fmac_f32_e32 v14, v28, v35
	v_fma_f32 v10, -v27, v14, v10
	v_div_fmas_f32 v10, v10, v35, v14
	v_div_fixup_f32 v32, v10, v32, v0
	v_lshlrev_b32_e32 v0, 16, v11
	v_and_b32_e32 v27, 0xffff0000, v11
	v_mul_f32_e32 v11, 0xbfb8aa3b, v0
	v_exp_f32_e32 v34, v11
	v_mul_f32_e32 v11, 0xbfb8aa3b, v27
	v_exp_f32_e32 v35, v11
	s_waitcnt vmcnt(0)
	v_lshlrev_b32_e32 v10, 16, v6
	v_and_b32_e32 v11, 0xffff0000, v6
	v_pk_fma_f32 v[10:11], v[30:31], v[32:33], v[10:11]
	v_lshlrev_b32_e32 v14, 16, v15
	v_cvt_pk_bf16_f32 v6, v10, v11
	v_pk_add_f32 v[10:11], v[34:35], 1.0 op_sel_hi:[1,0]
	v_and_b32_e32 v15, 0xffff0000, v15
	v_div_scale_f32 v28, s[0:1], v11, v11, v27
	v_rcp_f32_e32 v30, v28
	v_pk_mul_f32 v[14:15], v[26:27], v[14:15] op_sel_hi:[0,1]
	v_fma_f32 v31, -v28, v30, 1.0
	v_fmac_f32_e32 v30, v31, v30
	v_div_scale_f32 v31, vcc, v27, v11, v27
	v_mul_f32_e32 v32, v31, v30
	v_fma_f32 v33, -v28, v32, v31
	v_fmac_f32_e32 v32, v33, v30
	v_fma_f32 v28, -v28, v32, v31
	v_div_scale_f32 v31, s[0:1], v10, v10, v0
	v_rcp_f32_e32 v33, v31
	v_div_fmas_f32 v28, v28, v30, v32
	v_div_fixup_f32 v11, v28, v11, v27
	v_fma_f32 v27, -v31, v33, 1.0
	v_fmac_f32_e32 v33, v27, v33
	v_div_scale_f32 v27, vcc, v0, v10, v0
	v_mul_f32_e32 v28, v27, v33
	v_fma_f32 v30, -v31, v28, v27
	v_fmac_f32_e32 v28, v30, v33
	v_fma_f32 v27, -v31, v28, v27
	v_div_fmas_f32 v27, v27, v33, v28
	v_div_fixup_f32 v10, v27, v10, v0
	v_lshlrev_b32_e32 v0, 16, v12
	v_and_b32_e32 v12, 0xffff0000, v12
	v_mul_f32_e32 v27, 0xbfb8aa3b, v0
	v_exp_f32_e32 v32, v27
	v_mul_f32_e32 v27, 0xbfb8aa3b, v12
	v_exp_f32_e32 v33, v27
	v_lshlrev_b32_e32 v30, 16, v7
	v_and_b32_e32 v31, 0xffff0000, v7
	v_pk_fma_f32 v[10:11], v[14:15], v[10:11], v[30:31]
	v_lshlrev_b32_e32 v14, 16, v16
	v_cvt_pk_bf16_f32 v7, v10, v11
	v_pk_add_f32 v[10:11], v[32:33], 1.0 op_sel_hi:[1,0]
	v_and_b32_e32 v15, 0xffff0000, v16
	v_div_scale_f32 v27, s[0:1], v11, v11, v12
	v_rcp_f32_e32 v28, v27
	v_pk_mul_f32 v[14:15], v[26:27], v[14:15] op_sel_hi:[0,1]
	v_fma_f32 v16, -v27, v28, 1.0
	v_fmac_f32_e32 v28, v16, v28
	v_div_scale_f32 v16, vcc, v12, v11, v12
	v_mul_f32_e32 v30, v16, v28
	v_fma_f32 v31, -v27, v30, v16
	v_fmac_f32_e32 v30, v31, v28
	v_fma_f32 v16, -v27, v30, v16
	v_div_scale_f32 v27, s[0:1], v10, v10, v0
	v_rcp_f32_e32 v31, v27
	v_div_fmas_f32 v16, v16, v28, v30
	v_div_fixup_f32 v11, v16, v11, v12
	v_fma_f32 v12, -v27, v31, 1.0
	v_fmac_f32_e32 v31, v12, v31
	v_div_scale_f32 v12, vcc, v0, v10, v0
	v_mul_f32_e32 v16, v12, v31
	v_fma_f32 v28, -v27, v16, v12
	v_fmac_f32_e32 v16, v28, v31
	v_fma_f32 v12, -v27, v16, v12
	v_div_fmas_f32 v12, v12, v31, v16
	v_div_fixup_f32 v10, v12, v10, v0
	v_lshlrev_b32_e32 v0, 16, v13
	v_and_b32_e32 v16, 0xffff0000, v13
	v_mul_f32_e32 v13, 0xbfb8aa3b, v0
	v_exp_f32_e32 v30, v13
	v_mul_f32_e32 v13, 0xbfb8aa3b, v16
	v_exp_f32_e32 v31, v13
	v_lshlrev_b32_e32 v12, 16, v8
	v_and_b32_e32 v13, 0xffff0000, v8
	v_pk_fma_f32 v[10:11], v[14:15], v[10:11], v[12:13]
	v_lshlrev_b32_e32 v12, 16, v17
	v_cvt_pk_bf16_f32 v8, v10, v11
	v_pk_add_f32 v[10:11], v[30:31], 1.0 op_sel_hi:[1,0]
	v_and_b32_e32 v13, 0xffff0000, v17
	v_div_scale_f32 v14, s[0:1], v11, v11, v16
	v_rcp_f32_e32 v15, v14
	v_pk_mul_f32 v[12:13], v[26:27], v[12:13] op_sel_hi:[0,1]
	v_fma_f32 v17, -v14, v15, 1.0
	v_fmac_f32_e32 v15, v17, v15
	v_div_scale_f32 v17, vcc, v16, v11, v16
	v_mul_f32_e32 v26, v17, v15
	v_fma_f32 v27, -v14, v26, v17
	v_fmac_f32_e32 v26, v27, v15
	v_fma_f32 v14, -v14, v26, v17
	v_div_scale_f32 v17, s[0:1], v10, v10, v0
	v_rcp_f32_e32 v27, v17
	v_div_fmas_f32 v14, v14, v15, v26
	v_div_fixup_f32 v11, v14, v11, v16
	v_fma_f32 v14, -v17, v27, 1.0
	v_fmac_f32_e32 v27, v14, v27
	v_div_scale_f32 v14, vcc, v0, v10, v0
	v_mul_f32_e32 v15, v14, v27
	v_fma_f32 v16, -v17, v15, v14
	v_fmac_f32_e32 v15, v16, v27
	v_fma_f32 v14, -v17, v15, v14
	v_div_fmas_f32 v14, v14, v27, v15
	v_div_fixup_f32 v10, v14, v10, v0
	v_lshlrev_b32_e32 v14, 16, v9
	v_and_b32_e32 v15, 0xffff0000, v9
	v_pk_fma_f32 v[10:11], v[12:13], v[10:11], v[14:15]
	v_add_u32_e32 v0, 28, v29
	v_cvt_pk_bf16_f32 v9, v10, v11
	global_store_dwordx4 v[24:25], v[6:9], off
	v_and_or_b32 v14, v0, 7, s34
	v_mov_b32_e32 v15, v1
	v_ashrrev_i32_e32 v6, 3, v0
	v_ashrrev_i32_e32 v7, 31, v6
	v_lshl_add_u64 v[10:11], s[80:81], 0, v[6:7]
	v_mad_u64_u32 v[6:7], s[0:1], v10, s76, v[20:21]
	v_mad_i32_i24 v7, v11, s76, v7
	v_lshlrev_b32_e32 v0, 8, v14
	v_lshl_add_u64 v[6:7], v[6:7], 0, v[0:1]
	v_lshl_add_u64 v[6:7], v[6:7], 0, v[18:19]
	v_add_co_u32_e32 v6, vcc, s35, v6
	v_mad_u64_u32 v[12:13], s[0:1], v10, s77, v[22:23]
	s_nop 0
	v_addc_co_u32_e32 v7, vcc, 0, v7, vcc
	global_load_dwordx4 v[6:9], v[6:7], off
	v_mad_i32_i24 v13, v11, s77, v13
	v_lshlrev_b32_e32 v14, 2, v14
	v_lshl_add_u64 v[12:13], v[12:13], 0, v[14:15]
	global_load_dword v14, v[12:13], off offset:128
	v_lshlrev_b64 v[10:11], 13, v[10:11]
	v_lshl_add_u64 v[10:11], s[44:45], 0, v[10:11]
	v_lshl_add_u64 v[10:11], v[10:11], 0, v[0:1]
	v_lshl_add_u64 v[16:17], v[10:11], 0, v[18:19]
	global_load_dwordx4 v[10:13], v[16:17], off
	s_waitcnt lgkmcnt(0)
	v_lshlrev_b32_e32 v20, 16, v2
	v_and_b32_e32 v21, 0xffff0000, v2
	s_waitcnt vmcnt(2)
	v_lshlrev_b32_e32 v0, 16, v6
	v_and_b32_e32 v6, 0xffff0000, v6
	v_mul_f32_e32 v15, 0xbfb8aa3b, v0
	v_exp_f32_e32 v18, v15
	v_mul_f32_e32 v15, 0xbfb8aa3b, v6
	v_exp_f32_e32 v19, v15
	s_nop 0
	v_pk_add_f32 v[18:19], v[18:19], 1.0 op_sel_hi:[1,0]
	s_nop 0
	v_div_scale_f32 v15, s[0:1], v19, v19, v6
	v_rcp_f32_e32 v22, v15
	s_waitcnt vmcnt(1)
	v_pk_mul_f32 v[20:21], v[14:15], v[20:21] op_sel_hi:[0,1]
	v_fma_f32 v2, -v15, v22, 1.0
	v_fmac_f32_e32 v22, v2, v22
	v_div_scale_f32 v2, vcc, v6, v19, v6
	v_mul_f32_e32 v23, v2, v22
	v_fma_f32 v24, -v15, v23, v2
	v_fmac_f32_e32 v23, v24, v22
	v_fma_f32 v2, -v15, v23, v2
	v_div_scale_f32 v15, s[0:1], v18, v18, v0
	v_rcp_f32_e32 v24, v15
	v_div_fmas_f32 v2, v2, v22, v23
	v_div_fixup_f32 v19, v2, v19, v6
	v_fma_f32 v2, -v15, v24, 1.0
	v_fmac_f32_e32 v24, v2, v24
	v_div_scale_f32 v2, vcc, v0, v18, v0
	v_mul_f32_e32 v6, v2, v24
	v_fma_f32 v22, -v15, v6, v2
	v_fmac_f32_e32 v6, v22, v24
	v_fma_f32 v2, -v15, v6, v2
	v_div_fmas_f32 v2, v2, v24, v6
	v_div_fixup_f32 v18, v2, v18, v0
	v_lshlrev_b32_e32 v0, 16, v7
	v_and_b32_e32 v15, 0xffff0000, v7
	v_mul_f32_e32 v2, 0xbfb8aa3b, v0
	v_exp_f32_e32 v22, v2
	v_mul_f32_e32 v2, 0xbfb8aa3b, v15
	v_exp_f32_e32 v23, v2
	s_waitcnt vmcnt(0)
	v_lshlrev_b32_e32 v6, 16, v10
	v_and_b32_e32 v7, 0xffff0000, v10
	v_pk_fma_f32 v[6:7], v[20:21], v[18:19], v[6:7]
	v_lshlrev_b32_e32 v18, 16, v3
	v_cvt_pk_bf16_f32 v2, v6, v7
	v_pk_add_f32 v[6:7], v[22:23], 1.0 op_sel_hi:[1,0]
	v_and_b32_e32 v19, 0xffff0000, v3
	v_div_scale_f32 v10, s[0:1], v7, v7, v15
	v_rcp_f32_e32 v20, v10
	v_pk_mul_f32 v[18:19], v[14:15], v[18:19] op_sel_hi:[0,1]
	v_fma_f32 v3, -v10, v20, 1.0
	v_fmac_f32_e32 v20, v3, v20
	v_div_scale_f32 v3, vcc, v15, v7, v15
	v_mul_f32_e32 v21, v3, v20
	v_fma_f32 v22, -v10, v21, v3
	v_fmac_f32_e32 v21, v22, v20
	v_fma_f32 v3, -v10, v21, v3
	v_div_scale_f32 v10, s[0:1], v6, v6, v0
	v_rcp_f32_e32 v22, v10
	v_div_fmas_f32 v3, v3, v20, v21
	v_div_fixup_f32 v7, v3, v7, v15
	v_fma_f32 v3, -v10, v22, 1.0
	v_fmac_f32_e32 v22, v3, v22
	v_div_scale_f32 v3, vcc, v0, v6, v0
	v_mul_f32_e32 v15, v3, v22
	v_fma_f32 v20, -v10, v15, v3
	v_fmac_f32_e32 v15, v20, v22
	v_fma_f32 v3, -v10, v15, v3
	v_div_fmas_f32 v3, v3, v22, v15
	v_div_fixup_f32 v6, v3, v6, v0
	v_lshlrev_b32_e32 v0, 16, v8
	v_and_b32_e32 v8, 0xffff0000, v8
	v_mul_f32_e32 v3, 0xbfb8aa3b, v0
	v_exp_f32_e32 v20, v3
	v_mul_f32_e32 v3, 0xbfb8aa3b, v8
	v_exp_f32_e32 v21, v3
	v_lshlrev_b32_e32 v10, 16, v11
	v_and_b32_e32 v11, 0xffff0000, v11
	v_pk_fma_f32 v[6:7], v[18:19], v[6:7], v[10:11]
	v_lshlrev_b32_e32 v10, 16, v4
	v_cvt_pk_bf16_f32 v3, v6, v7
	v_pk_add_f32 v[6:7], v[20:21], 1.0 op_sel_hi:[1,0]
	v_and_b32_e32 v11, 0xffff0000, v4
	v_div_scale_f32 v15, s[0:1], v7, v7, v8
	v_rcp_f32_e32 v18, v15
	v_pk_mul_f32 v[10:11], v[14:15], v[10:11] op_sel_hi:[0,1]
	v_fma_f32 v4, -v15, v18, 1.0
	v_fmac_f32_e32 v18, v4, v18
	v_div_scale_f32 v4, vcc, v8, v7, v8
	v_mul_f32_e32 v19, v4, v18
	v_fma_f32 v20, -v15, v19, v4
	v_fmac_f32_e32 v19, v20, v18
	v_fma_f32 v4, -v15, v19, v4
	v_div_scale_f32 v15, s[0:1], v6, v6, v0
	v_rcp_f32_e32 v20, v15
	v_div_fmas_f32 v4, v4, v18, v19
	v_div_fixup_f32 v7, v4, v7, v8
	v_fma_f32 v4, -v15, v20, 1.0
	v_fmac_f32_e32 v20, v4, v20
	v_div_scale_f32 v4, vcc, v0, v6, v0
	v_mul_f32_e32 v8, v4, v20
	v_fma_f32 v18, -v15, v8, v4
	v_fmac_f32_e32 v8, v18, v20
	v_fma_f32 v4, -v15, v8, v4
	v_div_fmas_f32 v4, v4, v20, v8
	v_div_fixup_f32 v6, v4, v6, v0
	v_lshlrev_b32_e32 v0, 16, v9
	v_and_b32_e32 v15, 0xffff0000, v9
	v_mul_f32_e32 v4, 0xbfb8aa3b, v0
	v_exp_f32_e32 v18, v4
	v_mul_f32_e32 v4, 0xbfb8aa3b, v15
	v_exp_f32_e32 v19, v4
	v_lshlrev_b32_e32 v8, 16, v12
	v_and_b32_e32 v9, 0xffff0000, v12
	v_pk_fma_f32 v[6:7], v[10:11], v[6:7], v[8:9]
	v_lshlrev_b32_e32 v8, 16, v5
	v_cvt_pk_bf16_f32 v4, v6, v7
	v_pk_add_f32 v[6:7], v[18:19], 1.0 op_sel_hi:[1,0]
	v_and_b32_e32 v9, 0xffff0000, v5
	v_div_scale_f32 v10, s[0:1], v7, v7, v15
	v_rcp_f32_e32 v11, v10
	v_pk_mul_f32 v[8:9], v[14:15], v[8:9] op_sel_hi:[0,1]
	v_fma_f32 v5, -v10, v11, 1.0
	v_fmac_f32_e32 v11, v5, v11
	v_div_scale_f32 v5, vcc, v15, v7, v15
	v_mul_f32_e32 v12, v5, v11
	v_fma_f32 v14, -v10, v12, v5
	v_fmac_f32_e32 v12, v14, v11
	v_fma_f32 v5, -v10, v12, v5
	v_div_scale_f32 v10, s[0:1], v6, v6, v0
	v_rcp_f32_e32 v14, v10
	v_div_fmas_f32 v5, v5, v11, v12
	v_div_fixup_f32 v7, v5, v7, v15
	s_max_i32 s0, s67, 0x1ff
	v_fma_f32 v5, -v10, v14, 1.0
	v_fmac_f32_e32 v14, v5, v14
	v_div_scale_f32 v5, vcc, v0, v6, v0
	v_mul_f32_e32 v11, v5, v14
	v_fma_f32 v12, -v10, v11, v5
	v_fmac_f32_e32 v11, v12, v14
	v_fma_f32 v5, -v10, v11, v5
	v_div_fmas_f32 v5, v5, v14, v11
	s_addk_i32 s0, 0xfe01
	v_div_fixup_f32 v6, v5, v6, v0
	v_lshlrev_b32_e32 v10, 16, v13
	v_and_b32_e32 v11, 0xffff0000, v13
	s_lshr_b32 s12, s0, 6
	s_ashr_i32 s0, s31, 1
	v_pk_fma_f32 v[6:7], v[8:9], v[6:7], v[10:11]
	s_sub_i32 s14, s0, s12
	v_cvt_pk_bf16_f32 v5, v6, v7
	v_cmp_ge_i32_e32 vcc, s14, v176
	global_store_dwordx4 v[16:17], v[2:5], off
	s_barrier
	s_and_saveexec_b64 s[0:1], vcc
	v_add_u32_e32 v0, s12, v176
	ds_write_b32 v179, v0
	s_or_b64 exec, exec, s[0:1]
	v_mov_b32_e32 v79, 0
	s_cmp_lt_i32 s14, 0
	v_mov_b32_e32 v78, 0
	v_mov_b32_e32 v77, 0
	v_mov_b32_e32 v76, 0
	v_mov_b32_e32 v75, 0
	v_mov_b32_e32 v74, 0
	v_mov_b32_e32 v73, 0
	v_mov_b32_e32 v72, 0
	v_mov_b32_e32 v71, 0
	v_mov_b32_e32 v70, 0
	v_mov_b32_e32 v69, 0
	v_mov_b32_e32 v68, 0
	v_mov_b32_e32 v67, 0
	v_mov_b32_e32 v66, 0
	v_mov_b32_e32 v65, 0
	v_mov_b32_e32 v64, 0
	v_mov_b32_e32 v63, 0
	v_mov_b32_e32 v62, 0
	v_mov_b32_e32 v61, 0
	v_mov_b32_e32 v60, 0
	v_mov_b32_e32 v59, 0
	v_mov_b32_e32 v58, 0
	v_mov_b32_e32 v57, 0
	v_mov_b32_e32 v56, 0
	v_mov_b32_e32 v55, 0
	v_mov_b32_e32 v54, 0
	v_mov_b32_e32 v53, 0
	v_mov_b32_e32 v52, 0
	v_mov_b32_e32 v51, 0
	v_mov_b32_e32 v50, 0
	v_mov_b32_e32 v49, 0
	v_mov_b32_e32 v48, 0
	v_mov_b32_e32 v47, 0
	v_mov_b32_e32 v46, 0
	v_mov_b32_e32 v45, 0
	v_mov_b32_e32 v44, 0
	v_mov_b32_e32 v43, 0
	v_mov_b32_e32 v42, 0
	v_mov_b32_e32 v41, 0
	v_mov_b32_e32 v40, 0
	v_mov_b32_e32 v39, 0
	v_mov_b32_e32 v38, 0
	v_mov_b32_e32 v37, 0
	v_mov_b32_e32 v36, 0
	v_mov_b32_e32 v35, 0
	v_mov_b32_e32 v34, 0
	v_mov_b32_e32 v33, 0
	v_mov_b32_e32 v32, 0
	v_mov_b32_e32 v31, 0
	v_mov_b32_e32 v30, 0
	v_mov_b32_e32 v29, 0
	v_mov_b32_e32 v28, 0
	v_mov_b32_e32 v27, 0
	v_mov_b32_e32 v26, 0
	v_mov_b32_e32 v25, 0
	v_mov_b32_e32 v24, 0
	v_mov_b32_e32 v23, 0
	v_mov_b32_e32 v22, 0
	v_mov_b32_e32 v21, 0
	v_mov_b32_e32 v20, 0
	v_mov_b32_e32 v19, 0
	v_mov_b32_e32 v18, 0
	v_mov_b32_e32 v17, 0
	v_mov_b32_e32 v16, 0
	v_mov_b32_e32 v170, 0
	s_waitcnt lgkmcnt(0)
	s_barrier
	s_cbranch_scc1 .LBB0_1058
	v_mov_b32_e32 v0, s92
	ds_read_b32 v2, v0
	s_lshl_b64 s[0:1], s[20:21], 1
	v_readlane_b32 s12, v255, 24
	s_add_u32 s12, s12, s0
	v_readlane_b32 s13, v255, 25
	s_addc_u32 s13, s13, s1
	v_readlane_b32 s15, v255, 26
	s_add_u32 s0, s15, s0
	v_readlane_b32 s15, v255, 27
	s_waitcnt lgkmcnt(0)
	v_ashrrev_i32_e32 v3, 31, v2
	s_addc_u32 s1, s15, s1
	v_lshlrev_b64 v[4:5], 14, v[2:3]
	v_lshl_add_u64 v[4:5], s[0:1], 0, v[4:5]
	v_lshl_add_u64 v[4:5], v[4:5], 0, v[146:147]
	v_lshlrev_b64 v[2:3], 7, v[2:3]
	v_add_co_u32_e32 v6, vcc, s35, v4
	v_lshl_add_u64 v[2:3], s[12:13], 0, v[2:3]
	s_nop 0
	v_addc_co_u32_e32 v7, vcc, 0, v5, vcc
	v_lshl_add_u64 v[2:3], v[2:3], 0, v[162:163]
	s_mov_b32 s15, 0x80000
	global_load_dwordx4 v[64:67], v[4:5], off
	global_load_dwordx4 v[68:71], v[6:7], off
	v_add_co_u32_e32 v4, vcc, s15, v2
	v_mov_b32_e32 v14, v1
	s_nop 0
	v_addc_co_u32_e32 v5, vcc, 0, v3, vcc
	global_load_dwordx4 v[72:75], v[2:3], off
	global_load_dwordx4 v[76:79], v[4:5], off
	v_mov_b32_e32 v15, v1
	v_mov_b32_e32 v0, v1
	v_mov_b32_e32 v2, v1
	v_mov_b32_e32 v3, v1
	v_mov_b32_e32 v4, v1
	v_mov_b32_e32 v5, v1
	v_mov_b32_e32 v6, v1
	v_mov_b32_e32 v7, v1
	v_mov_b32_e32 v8, v1
	v_mov_b32_e32 v9, v1
	v_mov_b32_e32 v10, v1
	v_mov_b32_e32 v11, v1
	v_mov_b32_e32 v12, v1
	v_mov_b32_e32 v13, v1
	v_mov_b64_e32 v[30:31], v[14:15]
	v_mov_b64_e32 v[46:47], v[14:15]
	v_mov_b64_e32 v[62:63], v[14:15]
	s_mov_b32 s15, 0
	v_sub_u32_e32 v171, v221, v168
	v_mov_b32_e32 v170, 0
	v_mov_b32_e32 v142, 0xf149f2ca
	v_mov_b32_e32 v130, 0
	v_mov_b32_e32 v131, 0
	v_mov_b32_e32 v132, 0
	v_mov_b32_e32 v133, 0
	v_mov_b32_e32 v134, 0
	v_mov_b32_e32 v135, 0
	v_mov_b32_e32 v136, 0
	v_mov_b32_e32 v137, 0
	v_mov_b64_e32 v[28:29], v[12:13]
	v_mov_b64_e32 v[26:27], v[10:11]
	v_mov_b64_e32 v[24:25], v[8:9]
	v_mov_b64_e32 v[22:23], v[6:7]
	v_mov_b64_e32 v[20:21], v[4:5]
	v_mov_b64_e32 v[18:19], v[2:3]
	v_mov_b64_e32 v[16:17], v[0:1]
	v_mov_b64_e32 v[44:45], v[12:13]
	v_mov_b64_e32 v[42:43], v[10:11]
	v_mov_b64_e32 v[40:41], v[8:9]
	v_mov_b64_e32 v[38:39], v[6:7]
	v_mov_b64_e32 v[36:37], v[4:5]
	v_mov_b64_e32 v[34:35], v[2:3]
	v_mov_b64_e32 v[32:33], v[0:1]
	v_mov_b64_e32 v[60:61], v[12:13]
	v_mov_b64_e32 v[58:59], v[10:11]
	v_mov_b64_e32 v[56:57], v[8:9]
	v_mov_b64_e32 v[54:55], v[6:7]
	v_mov_b64_e32 v[52:53], v[4:5]
	v_mov_b64_e32 v[50:51], v[2:3]
	v_mov_b64_e32 v[48:49], v[0:1]
	v_lshl_add_u64 v[96:97], s[12:13], 0, v[162:163]
	s_add_i32 s16, 0, 0x1bb04
	s_add_i32 s17, s14, 1
	v_lshl_add_u64 v[168:169], s[0:1], 0, v[146:147]
	s_waitcnt vmcnt(3)
	ds_write_b128 v225, v[64:67]
	s_waitcnt vmcnt(2)
	ds_write_b128 v225, v[68:71] offset:8704
	s_waitcnt vmcnt(1)
	ds_write2_b64 v167, v[72:73], v[74:75] offset0:128 offset1:130
	s_waitcnt vmcnt(0)
	ds_write2_b64 v232, v[76:77], v[78:79] offset1:2
	v_mov_b64_e32 v[78:79], v[14:15]
	v_mov_b64_e32 v[76:77], v[12:13]
	v_mov_b64_e32 v[74:75], v[10:11]
	v_mov_b64_e32 v[72:73], v[8:9]
	v_mov_b64_e32 v[70:71], v[6:7]
	v_mov_b64_e32 v[68:69], v[4:5]
	v_mov_b64_e32 v[66:67], v[2:3]
	v_mov_b64_e32 v[64:65], v[0:1]
	s_waitcnt lgkmcnt(0)
	s_barrier
	s_branch .LBB0_1234

.LBB0_1238:
	s_bitcmp1_b32 s15, 0
	s_cselect_b32 s0, 0x8c00, 0
	v_add_u32_e32 v245, s0, v219
	ds_read_b128 v[10:13], v245
	ds_read_b128 v[138:141], v245 offset:32
	v_add_u32_e32 v167, s0, v220
	v_lshl_add_u32 v172, v0, 6, v171
	s_waitcnt lgkmcnt(1)
	v_mfma_f32_32x32x16_bf16 v[80:95], v[10:13], v[122:125], 0
	s_waitcnt lgkmcnt(0)
	v_mfma_f32_32x32x16_bf16 v[80:95], v[138:141], v[126:129], v[80:95]
	ds_read_b128 v[10:13], v245 offset:64
	ds_read_b128 v[138:141], v245 offset:96
	s_waitcnt lgkmcnt(1)
	v_mfma_f32_32x32x16_bf16 v[80:95], v[10:13], v[98:101], v[80:95]
	ds_read_b128 v[10:13], v245 offset:128
	ds_read_b128 v[232:235], v245 offset:160
	ds_read_b128 v[236:239], v245 offset:192
	ds_read_b128 v[240:243], v245 offset:224
	s_waitcnt lgkmcnt(4)
	v_mfma_f32_32x32x16_bf16 v[80:95], v[138:141], v[102:105], v[80:95]
	s_waitcnt lgkmcnt(3)
	v_mfma_f32_32x32x16_bf16 v[80:95], v[10:13], v[106:109], v[80:95]
	s_movk_i32 s0, 0x200
	v_add_u32_e32 v0, 0xfffffe01, v172
	v_cmp_gt_u32_e32 vcc, s0, v172
	v_add_u32_e32 v145, 0xfffffe02, v172
	v_add_u32_e32 v173, 0xfffffe03, v172
	v_add_u32_e32 v174, 0xfffffe08, v172
	v_add_u32_e32 v175, 0xfffffe09, v172
	s_waitcnt lgkmcnt(2)
	v_mfma_f32_32x32x16_bf16 v[80:95], v[232:235], v[110:113], v[80:95]
	v_add_u32_e32 v208, 0xfffffe0a, v172
	v_add_u32_e32 v209, 0xfffffe0b, v172
	v_add_u32_e32 v210, 0xfffffe10, v172
	v_add_u32_e32 v211, 0xfffffe11, v172
	ds_read_b128 v[138:141], v167 offset:17408
	ds_read_b128 v[10:13], v167 offset:22016
	s_waitcnt lgkmcnt(3)
	v_mfma_f32_32x32x16_bf16 v[80:95], v[236:239], v[114:117], v[80:95]
	s_waitcnt lgkmcnt(2)
	v_mfma_f32_32x32x16_bf16 v[80:95], v[240:243], v[118:121], v[80:95]
	s_cmp_eq_u64 s[12:13], 0
	s_cselect_b32 s98, s15, 0
	s_cmp_lg_u32 s98, 0
	s_nop 8
	s_cbranch_scc0 .Lwinf0_slow
	v_mov_b32_e32 v143, v80
	v_max_f32_e32 v80, v143, v143
	v_mov_b32_e32 v144, v81
	v_mov_b32_e32 v145, v82
	v_mov_b32_e32 v232, v83
	v_mov_b32_e32 v233, v84
	v_mov_b32_e32 v234, v85
	v_mov_b32_e32 v235, v86
	v_mov_b32_e32 v236, v87
	v_max_f32_e32 v0, v144, v144
	v_max_f32_e32 v0, v80, v0
	v_max3_f32 v0, v0, v145, v232
	v_max3_f32 v0, v0, v233, v234
	v_max3_f32 v0, v0, v235, v236
	v_max3_f32 v0, v0, v88, v89
	v_max3_f32 v0, v0, v90, v91
	v_max3_f32 v0, v0, v92, v93
	v_max3_f32 v0, v0, v94, v95

.LBB0_1242:
	s_waitcnt lgkmcnt(3)
	v_mfma_f32_32x32x16_bf16 v[80:95], v[80:83], v[122:125], 0
	s_waitcnt lgkmcnt(2)
	v_mfma_f32_32x32x16_bf16 v[80:95], v[142:145], v[126:129], v[80:95]
	s_waitcnt lgkmcnt(1)
	v_mfma_f32_32x32x16_bf16 v[80:95], v[138:141], v[98:101], v[80:95]
	ds_read_b128 v[138:141], v245 offset:8832
	ds_read_b128 v[142:145], v245 offset:8864
	ds_read_b128 v[248:251], v245 offset:8896
	ds_read_b128 v[208:211], v245 offset:8928
	s_waitcnt lgkmcnt(4)
	v_mfma_f32_32x32x16_bf16 v[80:95], v[10:13], v[102:105], v[80:95]
	s_waitcnt lgkmcnt(3)
	v_mfma_f32_32x32x16_bf16 v[80:95], v[138:141], v[106:109], v[80:95]
	v_add_u32_e32 v14, 0xfffffe20, v172
	v_cmp_lt_u32_e32 vcc, s87, v14
	v_add_u32_e32 v245, 0xfffffe28, v172
	v_add_u32_e32 v247, 0xfffffe29, v172
	v_add_u32_e32 v14, 0xfffffe31, v172
	ds_read_b128 v[138:141], v167 offset:17472
	ds_read_b128 v[10:13], v167 offset:22080
	s_waitcnt lgkmcnt(4)
	v_mfma_f32_32x32x16_bf16 v[80:95], v[142:145], v[110:113], v[80:95]
	v_add_u32_e32 v142, 0xfffffe21, v172
	v_add_u32_e32 v144, 0xfffffe22, v172
	v_add_u32_e32 v145, 0xfffffe23, v172
	s_waitcnt lgkmcnt(3)
	v_mfma_f32_32x32x16_bf16 v[80:95], v[248:251], v[114:117], v[80:95]
	v_add_u32_e32 v248, 0xfffffe2a, v172
	v_add_u32_e32 v249, 0xfffffe2b, v172
	v_add_u32_e32 v250, 0xfffffe30, v172
	s_waitcnt lgkmcnt(2)
	v_mfma_f32_32x32x16_bf16 v[80:95], v[208:211], v[118:121], v[80:95]
	s_cmp_eq_u64 s[12:13], 0
	s_cselect_b32 s98, s15, 1
	s_cmp_lg_u32 s98, 1
	s_nop 8
	s_cbranch_scc0 .Lwinf1_slow
	v_mov_b32_e32 v15, v80
	v_max_f32_e32 v80, v15, v15
	v_mov_b32_e32 v143, v81
	v_mov_b32_e32 v144, v82
	v_mov_b32_e32 v145, v83
	v_mov_b32_e32 v245, v84
	v_mov_b32_e32 v247, v85
	v_mov_b32_e32 v248, v86
	v_mov_b32_e32 v249, v87
	v_max_f32_e32 v14, v143, v143
	v_max_f32_e32 v14, v80, v14
	v_max3_f32 v14, v14, v144, v145
	v_max3_f32 v14, v14, v245, v247
	v_max3_f32 v14, v14, v248, v249
	v_max3_f32 v14, v14, v88, v89
	v_max3_f32 v14, v14, v90, v91
	v_max3_f32 v14, v14, v92, v93
	v_max3_f32 v14, v14, v94, v95

.Lwinf0_slow:
	v_cndmask_b32_e32 v143, v231, v80, vcc
	v_cmp_lt_u32_e32 vcc, s87, v0
	v_add_u32_e32 v0, 0xfffffe12, v172
	v_max_f32_e32 v80, v143, v143
	v_cndmask_b32_e32 v144, v231, v81, vcc
	v_cmp_lt_u32_e32 vcc, s87, v145
	s_nop 1
	v_cndmask_b32_e32 v145, v231, v82, vcc
	v_cmp_lt_u32_e32 vcc, s87, v173
	s_nop 1
	v_cndmask_b32_e32 v232, v231, v83, vcc
	v_cmp_lt_u32_e32 vcc, s87, v174
	s_nop 1
	v_cndmask_b32_e32 v233, v231, v84, vcc
	v_cmp_lt_u32_e32 vcc, s87, v175
	s_nop 1
	v_cndmask_b32_e32 v234, v231, v85, vcc
	v_cmp_lt_u32_e32 vcc, s87, v208
	s_nop 1
	v_cndmask_b32_e32 v235, v231, v86, vcc
	v_cmp_lt_u32_e32 vcc, s87, v209
	s_nop 1
	v_cndmask_b32_e32 v236, v231, v87, vcc
	v_cmp_lt_u32_e32 vcc, s87, v210
	s_nop 1
	v_cndmask_b32_e32 v88, v231, v88, vcc
	v_cmp_lt_u32_e32 vcc, s87, v211
	s_nop 1
	v_cndmask_b32_e32 v89, v231, v89, vcc
	v_cmp_lt_u32_e32 vcc, s87, v0
	v_add_u32_e32 v0, 0xfffffe13, v172
	s_nop 0
	v_cndmask_b32_e32 v90, v231, v90, vcc
	v_cmp_lt_u32_e32 vcc, s87, v0
	v_add_u32_e32 v0, 0xfffffe18, v172
	s_nop 0
	v_cndmask_b32_e32 v91, v231, v91, vcc
	v_cmp_lt_u32_e32 vcc, s87, v0
	v_add_u32_e32 v0, 0xfffffe19, v172
	s_nop 0
	v_cndmask_b32_e32 v92, v231, v92, vcc
	v_cmp_lt_u32_e32 vcc, s87, v0
	v_add_u32_e32 v0, 0xfffffe1a, v172
	s_nop 0
	v_cndmask_b32_e32 v93, v231, v93, vcc
	v_cmp_lt_u32_e32 vcc, s87, v0
	v_add_u32_e32 v0, 0xfffffe1b, v172
	s_nop 0
	v_cndmask_b32_e32 v94, v231, v94, vcc
	v_cmp_lt_u32_e32 vcc, s87, v0
	v_max_f32_e32 v0, v144, v144
	v_max_f32_e32 v0, v80, v0
	v_max3_f32 v0, v0, v145, v232
	v_max3_f32 v0, v0, v233, v234
	v_max3_f32 v0, v0, v235, v236
	v_max3_f32 v0, v0, v88, v89
	v_max3_f32 v0, v0, v90, v91
	v_cndmask_b32_e32 v95, v231, v95, vcc
	v_max3_f32 v0, v0, v92, v93
	v_max3_f32 v0, v0, v94, v95
	s_branch .Lwinf0_join
.Lwinf1_slow:
	v_cndmask_b32_e32 v15, v231, v80, vcc
	v_cmp_lt_u32_e32 vcc, s87, v142
	v_max_f32_e32 v80, v15, v15
	s_nop 0
	v_cndmask_b32_e32 v143, v231, v81, vcc
	v_cmp_lt_u32_e32 vcc, s87, v144
	s_nop 1
	v_cndmask_b32_e32 v144, v231, v82, vcc
	v_cmp_lt_u32_e32 vcc, s87, v145
	s_nop 1
	v_cndmask_b32_e32 v145, v231, v83, vcc
	v_cmp_lt_u32_e32 vcc, s87, v245
	s_nop 1
	v_cndmask_b32_e32 v245, v231, v84, vcc
	v_cmp_lt_u32_e32 vcc, s87, v247
	s_nop 1
	v_cndmask_b32_e32 v247, v231, v85, vcc
	v_cmp_lt_u32_e32 vcc, s87, v248
	s_nop 1
	v_cndmask_b32_e32 v248, v231, v86, vcc
	v_cmp_lt_u32_e32 vcc, s87, v249
	s_nop 1
	v_cndmask_b32_e32 v249, v231, v87, vcc
	v_cmp_lt_u32_e32 vcc, s87, v250
	s_nop 1
	v_cndmask_b32_e32 v88, v231, v88, vcc
	v_cmp_lt_u32_e32 vcc, s87, v14
	v_add_u32_e32 v14, 0xfffffe32, v172
	s_nop 0
	v_cndmask_b32_e32 v89, v231, v89, vcc
	v_cmp_lt_u32_e32 vcc, s87, v14
	v_add_u32_e32 v14, 0xfffffe33, v172
	s_nop 0
	v_cndmask_b32_e32 v90, v231, v90, vcc
	v_cmp_lt_u32_e32 vcc, s87, v14
	v_add_u32_e32 v14, 0xfffffe38, v172
	s_nop 0
	v_cndmask_b32_e32 v91, v231, v91, vcc
	v_cmp_lt_u32_e32 vcc, s87, v14
	v_add_u32_e32 v14, 0xfffffe39, v172
	s_nop 0
	v_cndmask_b32_e32 v92, v231, v92, vcc
	v_cmp_lt_u32_e32 vcc, s87, v14
	v_add_u32_e32 v14, 0xfffffe3a, v172
	s_nop 0
	v_cndmask_b32_e32 v93, v231, v93, vcc
	v_cmp_lt_u32_e32 vcc, s87, v14
	v_add_u32_e32 v14, 0xfffffe3b, v172
	s_nop 0
	v_cndmask_b32_e32 v94, v231, v94, vcc
	v_cmp_lt_u32_e32 vcc, s87, v14
	v_max_f32_e32 v14, v143, v143
	v_max_f32_e32 v14, v80, v14
	v_max3_f32 v14, v14, v144, v145
	v_max3_f32 v14, v14, v245, v247
	v_max3_f32 v14, v14, v248, v249
	v_max3_f32 v14, v14, v88, v89
	v_max3_f32 v14, v14, v90, v91
	v_cndmask_b32_e32 v95, v231, v95, vcc
	v_max3_f32 v14, v14, v92, v93
	v_max3_f32 v14, v14, v94, v95
	s_branch .Lwinf1_join
